# static s_setprio 1 for waves 4-7 at kernel entry, all per-segment priority flips in the GEMM K-loops deleted (on top of c5 stack)
# speedup vs baseline: 1.0038x; 1.0037x over previous
; #define LAS __attribute__((address_space(3)))
; #define LDS_WAIT() asm volatile("s_waitcnt lgkmcnt(0)" ::: "memory")
; __device__ __forceinline__ void transpose_item(const float* W, int ldw, int col0_src, bf16* WT, int K, int row0_dst, const float* gain, LAS float* scr, int k0, int lane) {
;     float wv[32];
; #pragma unroll
;     for (int i = 0; i < 32; ++i) wv[i] = W[(size_t)(k0 + 2 * i + (lane >> 5)) * ldw + col0_src + (lane & 31)];
; #pragma unroll
;     for (int i = 0; i < 32; ++i) { const int kk = 2 * i + (lane >> 5); float v = wv[i]; if (gain) v *= gain[k0 + kk]; scr[kk * 33 + (lane & 31)] = v; }
;     LDS_WAIT(); asm volatile("" ::: "memory");
;     const int c = lane & 7;
; #pragma unroll
;     for (int j = 0; j < 4; ++j) { const int n = (lane >> 3) + 8 * j; const LAS float* s = scr + (8 * c) * 33 + n;
; __device__ __forceinline__ void prologue_phase(const Args& a, LAS unsigned char* lds) {
;     int tid_ = threadIdx.x; asm volatile("" : "+v"(tid_));
;     const int tid = tid_, lane = tid & 63, wave = __builtin_amdgcn_readfirstlane(tid >> 6);
;     LAS float* scr = (LAS float*)(lds + wave * 16384);
;     const int gw = blockIdx.x * NWAVES + wave, NGW = gridDim.x * NWAVES;
;     unsigned char* ws = a.ws;
;     constexpr int I_QKV1 = (DM / 64) * (NQKV / 32), I_O1 = (DM / 64) * (DM / 32), I_UP1 = (DM / 64) * (NUP / 32), I_DN1 = (DFF / 64) * (DM / 32), I_PL1 = (PG / 64) * (PG / 32);
;     constexpr int NITEMS = 2 * I_QKV1 + 2 * I_O1 + 4 * I_UP1 + 4 * I_DN1 + 8 * I_PL1;
;     for (int it = gw; it < NITEMS; it += NGW) {
;         int r = it;
;         if (r < 4 * I_UP1) { const int l = r / I_UP1; r -= l * I_UP1; const int nblk = NUP / 32, kb = r / nblk, nb = r % nblk, n0 = nb * 32;
;             const int src = ((n0 >> 7) & 1) * DFF + (n0 >> 8) * 128 + (n0 & 127);
;             transpose_item(a.in[I_WUP] + (size_t)l * DM * NUP, NUP, src, (bf16*)(ws + WS_WUP) + (size_t)l * NUP * DM, DM, n0, a.in[I_NFFN] + l * DM, scr, kb * 64, lane); continue; }
.LBB0_4:
	s_or_b64 exec, exec, s[2:3]
	v_writelane_b32 v255, s0, 1
	s_load_dwordx4 s[20:23], s[0:1], 0x40
	v_mov_b32_e32 v2, v1
	v_writelane_b32 v255, s1, 2
	s_waitcnt lgkmcnt(0)
	s_lshl_b32 s24, s38, 3
	v_readlane_b32 s0, v255, 0
	v_readfirstlane_b32 s3, v2
	s_lshl_b32 s0, s0, 3
	s_ashr_i32 s2, s3, 6
	s_cmp_ge_i32 s2, 4
	s_cbranch_scc0 .Lprio_done
	s_setprio 1
.Lprio_done:
	s_add_i32 s26, s2, s0
	s_cmp_gt_i32 s26, 0x12fff
	v_and_b32_e32 v3, 63, v2
	s_cbranch_scc1 .LBB0_87
	s_add_u32 s1, s36, 0x14000000
	s_addc_u32 s25, s37, 0
	v_lshrrev_b32_e32 v4, 5, v3
	s_movk_i32 s5, 0x84
	v_mov_b32_e32 v5, 0x210
	s_add_u32 s27, s36, 0x2800000
	v_mad_u32_u24 v29, v4, s5, v5
	v_mov_b32_e32 v5, 0x420
	s_addc_u32 s33, s37, 0
	v_mad_u32_u24 v30, v4, s5, v5
	v_mov_b32_e32 v5, 0x630
	s_add_u32 s54, s36, 0x1400000
	v_mad_u32_u24 v10, v4, s5, v5
	v_mov_b32_e32 v5, 0x840
	s_addc_u32 s55, s37, 0
	v_mad_u32_u24 v31, v4, s5, v5
	v_mov_b32_e32 v5, 0xa50
	s_add_u32 s56, s36, 0xe800000
	v_mad_u32_u24 v32, v4, s5, v5
	v_mov_b32_e32 v5, 0xc60
	s_addc_u32 s57, s37, 0
	v_mad_u32_u24 v11, v4, s5, v5
	v_mov_b32_e32 v5, 0xe70
	s_add_u32 s58, s36, 0x3800000
	v_mad_u32_u24 v33, v4, s5, v5
	v_mov_b32_e32 v5, 0x1080
	s_addc_u32 s59, s37, 0
	v_mad_u32_u24 v34, v4, s5, v5
	v_mov_b32_e32 v5, 0x1290
	s_cmp_lg_u64 s[14:15], 0
	v_mad_u32_u24 v12, v4, s5, v5
	v_mov_b32_e32 v5, 0x14a0
	s_cselect_b64 s[34:35], -1, 0
	s_cmp_lg_u64 s[16:17], 0
	v_mad_u32_u24 v35, v4, s5, v5
	v_lshlrev_b32_e32 v5, 3, v3
	s_cselect_b64 s[40:41], -1, 0
	s_lshl_b32 s4, s2, 14
	v_lshrrev_b32_e32 v36, 3, v3
	v_and_b32_e32 v8, 56, v5
	s_add_i32 s4, s4, 0
	v_and_b32_e32 v6, 31, v2
	v_mul_u32_u24_e32 v5, 0x84, v8
	v_lshlrev_b32_e32 v13, 2, v36
	v_readlane_b32 s42, v255, 0
	s_lshr_b32 s3, s3, 6
	v_lshl_add_u32 v28, v6, 2, s4
	v_mul_u32_u24_e32 v9, 0x84, v4
	v_add3_u32 v37, s4, v5, v13
	s_lshl_b32 s4, s42, 5
	s_lshl_b32 s5, s2, 2
	v_mov_b32_e32 v7, 0
	s_add_i32 s60, s4, s5
	s_lshl_b32 s4, s42, 8
	s_lshl_b32 s2, s2, 5
	s_add_i32 s0, s0, s3
	v_add_u32_e32 v41, v28, v9
	v_add_u32_e32 v42, v28, v10
	v_add_u32_e32 v43, v28, v11
	v_add_u32_e32 v44, v28, v12
	v_or_b32_e32 v38, 8, v36
	v_or_b32_e32 v39, 16, v36
	v_or_b32_e32 v40, 24, v36
	v_mov_b32_e32 v5, v7
	s_lshl_b32 s61, s38, 5
	s_add_i32 s62, s4, s2
	s_lshl_b32 s63, s38, 8
	s_add_i32 s64, s0, 0x5000
	s_movk_i32 s65, 0x2000
	s_movk_i32 s66, 0x4000
	s_mov_b32 s67, 0x8000
	s_mov_b32 s68, 0xa000
	s_mov_b32 s69, 0xb000
	s_mov_b32 s70, 0xc000
	s_mov_b32 s71, 0x10000
	s_mov_b32 s72, 0x14000
	s_mov_b32 s73, 0x18000
	s_mov_b32 s74, 0x1c000
	s_mov_b32 s75, 0x1e000
	s_mov_b32 s76, 0x28000
	s_mov_b32 s77, 0x3c000
	s_mov_b32 s78, 0x50000
	s_mov_b32 s79, 0x64000
	s_mov_b32 s45, 0x70000
	v_lshlrev_b32_e32 v6, 2, v6
	v_add_u32_e32 v45, 0x400, v41
	v_add_u32_e32 v46, 0x400, v42
	v_add_u32_e32 v47, 0x400, v43
	v_add_u32_e32 v48, 0x400, v44
	v_add_u32_e32 v49, 0x800, v44
	v_add_u32_e32 v50, 0xc00, v44
	v_lshlrev_b32_e32 v8, 1, v8
	s_mov_b32 s82, 0x78000
	s_mov_b32 s84, 0x23000
	s_mov_b32 s85, 0x2d000
	s_mov_b32 s86, 0x32000
	s_mov_b32 s87, 0x37000
	s_mov_b32 s88, 0x41000
	s_mov_b32 s89, 0x46000
	s_mov_b32 s90, 0x4b000
	s_mov_b32 s91, 0x55000
	s_mov_b32 s92, 0x5a000
	s_mov_b32 s93, 0x5f000
	s_mov_b32 s94, 0x69000
	s_mov_b32 s95, 0x6e000
	s_mov_b32 s96, 0x73000
	s_mov_b32 s97, 0x7d000
	s_mov_b32 s0, 0x82000
	s_mov_b32 s80, 0x87000
	s_mov_b32 s81, 0x8c000
	s_mov_b32 s83, s26
	s_mov_b32 s43, 0
	s_branch .LBB0_9

; #define PG8_STAGE(bufoff, gbase, voff) do { _Pragma("unroll") for (int _i = 0; _i < 2; ++_i) \
;         __builtin_amdgcn_global_load_lds((const unsigned*)((const char*)(gbase) + (voff)[_i]), (PG8_LAS unsigned*)(lds + (bufoff) + ldsw + _i * 8192), 16, 0, 0); } while (0)
; #define PG8_LDA(dst, b, h) do { _Pragma("unroll") for (int m = 0; m < 4; ++m) _Pragma("unroll") for (int k = 0; k < 2; ++k) dst[m][k] = *(const PG8_LAS bf16x8*)(lds + PG8_SA(b, h) + aoff + m * 2048 + k * 1024); } while (0)
; #define PG8_LDB(dst, b, h) do { _Pragma("unroll") for (int n = 0; n < 2; ++n) _Pragma("unroll") for (int k = 0; k < 2; ++k) dst[n][k] = *(const PG8_LAS bf16x8*)(lds + PG8_SB(b, h) + boff + n * 2048 + k * 1024); } while (0)
; #define PG8_WAIT_V(n) asm volatile("s_waitcnt vmcnt(" #n ")" ::: "memory")
; #define PG8_WAIT_L(n) asm volatile("s_waitcnt lgkmcnt(" #n ")" ::: "memory")
; #define PG8_BAR __builtin_amdgcn_s_barrier()
; template <class Epi, class Sched, bool ALIGN_EPI = false, bool SP2 = false>
; __device__ __forceinline__ void gemm_phase(PG8_LAS unsigned char* lds, const Gemm g, const Sched& S, const Epi& E, int wave_s) {
;     ...
;         const bool has_next = S.next(ui + 1, nxt);
;         const char* nA = has_next ? (const char*)g.A + (size_t)nxt.pm * tstepA + (size_t)(nxt.pn / g.npg) * (size_t)(K * 2) : cA; const char* nB = has_next ? (const char*)g.Bt + (size_t)nxt.pn * tstepB : cB;
;         for (int t = 0; t < nt; t += 2) {
;             const bool last = (t == nt - 2);
;             const char* a1 = cA + (size_t)(t + 1) * kstep;
;             const char* a2 = last ? nA : cA + (size_t)(t + 2) * kstep; const char* b2 = last ? nB : cB + (size_t)(t + 2) * kstep;
;             const char* a3 = a2 + kstep; const char* b3 = b2 + kstep;
;             if (last && has_next) S.a_ready(nxt);
;             if constexpr (SP2) {
;             PG8_LDB(B0, 0, 0); PG8_LDB(B1, 0, 1); PG8_SCHED; PG8_LDA(At, 0, 0); PG8_STAGE(PG8_SA(1, 1), a1 + hstepA, voffA);
;             PG8_WAIT_V(8); PG8_WAIT_L(0); PG8_BAR; PG8_MMA(0, 0, At, B0); PG8_MMA(0, 1, At, B1); PG8_BAR; PG8_SCHED;
;             PG8_LDA(At, 0, 1); PG8_STAGE(PG8_SB(0, 0), b2, voffB); PG8_STAGE(PG8_SB(0, 1), b2 + hstepB, voffB); PG8_STAGE(PG8_SA(0, 0), a2, voffA);
;             PG8_WAIT_V(8); PG8_WAIT_L(0); PG8_BAR; PG8_MMA(1, 0, At, B0); PG8_MMA(1, 1, At, B1); PG8_BAR; PG8_SCHED;
.LBB0_313:
	s_ashr_i32 s29, s28, 31
	s_lshl_b64 s[2:3], s[28:29], 18
	s_add_u32 s96, s22, s2
	s_addc_u32 s97, s23, s3
	s_and_b64 s[2:3], s[4:5], exec
	s_cselect_b32 s2, s97, s31
	s_cselect_b32 s3, s96, s30
	s_add_u32 s4, s40, 0x80080
	s_addc_u32 s5, s41, 0
	s_add_u32 s29, s30, 0x100
	s_addc_u32 s81, s31, 0
	s_mov_b32 s84, -2
	s_add_u32 s30, s4, 0xfff80080
	s_addc_u32 s31, s5, -1
	s_add_i32 s85, 0, 0x10000
	s_cmp_eq_u32 s84, 4
	s_cselect_b32 s41, s91, s31
	s_cselect_b32 s40, s90, s30
	s_cselect_b32 s31, s2, s81
	s_cselect_b32 s30, s3, s29
	s_add_i32 s89, 0, 0x14000
	v_add_u32_e32 v118, s85, v229
	v_add_u32_e32 v150, s89, v229
	ds_read_b128 v[106:109], v118
	ds_read_b128 v[110:113], v118 offset:1024
	ds_read_b128 v[114:117], v118 offset:2048
	ds_read_b128 v[118:121], v118 offset:3072
	ds_read_b128 v[122:125], v150
	ds_read_b128 v[126:129], v150 offset:1024
	ds_read_b128 v[142:145], v150 offset:2048
	ds_read_b128 v[150:153], v150 offset:3072
	v_lshl_add_u64 v[194:195], s[4:5], 0, v[218:219]
	s_add_i32 m0, s35, 0xc000
	ds_read_b128 v[162:165], v230
	ds_read_b128 v[166:169], v230 offset:1024
	ds_read_b128 v[170:173], v230 offset:2048
	ds_read_b128 v[174:177], v230 offset:3072
	ds_read_b128 v[178:181], v230 offset:4096
	ds_read_b128 v[182:185], v230 offset:5120
	ds_read_b128 v[186:189], v230 offset:6144
	ds_read_b128 v[190:193], v230 offset:7168
	global_load_lds_dwordx4 v[194:195], off
	v_lshl_add_u64 v[194:195], s[4:5], 0, v[220:221]
	s_add_i32 m0, s35, 0xe000
	s_nop 0
	global_load_lds_dwordx4 v[194:195], off
	s_waitcnt vmcnt(8)
	s_waitcnt lgkmcnt(0)
	s_barrier
	s_waitcnt lgkmcnt(0)
	v_mfma_f32_16x16x32_bf16 v[158:161], v[106:109], v[162:165], 0
	v_mfma_f32_16x16x32_bf16 v[154:157], v[114:117], v[162:165], 0
	v_mfma_f32_16x16x32_bf16 v[134:137], v[106:109], v[170:173], 0
	v_mfma_f32_16x16x32_bf16 v[130:133], v[114:117], v[170:173], 0
	v_mfma_f32_16x16x32_bf16 v[94:97], v[106:109], v[178:181], 0
	v_mfma_f32_16x16x32_bf16 v[90:93], v[114:117], v[178:181], 0
	v_mfma_f32_16x16x32_bf16 v[78:81], v[106:109], v[186:189], 0
	v_mfma_f32_16x16x32_bf16 v[74:77], v[114:117], v[186:189], 0
	v_mfma_f32_16x16x32_bf16 v[158:161], v[110:113], v[166:169], v[158:161]
	v_mfma_f32_16x16x32_bf16 v[154:157], v[118:121], v[166:169], v[154:157]
	v_mfma_f32_16x16x32_bf16 v[134:137], v[110:113], v[174:177], v[134:137]
	v_mfma_f32_16x16x32_bf16 v[130:133], v[118:121], v[174:177], v[130:133]
	v_mfma_f32_16x16x32_bf16 v[94:97], v[110:113], v[182:185], v[94:97]
	v_mfma_f32_16x16x32_bf16 v[90:93], v[118:121], v[182:185], v[90:93]
	v_mfma_f32_16x16x32_bf16 v[78:81], v[110:113], v[190:193], v[78:81]
	v_mfma_f32_16x16x32_bf16 v[74:77], v[118:121], v[190:193], v[74:77]
	v_mfma_f32_16x16x32_bf16 v[146:149], v[122:125], v[162:165], 0
	v_mfma_f32_16x16x32_bf16 v[138:141], v[142:145], v[162:165], 0
	v_mfma_f32_16x16x32_bf16 v[102:105], v[122:125], v[170:173], 0
	v_mfma_f32_16x16x32_bf16 v[98:101], v[142:145], v[170:173], 0
	v_mfma_f32_16x16x32_bf16 v[86:89], v[122:125], v[178:181], 0
	v_mfma_f32_16x16x32_bf16 v[82:85], v[142:145], v[178:181], 0
	v_mfma_f32_16x16x32_bf16 v[70:73], v[122:125], v[186:189], 0
	v_mfma_f32_16x16x32_bf16 v[66:69], v[142:145], v[186:189], 0
	v_mfma_f32_16x16x32_bf16 v[146:149], v[126:129], v[166:169], v[146:149]
	v_mfma_f32_16x16x32_bf16 v[138:141], v[150:153], v[166:169], v[138:141]
	v_mfma_f32_16x16x32_bf16 v[102:105], v[126:129], v[174:177], v[102:105]
	v_mfma_f32_16x16x32_bf16 v[98:101], v[150:153], v[174:177], v[98:101]
	v_mfma_f32_16x16x32_bf16 v[86:89], v[126:129], v[182:185], v[86:89]
	v_mfma_f32_16x16x32_bf16 v[82:85], v[150:153], v[182:185], v[82:85]
	v_mfma_f32_16x16x32_bf16 v[70:73], v[126:129], v[190:193], v[70:73]
	v_mfma_f32_16x16x32_bf16 v[66:69], v[150:153], v[190:193], v[66:69]
	s_barrier
	s_add_i32 s85, s85, s34
	v_lshl_add_u64 v[194:195], s[30:31], 0, v[214:215]
	s_mov_b32 m0, s85
	ds_read_b128 v[162:165], v230 offset:16384
	ds_read_b128 v[166:169], v230 offset:17408
	ds_read_b128 v[170:173], v230 offset:18432
	ds_read_b128 v[174:177], v230 offset:19456
	ds_read_b128 v[178:181], v230 offset:20480
	ds_read_b128 v[182:185], v230 offset:21504
	ds_read_b128 v[186:189], v230 offset:22528
	ds_read_b128 v[190:193], v230 offset:23552
	global_load_lds_dwordx4 v[194:195], off
	s_add_i32 m0, s85, 0x2000
	s_add_u32 s94, s30, 0x20000
	v_lshl_add_u64 v[196:197], s[30:31], 0, v[210:211]
	s_addc_u32 s95, s31, 0
	s_add_i32 s85, s89, s34
	global_load_lds_dwordx4 v[196:197], off
	v_lshl_add_u64 v[198:199], s[94:95], 0, v[214:215]
	s_mov_b32 m0, s85
	v_lshl_add_u64 v[200:201], s[40:41], 0, v[212:213]
	global_load_lds_dwordx4 v[198:199], off
	v_lshl_add_u64 v[198:199], s[94:95], 0, v[210:211]
	s_add_i32 m0, s85, 0x2000
	s_nop 0
	global_load_lds_dwordx4 v[198:199], off
	v_lshl_add_u64 v[198:199], s[40:41], 0, v[216:217]
	s_mov_b32 m0, s35
	s_nop 0
	global_load_lds_dwordx4 v[198:199], off
	s_mov_b32 m0, s36
	s_nop 0
	global_load_lds_dwordx4 v[200:201], off
	s_waitcnt vmcnt(8)
	s_waitcnt lgkmcnt(0)
	s_barrier
; #define PG8_STAGE(bufoff, gbase, voff) do { _Pragma("unroll") for (int _i = 0; _i < 2; ++_i) \
;         __builtin_amdgcn_global_load_lds((const unsigned*)((const char*)(gbase) + (voff)[_i]), (PG8_LAS unsigned*)(lds + (bufoff) + ldsw + _i * 8192), 16, 0, 0); } while (0)
; #define PG8_LDA(dst, b, h) do { _Pragma("unroll") for (int m = 0; m < 4; ++m) _Pragma("unroll") for (int k = 0; k < 2; ++k) dst[m][k] = *(const PG8_LAS bf16x8*)(lds + PG8_SA(b, h) + aoff + m * 2048 + k * 1024); } while (0)
; #define PG8_LDB(dst, b, h) do { _Pragma("unroll") for (int n = 0; n < 2; ++n) _Pragma("unroll") for (int k = 0; k < 2; ++k) dst[n][k] = *(const PG8_LAS bf16x8*)(lds + PG8_SB(b, h) + boff + n * 2048 + k * 1024); } while (0)
; #define PG8_MMA(ai, bj, At, Bt) do { __builtin_amdgcn_s_setprio(1); _Pragma("unroll") for (int m = 0; m < 4; ++m) _Pragma("unroll") for (int n = 0; n < 2; ++n) _Pragma("unroll") for (int k = 0; k < 2; ++k) \
;         acc[ai][bj][m][n] = __builtin_amdgcn_mfma_f32_16x16x32_bf16(Bt[n][k], At[m][k], acc[ai][bj][m][n], 0, 0, 0); __builtin_amdgcn_s_setprio(0); } while (0)
; #define PG8_WAIT_V(n) asm volatile("s_waitcnt vmcnt(" #n ")" ::: "memory")
; #define PG8_WAIT_L(n) asm volatile("s_waitcnt lgkmcnt(" #n ")" ::: "memory")
; #define PG8_BAR __builtin_amdgcn_s_barrier()
; #define PG8_SCHED __builtin_amdgcn_sched_barrier(0)
; template <class Epi, class Sched, bool ALIGN_EPI = false, bool SP2 = false>
; __device__ __forceinline__ void gemm_phase(PG8_LAS unsigned char* lds, const Gemm g, const Sched& S, const Epi& E, int wave_s) {
;     ...
;             PG8_WAIT_V(8); PG8_WAIT_L(0); PG8_BAR; PG8_MMA(1, 0, At, B0); PG8_MMA(1, 1, At, B1); PG8_BAR; PG8_SCHED;
;             PG8_LDB(B0, 1, 0); PG8_LDB(B1, 1, 1); PG8_SCHED; PG8_LDA(At, 1, 0); PG8_STAGE(PG8_SA(0, 1), a2 + hstepA, voffA);
;             PG8_WAIT_V(8); PG8_WAIT_L(0); PG8_BAR; PG8_MMA(0, 0, At, B0); PG8_MMA(0, 1, At, B1); PG8_BAR; PG8_SCHED;
	s_waitcnt lgkmcnt(0)
	v_mfma_f32_16x16x32_bf16 v[62:65], v[106:109], v[162:165], 0
	v_mfma_f32_16x16x32_bf16 v[58:61], v[114:117], v[162:165], 0
	v_mfma_f32_16x16x32_bf16 v[46:49], v[106:109], v[170:173], 0
	v_mfma_f32_16x16x32_bf16 v[42:45], v[114:117], v[170:173], 0
	v_mfma_f32_16x16x32_bf16 v[30:33], v[106:109], v[178:181], 0
	v_mfma_f32_16x16x32_bf16 v[26:29], v[114:117], v[178:181], 0
	v_mfma_f32_16x16x32_bf16 v[14:17], v[106:109], v[186:189], 0
	v_mfma_f32_16x16x32_bf16 v[10:13], v[114:117], v[186:189], 0
	v_mfma_f32_16x16x32_bf16 v[62:65], v[110:113], v[166:169], v[62:65]
	v_mfma_f32_16x16x32_bf16 v[58:61], v[118:121], v[166:169], v[58:61]
	v_mfma_f32_16x16x32_bf16 v[46:49], v[110:113], v[174:177], v[46:49]
	v_mfma_f32_16x16x32_bf16 v[42:45], v[118:121], v[174:177], v[42:45]
	v_mfma_f32_16x16x32_bf16 v[30:33], v[110:113], v[182:185], v[30:33]
	v_mfma_f32_16x16x32_bf16 v[26:29], v[118:121], v[182:185], v[26:29]
	v_mfma_f32_16x16x32_bf16 v[14:17], v[110:113], v[190:193], v[14:17]
	v_mfma_f32_16x16x32_bf16 v[10:13], v[118:121], v[190:193], v[10:13]
	v_mfma_f32_16x16x32_bf16 v[54:57], v[122:125], v[162:165], 0
	v_mfma_f32_16x16x32_bf16 v[50:53], v[142:145], v[162:165], 0
	v_mfma_f32_16x16x32_bf16 v[38:41], v[122:125], v[170:173], 0
	v_mfma_f32_16x16x32_bf16 v[34:37], v[142:145], v[170:173], 0
	v_mfma_f32_16x16x32_bf16 v[22:25], v[122:125], v[178:181], 0
	v_mfma_f32_16x16x32_bf16 v[18:21], v[142:145], v[178:181], 0
	v_mfma_f32_16x16x32_bf16 v[6:9], v[122:125], v[186:189], 0
	v_mfma_f32_16x16x32_bf16 v[2:5], v[142:145], v[186:189], 0
	v_mfma_f32_16x16x32_bf16 v[54:57], v[126:129], v[166:169], v[54:57]
	v_mfma_f32_16x16x32_bf16 v[50:53], v[150:153], v[166:169], v[50:53]
	v_mfma_f32_16x16x32_bf16 v[38:41], v[126:129], v[174:177], v[38:41]
	v_mfma_f32_16x16x32_bf16 v[34:37], v[150:153], v[174:177], v[34:37]
	v_mfma_f32_16x16x32_bf16 v[22:25], v[126:129], v[182:185], v[22:25]
	v_mfma_f32_16x16x32_bf16 v[18:21], v[150:153], v[182:185], v[18:21]
	v_mfma_f32_16x16x32_bf16 v[6:9], v[126:129], v[190:193], v[6:9]
	v_mfma_f32_16x16x32_bf16 v[2:5], v[150:153], v[190:193], v[2:5]
	s_barrier
	s_add_i32 s85, 0, 0x18000
	s_add_i32 s89, 0, 0x1c000
	v_add_u32_e32 v118, s85, v229
	v_add_u32_e32 v150, s89, v229
	ds_read_b128 v[106:109], v118
	ds_read_b128 v[110:113], v118 offset:1024
	ds_read_b128 v[114:117], v118 offset:2048
	ds_read_b128 v[118:121], v118 offset:3072
	ds_read_b128 v[122:125], v150
	ds_read_b128 v[126:129], v150 offset:1024
	ds_read_b128 v[142:145], v150 offset:2048
	ds_read_b128 v[150:153], v150 offset:3072
	s_add_u32 s40, s40, 0x80000
	s_addc_u32 s41, s41, 0
	s_mov_b32 m0, s37
	v_lshl_add_u64 v[202:203], s[40:41], 0, v[216:217]
	ds_read_b128 v[162:165], v230 offset:32768
	ds_read_b128 v[166:169], v230 offset:33792
	ds_read_b128 v[170:173], v230 offset:34816
	ds_read_b128 v[174:177], v230 offset:35840
	ds_read_b128 v[178:181], v230 offset:36864
	ds_read_b128 v[182:185], v230 offset:37888
	ds_read_b128 v[186:189], v230 offset:38912
	ds_read_b128 v[190:193], v230 offset:39936
	global_load_lds_dwordx4 v[202:203], off
	v_lshl_add_u64 v[202:203], s[40:41], 0, v[212:213]
	s_mov_b32 m0, s42
	s_nop 0
	global_load_lds_dwordx4 v[202:203], off
	s_waitcnt vmcnt(8)
	s_waitcnt lgkmcnt(0)
	s_barrier
	s_waitcnt lgkmcnt(0)
	v_mfma_f32_16x16x32_bf16 v[158:161], v[106:109], v[162:165], v[158:161]
	v_mfma_f32_16x16x32_bf16 v[154:157], v[114:117], v[162:165], v[154:157]
	v_mfma_f32_16x16x32_bf16 v[134:137], v[106:109], v[170:173], v[134:137]
	v_mfma_f32_16x16x32_bf16 v[130:133], v[114:117], v[170:173], v[130:133]
	v_mfma_f32_16x16x32_bf16 v[94:97], v[106:109], v[178:181], v[94:97]
	v_mfma_f32_16x16x32_bf16 v[90:93], v[114:117], v[178:181], v[90:93]
	v_mfma_f32_16x16x32_bf16 v[78:81], v[106:109], v[186:189], v[78:81]
	v_mfma_f32_16x16x32_bf16 v[74:77], v[114:117], v[186:189], v[74:77]
	v_mfma_f32_16x16x32_bf16 v[158:161], v[110:113], v[166:169], v[158:161]
	v_mfma_f32_16x16x32_bf16 v[154:157], v[118:121], v[166:169], v[154:157]
	v_mfma_f32_16x16x32_bf16 v[134:137], v[110:113], v[174:177], v[134:137]
	v_mfma_f32_16x16x32_bf16 v[130:133], v[118:121], v[174:177], v[130:133]
	v_mfma_f32_16x16x32_bf16 v[94:97], v[110:113], v[182:185], v[94:97]
	v_mfma_f32_16x16x32_bf16 v[90:93], v[118:121], v[182:185], v[90:93]
	v_mfma_f32_16x16x32_bf16 v[78:81], v[110:113], v[190:193], v[78:81]
	v_mfma_f32_16x16x32_bf16 v[74:77], v[118:121], v[190:193], v[74:77]
	v_mfma_f32_16x16x32_bf16 v[146:149], v[122:125], v[162:165], v[146:149]
	v_mfma_f32_16x16x32_bf16 v[138:141], v[142:145], v[162:165], v[138:141]
	v_mfma_f32_16x16x32_bf16 v[102:105], v[122:125], v[170:173], v[102:105]
	v_mfma_f32_16x16x32_bf16 v[98:101], v[142:145], v[170:173], v[98:101]
	v_mfma_f32_16x16x32_bf16 v[86:89], v[122:125], v[178:181], v[86:89]
	v_mfma_f32_16x16x32_bf16 v[82:85], v[142:145], v[178:181], v[82:85]
	v_mfma_f32_16x16x32_bf16 v[70:73], v[122:125], v[186:189], v[70:73]
	v_mfma_f32_16x16x32_bf16 v[66:69], v[142:145], v[186:189], v[66:69]
	v_mfma_f32_16x16x32_bf16 v[146:149], v[126:129], v[166:169], v[146:149]
	v_mfma_f32_16x16x32_bf16 v[138:141], v[150:153], v[166:169], v[138:141]
	v_mfma_f32_16x16x32_bf16 v[102:105], v[126:129], v[174:177], v[102:105]
	v_mfma_f32_16x16x32_bf16 v[98:101], v[150:153], v[174:177], v[98:101]
	v_mfma_f32_16x16x32_bf16 v[86:89], v[126:129], v[182:185], v[86:89]
	v_mfma_f32_16x16x32_bf16 v[82:85], v[150:153], v[182:185], v[82:85]
	v_mfma_f32_16x16x32_bf16 v[70:73], v[126:129], v[190:193], v[70:73]
	v_mfma_f32_16x16x32_bf16 v[66:69], v[150:153], v[190:193], v[66:69]
	s_barrier
; #define PG8_STAGE(bufoff, gbase, voff) do { _Pragma("unroll") for (int _i = 0; _i < 2; ++_i) \
;         __builtin_amdgcn_global_load_lds((const unsigned*)((const char*)(gbase) + (voff)[_i]), (PG8_LAS unsigned*)(lds + (bufoff) + ldsw + _i * 8192), 16, 0, 0); } while (0)
; #define PG8_LDA(dst, b, h) do { _Pragma("unroll") for (int m = 0; m < 4; ++m) _Pragma("unroll") for (int k = 0; k < 2; ++k) dst[m][k] = *(const PG8_LAS bf16x8*)(lds + PG8_SA(b, h) + aoff + m * 2048 + k * 1024); } while (0)
; #define PG8_LDB(dst, b, h) do { _Pragma("unroll") for (int n = 0; n < 2; ++n) _Pragma("unroll") for (int k = 0; k < 2; ++k) dst[n][k] = *(const PG8_LAS bf16x8*)(lds + PG8_SB(b, h) + boff + n * 2048 + k * 1024); } while (0)
; #define PG8_MMA(ai, bj, At, Bt) do { __builtin_amdgcn_s_setprio(1); _Pragma("unroll") for (int m = 0; m < 4; ++m) _Pragma("unroll") for (int n = 0; n < 2; ++n) _Pragma("unroll") for (int k = 0; k < 2; ++k) \
;         acc[ai][bj][m][n] = __builtin_amdgcn_mfma_f32_16x16x32_bf16(Bt[n][k], At[m][k], acc[ai][bj][m][n], 0, 0, 0); __builtin_amdgcn_s_setprio(0); } while (0)
; #define PG8_WAIT_V(n) asm volatile("s_waitcnt vmcnt(" #n ")" ::: "memory")
; #define PG8_BAR __builtin_amdgcn_s_barrier()
; template <class Epi, class Sched, bool ALIGN_EPI = false, bool SP2 = false>
; __device__ __forceinline__ void gemm_phase(PG8_LAS unsigned char* lds, const Gemm g, const Sched& S, const Epi& E, int wave_s) {
;     ...
;         for (int t = 0; t < nt; t += 2) {
;             const bool last = (t == nt - 2);
;             const char* a1 = cA + (size_t)(t + 1) * kstep;
;             const char* a2 = last ? nA : cA + (size_t)(t + 2) * kstep; const char* b2 = last ? nB : cB + (size_t)(t + 2) * kstep;
;             const char* a3 = a2 + kstep; const char* b3 = b2 + kstep;
;             if (last && has_next) S.a_ready(nxt);
;             if constexpr (SP2) {
;             PG8_LDB(B0, 0, 0); PG8_LDB(B1, 0, 1); PG8_SCHED; PG8_LDA(At, 0, 0); PG8_STAGE(PG8_SA(1, 1), a1 + hstepA, voffA);
;             PG8_WAIT_V(8); PG8_WAIT_L(0); PG8_BAR; PG8_MMA(0, 0, At, B0); PG8_MMA(0, 1, At, B1); PG8_BAR; PG8_SCHED;
;     ...
;             PG8_LDA(At, 1, 1); PG8_STAGE(PG8_SB(1, 0), b3, voffB); PG8_STAGE(PG8_SB(1, 1), b3 + hstepB, voffB); PG8_STAGE(PG8_SA(1, 0), a3, voffA);
;             PG8_WAIT_V(8); PG8_WAIT_L(0); PG8_BAR; PG8_MMA(1, 0, At, B0); PG8_MMA(1, 1, At, B1); PG8_BAR; PG8_SCHED;
	s_add_i32 s40, s85, s34
	v_lshl_add_u64 v[194:195], v[194:195], 0, s[60:61]
	s_mov_b32 m0, s40
	ds_read_b128 v[162:165], v230 offset:49152
	ds_read_b128 v[166:169], v230 offset:50176
	ds_read_b128 v[170:173], v230 offset:51200
	ds_read_b128 v[174:177], v230 offset:52224
	ds_read_b128 v[178:181], v230 offset:53248
	ds_read_b128 v[182:185], v230 offset:54272
	ds_read_b128 v[186:189], v230 offset:55296
	ds_read_b128 v[190:193], v230 offset:56320
	global_load_lds_dwordx4 v[194:195], off
	s_add_i32 m0, s40, 0x2000
	s_add_u32 s30, s30, 0x20080
	v_lshl_add_u64 v[194:195], v[196:197], 0, s[60:61]
	s_addc_u32 s31, s31, 0
	s_add_i32 s40, s89, s34
	global_load_lds_dwordx4 v[194:195], off
	v_lshl_add_u64 v[194:195], s[30:31], 0, v[214:215]
	s_mov_b32 m0, s40
	s_nop 0
	global_load_lds_dwordx4 v[194:195], off
	v_lshl_add_u64 v[194:195], s[30:31], 0, v[210:211]
	s_add_i32 m0, s40, 0x2000
	s_nop 0
	global_load_lds_dwordx4 v[194:195], off
	v_lshl_add_u64 v[194:195], v[198:199], 0, s[60:61]
	s_mov_b32 m0, s46
	s_nop 0
	global_load_lds_dwordx4 v[194:195], off
	v_lshl_add_u64 v[194:195], v[200:201], 0, s[60:61]
	s_mov_b32 m0, s47
	s_nop 0
	global_load_lds_dwordx4 v[194:195], off
	s_waitcnt vmcnt(8)
	s_waitcnt lgkmcnt(0)
	s_barrier
	s_waitcnt lgkmcnt(0)
	v_mfma_f32_16x16x32_bf16 v[62:65], v[106:109], v[162:165], v[62:65]
	v_mfma_f32_16x16x32_bf16 v[58:61], v[114:117], v[162:165], v[58:61]
	v_mfma_f32_16x16x32_bf16 v[46:49], v[106:109], v[170:173], v[46:49]
	v_mfma_f32_16x16x32_bf16 v[42:45], v[114:117], v[170:173], v[42:45]
	v_mfma_f32_16x16x32_bf16 v[30:33], v[106:109], v[178:181], v[30:33]
	v_mfma_f32_16x16x32_bf16 v[26:29], v[114:117], v[178:181], v[26:29]
	v_mfma_f32_16x16x32_bf16 v[14:17], v[106:109], v[186:189], v[14:17]
	v_mfma_f32_16x16x32_bf16 v[10:13], v[114:117], v[186:189], v[10:13]
	v_mfma_f32_16x16x32_bf16 v[62:65], v[110:113], v[166:169], v[62:65]
	v_mfma_f32_16x16x32_bf16 v[58:61], v[118:121], v[166:169], v[58:61]
	v_mfma_f32_16x16x32_bf16 v[46:49], v[110:113], v[174:177], v[46:49]
	v_mfma_f32_16x16x32_bf16 v[42:45], v[118:121], v[174:177], v[42:45]
	v_mfma_f32_16x16x32_bf16 v[30:33], v[110:113], v[182:185], v[30:33]
	v_mfma_f32_16x16x32_bf16 v[26:29], v[118:121], v[182:185], v[26:29]
	v_mfma_f32_16x16x32_bf16 v[14:17], v[110:113], v[190:193], v[14:17]
	v_mfma_f32_16x16x32_bf16 v[10:13], v[118:121], v[190:193], v[10:13]
	v_mfma_f32_16x16x32_bf16 v[54:57], v[122:125], v[162:165], v[54:57]
	v_mfma_f32_16x16x32_bf16 v[50:53], v[142:145], v[162:165], v[50:53]
	v_mfma_f32_16x16x32_bf16 v[38:41], v[122:125], v[170:173], v[38:41]
	v_mfma_f32_16x16x32_bf16 v[34:37], v[142:145], v[170:173], v[34:37]
	v_mfma_f32_16x16x32_bf16 v[22:25], v[122:125], v[178:181], v[22:25]
	v_mfma_f32_16x16x32_bf16 v[18:21], v[142:145], v[178:181], v[18:21]
	v_mfma_f32_16x16x32_bf16 v[6:9], v[122:125], v[186:189], v[6:9]
	v_mfma_f32_16x16x32_bf16 v[2:5], v[142:145], v[186:189], v[2:5]
	v_mfma_f32_16x16x32_bf16 v[54:57], v[126:129], v[166:169], v[54:57]
	v_mfma_f32_16x16x32_bf16 v[50:53], v[150:153], v[166:169], v[50:53]
	v_mfma_f32_16x16x32_bf16 v[38:41], v[126:129], v[174:177], v[38:41]
	v_mfma_f32_16x16x32_bf16 v[34:37], v[150:153], v[174:177], v[34:37]
	v_mfma_f32_16x16x32_bf16 v[22:25], v[126:129], v[182:185], v[22:25]
	v_mfma_f32_16x16x32_bf16 v[18:21], v[150:153], v[182:185], v[18:21]
	v_mfma_f32_16x16x32_bf16 v[6:9], v[126:129], v[190:193], v[6:9]
	v_mfma_f32_16x16x32_bf16 v[2:5], v[150:153], v[190:193], v[2:5]
	s_barrier
	s_add_i32 s84, s84, 2
	s_add_u32 s4, s4, 0x100
	s_addc_u32 s5, s5, 0
	s_add_u32 s29, s29, 0x100
	s_addc_u32 s81, s81, 0
	s_cmp_gt_u32 s84, 5
.LBB0_314:
	s_add_u32 s30, s4, 0xfff80080
	s_addc_u32 s31, s5, -1
	s_add_i32 s85, 0, 0x10000
	s_cmp_eq_u32 s84, 4
	s_cselect_b32 s41, s91, s31
	s_cselect_b32 s40, s90, s30
	s_cselect_b32 s31, s2, s81
	s_cselect_b32 s30, s3, s29
	s_add_i32 s89, 0, 0x14000
	v_add_u32_e32 v118, s85, v229
	v_add_u32_e32 v150, s89, v229
	ds_read_b128 v[106:109], v118
	ds_read_b128 v[110:113], v118 offset:1024
	ds_read_b128 v[114:117], v118 offset:2048
	ds_read_b128 v[118:121], v118 offset:3072
	ds_read_b128 v[122:125], v150
	ds_read_b128 v[126:129], v150 offset:1024
	ds_read_b128 v[142:145], v150 offset:2048
	ds_read_b128 v[150:153], v150 offset:3072
	v_lshl_add_u64 v[194:195], s[4:5], 0, v[218:219]
	s_add_i32 m0, s35, 0xc000
	ds_read_b128 v[162:165], v230
	ds_read_b128 v[166:169], v230 offset:1024
	ds_read_b128 v[170:173], v230 offset:2048
	ds_read_b128 v[174:177], v230 offset:3072
	ds_read_b128 v[178:181], v230 offset:4096
	ds_read_b128 v[182:185], v230 offset:5120
	ds_read_b128 v[186:189], v230 offset:6144
	ds_read_b128 v[190:193], v230 offset:7168
	global_load_lds_dwordx4 v[194:195], off
	v_lshl_add_u64 v[194:195], s[4:5], 0, v[220:221]
	s_add_i32 m0, s35, 0xe000
	s_nop 0
	global_load_lds_dwordx4 v[194:195], off
	s_waitcnt vmcnt(8)
	s_waitcnt lgkmcnt(0)
	s_barrier
; #define PG8_STAGE(bufoff, gbase, voff) do { _Pragma("unroll") for (int _i = 0; _i < 2; ++_i) \
;         __builtin_amdgcn_global_load_lds((const unsigned*)((const char*)(gbase) + (voff)[_i]), (PG8_LAS unsigned*)(lds + (bufoff) + ldsw + _i * 8192), 16, 0, 0); } while (0)
; #define PG8_LDA(dst, b, h) do { _Pragma("unroll") for (int m = 0; m < 4; ++m) _Pragma("unroll") for (int k = 0; k < 2; ++k) dst[m][k] = *(const PG8_LAS bf16x8*)(lds + PG8_SA(b, h) + aoff + m * 2048 + k * 1024); } while (0)
; #define PG8_LDB(dst, b, h) do { _Pragma("unroll") for (int n = 0; n < 2; ++n) _Pragma("unroll") for (int k = 0; k < 2; ++k) dst[n][k] = *(const PG8_LAS bf16x8*)(lds + PG8_SB(b, h) + boff + n * 2048 + k * 1024); } while (0)
; #define PG8_MMA(ai, bj, At, Bt) do { __builtin_amdgcn_s_setprio(1); _Pragma("unroll") for (int m = 0; m < 4; ++m) _Pragma("unroll") for (int n = 0; n < 2; ++n) _Pragma("unroll") for (int k = 0; k < 2; ++k) \
;         acc[ai][bj][m][n] = __builtin_amdgcn_mfma_f32_16x16x32_bf16(Bt[n][k], At[m][k], acc[ai][bj][m][n], 0, 0, 0); __builtin_amdgcn_s_setprio(0); } while (0)
; #define PG8_WAIT_V(n) asm volatile("s_waitcnt vmcnt(" #n ")" ::: "memory")
; #define PG8_WAIT_L(n) asm volatile("s_waitcnt lgkmcnt(" #n ")" ::: "memory")
; #define PG8_BAR __builtin_amdgcn_s_barrier()
; #define PG8_SCHED __builtin_amdgcn_sched_barrier(0)
; template <class Epi, class Sched, bool ALIGN_EPI = false, bool SP2 = false>
; __device__ __forceinline__ void gemm_phase(PG8_LAS unsigned char* lds, const Gemm g, const Sched& S, const Epi& E, int wave_s) {
;     ...
;             PG8_LDB(B0, 0, 0); PG8_LDB(B1, 0, 1); PG8_SCHED; PG8_LDA(At, 0, 0); PG8_STAGE(PG8_SA(1, 1), a1 + hstepA, voffA);
;             PG8_WAIT_V(8); PG8_WAIT_L(0); PG8_BAR; PG8_MMA(0, 0, At, B0); PG8_MMA(0, 1, At, B1); PG8_BAR; PG8_SCHED;
;             PG8_LDA(At, 0, 1); PG8_STAGE(PG8_SB(0, 0), b2, voffB); PG8_STAGE(PG8_SB(0, 1), b2 + hstepB, voffB); PG8_STAGE(PG8_SA(0, 0), a2, voffA);
;             PG8_WAIT_V(8); PG8_WAIT_L(0); PG8_BAR; PG8_MMA(1, 0, At, B0); PG8_MMA(1, 1, At, B1); PG8_BAR; PG8_SCHED;
	s_waitcnt lgkmcnt(0)
	v_mfma_f32_16x16x32_bf16 v[158:161], v[106:109], v[162:165], v[158:161]
	v_mfma_f32_16x16x32_bf16 v[154:157], v[114:117], v[162:165], v[154:157]
	v_mfma_f32_16x16x32_bf16 v[134:137], v[106:109], v[170:173], v[134:137]
	v_mfma_f32_16x16x32_bf16 v[130:133], v[114:117], v[170:173], v[130:133]
	v_mfma_f32_16x16x32_bf16 v[94:97], v[106:109], v[178:181], v[94:97]
	v_mfma_f32_16x16x32_bf16 v[90:93], v[114:117], v[178:181], v[90:93]
	v_mfma_f32_16x16x32_bf16 v[78:81], v[106:109], v[186:189], v[78:81]
	v_mfma_f32_16x16x32_bf16 v[74:77], v[114:117], v[186:189], v[74:77]
	v_mfma_f32_16x16x32_bf16 v[158:161], v[110:113], v[166:169], v[158:161]
	v_mfma_f32_16x16x32_bf16 v[154:157], v[118:121], v[166:169], v[154:157]
	v_mfma_f32_16x16x32_bf16 v[134:137], v[110:113], v[174:177], v[134:137]
	v_mfma_f32_16x16x32_bf16 v[130:133], v[118:121], v[174:177], v[130:133]
	v_mfma_f32_16x16x32_bf16 v[94:97], v[110:113], v[182:185], v[94:97]
	v_mfma_f32_16x16x32_bf16 v[90:93], v[118:121], v[182:185], v[90:93]
	v_mfma_f32_16x16x32_bf16 v[78:81], v[110:113], v[190:193], v[78:81]
	v_mfma_f32_16x16x32_bf16 v[74:77], v[118:121], v[190:193], v[74:77]
	v_mfma_f32_16x16x32_bf16 v[146:149], v[122:125], v[162:165], v[146:149]
	v_mfma_f32_16x16x32_bf16 v[138:141], v[142:145], v[162:165], v[138:141]
	v_mfma_f32_16x16x32_bf16 v[102:105], v[122:125], v[170:173], v[102:105]
	v_mfma_f32_16x16x32_bf16 v[98:101], v[142:145], v[170:173], v[98:101]
	v_mfma_f32_16x16x32_bf16 v[86:89], v[122:125], v[178:181], v[86:89]
	v_mfma_f32_16x16x32_bf16 v[82:85], v[142:145], v[178:181], v[82:85]
	v_mfma_f32_16x16x32_bf16 v[70:73], v[122:125], v[186:189], v[70:73]
	v_mfma_f32_16x16x32_bf16 v[66:69], v[142:145], v[186:189], v[66:69]
	v_mfma_f32_16x16x32_bf16 v[146:149], v[126:129], v[166:169], v[146:149]
	v_mfma_f32_16x16x32_bf16 v[138:141], v[150:153], v[166:169], v[138:141]
	v_mfma_f32_16x16x32_bf16 v[102:105], v[126:129], v[174:177], v[102:105]
	v_mfma_f32_16x16x32_bf16 v[98:101], v[150:153], v[174:177], v[98:101]
	v_mfma_f32_16x16x32_bf16 v[86:89], v[126:129], v[182:185], v[86:89]
	v_mfma_f32_16x16x32_bf16 v[82:85], v[150:153], v[182:185], v[82:85]
	v_mfma_f32_16x16x32_bf16 v[70:73], v[126:129], v[190:193], v[70:73]
	v_mfma_f32_16x16x32_bf16 v[66:69], v[150:153], v[190:193], v[66:69]
	s_barrier
	s_add_i32 s85, s85, s34
	v_lshl_add_u64 v[194:195], s[30:31], 0, v[214:215]
	s_mov_b32 m0, s85
	ds_read_b128 v[162:165], v230 offset:16384
	ds_read_b128 v[166:169], v230 offset:17408
	ds_read_b128 v[170:173], v230 offset:18432
	ds_read_b128 v[174:177], v230 offset:19456
	ds_read_b128 v[178:181], v230 offset:20480
	ds_read_b128 v[182:185], v230 offset:21504
	ds_read_b128 v[186:189], v230 offset:22528
	ds_read_b128 v[190:193], v230 offset:23552
	global_load_lds_dwordx4 v[194:195], off
	s_add_i32 m0, s85, 0x2000
	s_add_u32 s94, s30, 0x20000
	v_lshl_add_u64 v[196:197], s[30:31], 0, v[210:211]
	s_addc_u32 s95, s31, 0
	s_add_i32 s85, s89, s34
	global_load_lds_dwordx4 v[196:197], off
	v_lshl_add_u64 v[198:199], s[94:95], 0, v[214:215]
	s_mov_b32 m0, s85
	v_lshl_add_u64 v[200:201], s[40:41], 0, v[212:213]
	global_load_lds_dwordx4 v[198:199], off
	v_lshl_add_u64 v[198:199], s[94:95], 0, v[210:211]
	s_add_i32 m0, s85, 0x2000
	s_nop 0
	global_load_lds_dwordx4 v[198:199], off
	v_lshl_add_u64 v[198:199], s[40:41], 0, v[216:217]
	s_mov_b32 m0, s35
	s_nop 0
	global_load_lds_dwordx4 v[198:199], off
	s_mov_b32 m0, s36
	s_nop 0
	global_load_lds_dwordx4 v[200:201], off
	s_waitcnt vmcnt(8)
	s_waitcnt lgkmcnt(0)
	s_barrier
	s_waitcnt lgkmcnt(0)
	v_mfma_f32_16x16x32_bf16 v[62:65], v[106:109], v[162:165], v[62:65]
	v_mfma_f32_16x16x32_bf16 v[58:61], v[114:117], v[162:165], v[58:61]
	v_mfma_f32_16x16x32_bf16 v[46:49], v[106:109], v[170:173], v[46:49]
	v_mfma_f32_16x16x32_bf16 v[42:45], v[114:117], v[170:173], v[42:45]
	v_mfma_f32_16x16x32_bf16 v[30:33], v[106:109], v[178:181], v[30:33]
	v_mfma_f32_16x16x32_bf16 v[26:29], v[114:117], v[178:181], v[26:29]
	v_mfma_f32_16x16x32_bf16 v[14:17], v[106:109], v[186:189], v[14:17]
	v_mfma_f32_16x16x32_bf16 v[10:13], v[114:117], v[186:189], v[10:13]
	v_mfma_f32_16x16x32_bf16 v[62:65], v[110:113], v[166:169], v[62:65]
	v_mfma_f32_16x16x32_bf16 v[58:61], v[118:121], v[166:169], v[58:61]
	v_mfma_f32_16x16x32_bf16 v[46:49], v[110:113], v[174:177], v[46:49]
	v_mfma_f32_16x16x32_bf16 v[42:45], v[118:121], v[174:177], v[42:45]
	v_mfma_f32_16x16x32_bf16 v[30:33], v[110:113], v[182:185], v[30:33]
	v_mfma_f32_16x16x32_bf16 v[26:29], v[118:121], v[182:185], v[26:29]
	v_mfma_f32_16x16x32_bf16 v[14:17], v[110:113], v[190:193], v[14:17]
	v_mfma_f32_16x16x32_bf16 v[10:13], v[118:121], v[190:193], v[10:13]
	v_mfma_f32_16x16x32_bf16 v[54:57], v[122:125], v[162:165], v[54:57]
	v_mfma_f32_16x16x32_bf16 v[50:53], v[142:145], v[162:165], v[50:53]
	v_mfma_f32_16x16x32_bf16 v[38:41], v[122:125], v[170:173], v[38:41]
	v_mfma_f32_16x16x32_bf16 v[34:37], v[142:145], v[170:173], v[34:37]
	v_mfma_f32_16x16x32_bf16 v[22:25], v[122:125], v[178:181], v[22:25]
	v_mfma_f32_16x16x32_bf16 v[18:21], v[142:145], v[178:181], v[18:21]
	v_mfma_f32_16x16x32_bf16 v[6:9], v[122:125], v[186:189], v[6:9]
	v_mfma_f32_16x16x32_bf16 v[2:5], v[142:145], v[186:189], v[2:5]
	v_mfma_f32_16x16x32_bf16 v[54:57], v[126:129], v[166:169], v[54:57]
	v_mfma_f32_16x16x32_bf16 v[50:53], v[150:153], v[166:169], v[50:53]
	v_mfma_f32_16x16x32_bf16 v[38:41], v[126:129], v[174:177], v[38:41]
	v_mfma_f32_16x16x32_bf16 v[34:37], v[150:153], v[174:177], v[34:37]
	v_mfma_f32_16x16x32_bf16 v[22:25], v[126:129], v[182:185], v[22:25]
	v_mfma_f32_16x16x32_bf16 v[18:21], v[150:153], v[182:185], v[18:21]
	v_mfma_f32_16x16x32_bf16 v[6:9], v[126:129], v[190:193], v[6:9]
	v_mfma_f32_16x16x32_bf16 v[2:5], v[150:153], v[190:193], v[2:5]
	s_barrier
; #define PG8_STAGE(bufoff, gbase, voff) do { _Pragma("unroll") for (int _i = 0; _i < 2; ++_i) \
;         __builtin_amdgcn_global_load_lds((const unsigned*)((const char*)(gbase) + (voff)[_i]), (PG8_LAS unsigned*)(lds + (bufoff) + ldsw + _i * 8192), 16, 0, 0); } while (0)
; #define PG8_LDA(dst, b, h) do { _Pragma("unroll") for (int m = 0; m < 4; ++m) _Pragma("unroll") for (int k = 0; k < 2; ++k) dst[m][k] = *(const PG8_LAS bf16x8*)(lds + PG8_SA(b, h) + aoff + m * 2048 + k * 1024); } while (0)
; #define PG8_LDB(dst, b, h) do { _Pragma("unroll") for (int n = 0; n < 2; ++n) _Pragma("unroll") for (int k = 0; k < 2; ++k) dst[n][k] = *(const PG8_LAS bf16x8*)(lds + PG8_SB(b, h) + boff + n * 2048 + k * 1024); } while (0)
; #define PG8_MMA(ai, bj, At, Bt) do { __builtin_amdgcn_s_setprio(1); _Pragma("unroll") for (int m = 0; m < 4; ++m) _Pragma("unroll") for (int n = 0; n < 2; ++n) _Pragma("unroll") for (int k = 0; k < 2; ++k) \
;         acc[ai][bj][m][n] = __builtin_amdgcn_mfma_f32_16x16x32_bf16(Bt[n][k], At[m][k], acc[ai][bj][m][n], 0, 0, 0); __builtin_amdgcn_s_setprio(0); } while (0)
; #define PG8_WAIT_V(n) asm volatile("s_waitcnt vmcnt(" #n ")" ::: "memory")
; #define PG8_WAIT_L(n) asm volatile("s_waitcnt lgkmcnt(" #n ")" ::: "memory")
; #define PG8_BAR __builtin_amdgcn_s_barrier()
; #define PG8_SCHED __builtin_amdgcn_sched_barrier(0)
; template <class Epi, class Sched, bool ALIGN_EPI = false, bool SP2 = false>
; __device__ __forceinline__ void gemm_phase(PG8_LAS unsigned char* lds, const Gemm g, const Sched& S, const Epi& E, int wave_s) {
;     ...
;             PG8_LDB(B0, 1, 0); PG8_LDB(B1, 1, 1); PG8_SCHED; PG8_LDA(At, 1, 0); PG8_STAGE(PG8_SA(0, 1), a2 + hstepA, voffA);
;             PG8_WAIT_V(8); PG8_WAIT_L(0); PG8_BAR; PG8_MMA(0, 0, At, B0); PG8_MMA(0, 1, At, B1); PG8_BAR; PG8_SCHED;
	s_add_i32 s85, 0, 0x18000
	s_add_i32 s89, 0, 0x1c000
	v_add_u32_e32 v118, s85, v229
	v_add_u32_e32 v150, s89, v229
	ds_read_b128 v[106:109], v118
	ds_read_b128 v[110:113], v118 offset:1024
	ds_read_b128 v[114:117], v118 offset:2048
	ds_read_b128 v[118:121], v118 offset:3072
	ds_read_b128 v[122:125], v150
	ds_read_b128 v[126:129], v150 offset:1024
	ds_read_b128 v[142:145], v150 offset:2048
	ds_read_b128 v[150:153], v150 offset:3072
	s_add_u32 s40, s40, 0x80000
	s_addc_u32 s41, s41, 0
	s_mov_b32 m0, s37
	v_lshl_add_u64 v[202:203], s[40:41], 0, v[216:217]
	ds_read_b128 v[162:165], v230 offset:32768
	ds_read_b128 v[166:169], v230 offset:33792
	ds_read_b128 v[170:173], v230 offset:34816
	ds_read_b128 v[174:177], v230 offset:35840
	ds_read_b128 v[178:181], v230 offset:36864
	ds_read_b128 v[182:185], v230 offset:37888
	ds_read_b128 v[186:189], v230 offset:38912
	ds_read_b128 v[190:193], v230 offset:39936
	global_load_lds_dwordx4 v[202:203], off
	v_lshl_add_u64 v[202:203], s[40:41], 0, v[212:213]
	s_mov_b32 m0, s42
	s_nop 0
	global_load_lds_dwordx4 v[202:203], off
	s_waitcnt vmcnt(8)
	s_waitcnt lgkmcnt(0)
	s_barrier
	s_waitcnt lgkmcnt(0)
	v_mfma_f32_16x16x32_bf16 v[158:161], v[106:109], v[162:165], v[158:161]
	v_mfma_f32_16x16x32_bf16 v[154:157], v[114:117], v[162:165], v[154:157]
	v_mfma_f32_16x16x32_bf16 v[134:137], v[106:109], v[170:173], v[134:137]
	v_mfma_f32_16x16x32_bf16 v[130:133], v[114:117], v[170:173], v[130:133]
	v_mfma_f32_16x16x32_bf16 v[94:97], v[106:109], v[178:181], v[94:97]
	v_mfma_f32_16x16x32_bf16 v[90:93], v[114:117], v[178:181], v[90:93]
	v_mfma_f32_16x16x32_bf16 v[78:81], v[106:109], v[186:189], v[78:81]
	v_mfma_f32_16x16x32_bf16 v[74:77], v[114:117], v[186:189], v[74:77]
	v_mfma_f32_16x16x32_bf16 v[158:161], v[110:113], v[166:169], v[158:161]
	v_mfma_f32_16x16x32_bf16 v[154:157], v[118:121], v[166:169], v[154:157]
	v_mfma_f32_16x16x32_bf16 v[134:137], v[110:113], v[174:177], v[134:137]
	v_mfma_f32_16x16x32_bf16 v[130:133], v[118:121], v[174:177], v[130:133]
	v_mfma_f32_16x16x32_bf16 v[94:97], v[110:113], v[182:185], v[94:97]
	v_mfma_f32_16x16x32_bf16 v[90:93], v[118:121], v[182:185], v[90:93]
	v_mfma_f32_16x16x32_bf16 v[78:81], v[110:113], v[190:193], v[78:81]
	v_mfma_f32_16x16x32_bf16 v[74:77], v[118:121], v[190:193], v[74:77]
	v_mfma_f32_16x16x32_bf16 v[146:149], v[122:125], v[162:165], v[146:149]
	v_mfma_f32_16x16x32_bf16 v[138:141], v[142:145], v[162:165], v[138:141]
	v_mfma_f32_16x16x32_bf16 v[102:105], v[122:125], v[170:173], v[102:105]
	v_mfma_f32_16x16x32_bf16 v[98:101], v[142:145], v[170:173], v[98:101]
	v_mfma_f32_16x16x32_bf16 v[86:89], v[122:125], v[178:181], v[86:89]
	v_mfma_f32_16x16x32_bf16 v[82:85], v[142:145], v[178:181], v[82:85]
	v_mfma_f32_16x16x32_bf16 v[70:73], v[122:125], v[186:189], v[70:73]
	v_mfma_f32_16x16x32_bf16 v[66:69], v[142:145], v[186:189], v[66:69]
	v_mfma_f32_16x16x32_bf16 v[146:149], v[126:129], v[166:169], v[146:149]
	v_mfma_f32_16x16x32_bf16 v[138:141], v[150:153], v[166:169], v[138:141]
	v_mfma_f32_16x16x32_bf16 v[102:105], v[126:129], v[174:177], v[102:105]
	v_mfma_f32_16x16x32_bf16 v[98:101], v[150:153], v[174:177], v[98:101]
	v_mfma_f32_16x16x32_bf16 v[86:89], v[126:129], v[182:185], v[86:89]
	v_mfma_f32_16x16x32_bf16 v[82:85], v[150:153], v[182:185], v[82:85]
	v_mfma_f32_16x16x32_bf16 v[70:73], v[126:129], v[190:193], v[70:73]
	v_mfma_f32_16x16x32_bf16 v[66:69], v[150:153], v[190:193], v[66:69]
	s_barrier
; #define PG8_STAGE(bufoff, gbase, voff) do { _Pragma("unroll") for (int _i = 0; _i < 2; ++_i) \
;         __builtin_amdgcn_global_load_lds((const unsigned*)((const char*)(gbase) + (voff)[_i]), (PG8_LAS unsigned*)(lds + (bufoff) + ldsw + _i * 8192), 16, 0, 0); } while (0)
; #define PG8_LDA(dst, b, h) do { _Pragma("unroll") for (int m = 0; m < 4; ++m) _Pragma("unroll") for (int k = 0; k < 2; ++k) dst[m][k] = *(const PG8_LAS bf16x8*)(lds + PG8_SA(b, h) + aoff + m * 2048 + k * 1024); } while (0)
; #define PG8_MMA(ai, bj, At, Bt) do { __builtin_amdgcn_s_setprio(1); _Pragma("unroll") for (int m = 0; m < 4; ++m) _Pragma("unroll") for (int n = 0; n < 2; ++n) _Pragma("unroll") for (int k = 0; k < 2; ++k) \
;         acc[ai][bj][m][n] = __builtin_amdgcn_mfma_f32_16x16x32_bf16(Bt[n][k], At[m][k], acc[ai][bj][m][n], 0, 0, 0); __builtin_amdgcn_s_setprio(0); } while (0)
; #define PG8_WAIT_V(n) asm volatile("s_waitcnt vmcnt(" #n ")" ::: "memory")
; #define PG8_WAIT_L(n) asm volatile("s_waitcnt lgkmcnt(" #n ")" ::: "memory")
; #define PG8_BAR __builtin_amdgcn_s_barrier()
; #define PG8_SCHED __builtin_amdgcn_sched_barrier(0)
; template <class Epi, class Sched, bool ALIGN_EPI = false, bool SP2 = false>
; __device__ __forceinline__ void gemm_phase(PG8_LAS unsigned char* lds, const Gemm g, const Sched& S, const Epi& E, int wave_s) {
;     ...
;             PG8_LDA(At, 1, 1); PG8_STAGE(PG8_SB(1, 0), b3, voffB); PG8_STAGE(PG8_SB(1, 1), b3 + hstepB, voffB); PG8_STAGE(PG8_SA(1, 0), a3, voffA);
;             PG8_WAIT_V(8); PG8_WAIT_L(0); PG8_BAR; PG8_MMA(1, 0, At, B0); PG8_MMA(1, 1, At, B1); PG8_BAR; PG8_SCHED;
;     ...
;         if constexpr (ALIGN_EPI) { if (wr == 0) PG8_BAR; }
	s_add_i32 s40, s85, s34
	v_lshl_add_u64 v[194:195], v[194:195], 0, s[60:61]
	s_mov_b32 m0, s40
	ds_read_b128 v[162:165], v230 offset:49152
	ds_read_b128 v[166:169], v230 offset:50176
	ds_read_b128 v[170:173], v230 offset:51200
	ds_read_b128 v[174:177], v230 offset:52224
	ds_read_b128 v[178:181], v230 offset:53248
	ds_read_b128 v[182:185], v230 offset:54272
	ds_read_b128 v[186:189], v230 offset:55296
	ds_read_b128 v[190:193], v230 offset:56320
	global_load_lds_dwordx4 v[194:195], off
	s_add_i32 m0, s40, 0x2000
	s_add_u32 s30, s30, 0x20080
	v_lshl_add_u64 v[194:195], v[196:197], 0, s[60:61]
	s_addc_u32 s31, s31, 0
	s_add_i32 s40, s89, s34
	global_load_lds_dwordx4 v[194:195], off
	v_lshl_add_u64 v[194:195], s[30:31], 0, v[214:215]
	s_mov_b32 m0, s40
	s_nop 0
	global_load_lds_dwordx4 v[194:195], off
	v_lshl_add_u64 v[194:195], s[30:31], 0, v[210:211]
	s_add_i32 m0, s40, 0x2000
	s_nop 0
	global_load_lds_dwordx4 v[194:195], off
	v_lshl_add_u64 v[194:195], v[198:199], 0, s[60:61]
	s_mov_b32 m0, s46
	s_nop 0
	global_load_lds_dwordx4 v[194:195], off
	v_lshl_add_u64 v[194:195], v[200:201], 0, s[60:61]
	s_mov_b32 m0, s47
	s_nop 0
	global_load_lds_dwordx4 v[194:195], off
	s_waitcnt vmcnt(8)
	s_waitcnt lgkmcnt(0)
	s_barrier
	s_waitcnt lgkmcnt(0)
	v_mfma_f32_16x16x32_bf16 v[62:65], v[106:109], v[162:165], v[62:65]
	v_mfma_f32_16x16x32_bf16 v[58:61], v[114:117], v[162:165], v[58:61]
	v_mfma_f32_16x16x32_bf16 v[46:49], v[106:109], v[170:173], v[46:49]
	v_mfma_f32_16x16x32_bf16 v[42:45], v[114:117], v[170:173], v[42:45]
	v_mfma_f32_16x16x32_bf16 v[30:33], v[106:109], v[178:181], v[30:33]
	v_mfma_f32_16x16x32_bf16 v[26:29], v[114:117], v[178:181], v[26:29]
	v_mfma_f32_16x16x32_bf16 v[14:17], v[106:109], v[186:189], v[14:17]
	v_mfma_f32_16x16x32_bf16 v[10:13], v[114:117], v[186:189], v[10:13]
	v_mfma_f32_16x16x32_bf16 v[62:65], v[110:113], v[166:169], v[62:65]
	v_mfma_f32_16x16x32_bf16 v[58:61], v[118:121], v[166:169], v[58:61]
	v_mfma_f32_16x16x32_bf16 v[46:49], v[110:113], v[174:177], v[46:49]
	v_mfma_f32_16x16x32_bf16 v[42:45], v[118:121], v[174:177], v[42:45]
	v_mfma_f32_16x16x32_bf16 v[30:33], v[110:113], v[182:185], v[30:33]
	v_mfma_f32_16x16x32_bf16 v[26:29], v[118:121], v[182:185], v[26:29]
	v_mfma_f32_16x16x32_bf16 v[14:17], v[110:113], v[190:193], v[14:17]
	v_mfma_f32_16x16x32_bf16 v[10:13], v[118:121], v[190:193], v[10:13]
	v_mfma_f32_16x16x32_bf16 v[54:57], v[122:125], v[162:165], v[54:57]
	v_mfma_f32_16x16x32_bf16 v[50:53], v[142:145], v[162:165], v[50:53]
	v_mfma_f32_16x16x32_bf16 v[38:41], v[122:125], v[170:173], v[38:41]
	v_mfma_f32_16x16x32_bf16 v[34:37], v[142:145], v[170:173], v[34:37]
	v_mfma_f32_16x16x32_bf16 v[22:25], v[122:125], v[178:181], v[22:25]
	v_mfma_f32_16x16x32_bf16 v[18:21], v[142:145], v[178:181], v[18:21]
	v_mfma_f32_16x16x32_bf16 v[6:9], v[122:125], v[186:189], v[6:9]
	v_mfma_f32_16x16x32_bf16 v[2:5], v[142:145], v[186:189], v[2:5]
	v_mfma_f32_16x16x32_bf16 v[54:57], v[126:129], v[166:169], v[54:57]
	v_mfma_f32_16x16x32_bf16 v[50:53], v[150:153], v[166:169], v[50:53]
	v_mfma_f32_16x16x32_bf16 v[38:41], v[126:129], v[174:177], v[38:41]
	v_mfma_f32_16x16x32_bf16 v[34:37], v[150:153], v[174:177], v[34:37]
	v_mfma_f32_16x16x32_bf16 v[22:25], v[126:129], v[182:185], v[22:25]
	v_mfma_f32_16x16x32_bf16 v[18:21], v[150:153], v[182:185], v[18:21]
	v_mfma_f32_16x16x32_bf16 v[6:9], v[126:129], v[190:193], v[6:9]
	v_mfma_f32_16x16x32_bf16 v[2:5], v[150:153], v[190:193], v[2:5]
	s_barrier
	s_add_i32 s84, s84, 2
	s_add_u32 s4, s4, 0x100
	s_addc_u32 s5, s5, 0
	s_add_u32 s29, s29, 0x100
	s_addc_u32 s81, s81, 0
	s_cmp_gt_u32 s84, 5
	s_cbranch_scc0 .LBB0_314
	s_and_b64 vcc, exec, s[20:21]
	s_cbranch_vccz .LBB0_317
	s_barrier

; #define PG8_STAGE(bufoff, gbase, voff) do { _Pragma("unroll") for (int _i = 0; _i < 2; ++_i) \
;         __builtin_amdgcn_global_load_lds((const unsigned*)((const char*)(gbase) + (voff)[_i]), (PG8_LAS unsigned*)(lds + (bufoff) + ldsw + _i * 8192), 16, 0, 0); } while (0)
; #define PG8_LDA(dst, b, h) do { _Pragma("unroll") for (int m = 0; m < 4; ++m) _Pragma("unroll") for (int k = 0; k < 2; ++k) dst[m][k] = *(const PG8_LAS bf16x8*)(lds + PG8_SA(b, h) + aoff + m * 2048 + k * 1024); } while (0)
; #define PG8_LDB(dst, b, h) do { _Pragma("unroll") for (int n = 0; n < 2; ++n) _Pragma("unroll") for (int k = 0; k < 2; ++k) dst[n][k] = *(const PG8_LAS bf16x8*)(lds + PG8_SB(b, h) + boff + n * 2048 + k * 1024); } while (0)
; #define PG8_WAIT_V(n) asm volatile("s_waitcnt vmcnt(" #n ")" ::: "memory")
; #define PG8_WAIT_L(n) asm volatile("s_waitcnt lgkmcnt(" #n ")" ::: "memory")
; #define PG8_BAR __builtin_amdgcn_s_barrier()
; template <class Epi, class Sched, bool ALIGN_EPI = false, bool SP2 = false>
; __device__ __forceinline__ void gemm_phase(PG8_LAS unsigned char* lds, const Gemm g, const Sched& S, const Epi& E, int wave_s) {
;     ...
;         const bool has_next = S.next(ui + 1, nxt);
;         const char* nA = has_next ? (const char*)g.A + (size_t)nxt.pm * tstepA + (size_t)(nxt.pn / g.npg) * (size_t)(K * 2) : cA; const char* nB = has_next ? (const char*)g.Bt + (size_t)nxt.pn * tstepB : cB;
;         for (int t = 0; t < nt; t += 2) {
;             const bool last = (t == nt - 2);
;             const char* a1 = cA + (size_t)(t + 1) * kstep;
;             const char* a2 = last ? nA : cA + (size_t)(t + 2) * kstep; const char* b2 = last ? nB : cB + (size_t)(t + 2) * kstep;
;             const char* a3 = a2 + kstep; const char* b3 = b2 + kstep;
;             if (last && has_next) S.a_ready(nxt);
;             if constexpr (SP2) {
;             PG8_LDB(B0, 0, 0); PG8_LDB(B1, 0, 1); PG8_SCHED; PG8_LDA(At, 0, 0); PG8_STAGE(PG8_SA(1, 1), a1 + hstepA, voffA);
;             PG8_WAIT_V(8); PG8_WAIT_L(0); PG8_BAR; PG8_MMA(0, 0, At, B0); PG8_MMA(0, 1, At, B1); PG8_BAR; PG8_SCHED;
;             PG8_LDA(At, 0, 1); PG8_STAGE(PG8_SB(0, 0), b2, voffB); PG8_STAGE(PG8_SB(0, 1), b2 + hstepB, voffB); PG8_STAGE(PG8_SA(0, 0), a2, voffA);
;             PG8_WAIT_V(8); PG8_WAIT_L(0); PG8_BAR; PG8_MMA(1, 0, At, B0); PG8_MMA(1, 1, At, B1); PG8_BAR; PG8_SCHED;
.LBB0_411:
	s_ashr_i32 s15, s14, 31
	s_lshl_b64 s[2:3], s[14:15], 20
	s_add_u32 s28, s22, s2
	s_addc_u32 s29, s23, s3
	s_and_b64 s[2:3], s[4:5], exec
	s_cselect_b32 s2, s29, s31
	s_cselect_b32 s3, s28, s30
	s_add_u32 s4, s40, 0x80080
	s_addc_u32 s5, s41, 0
	s_add_u32 s15, s30, 0x100
	s_addc_u32 s21, s31, 0
	s_mov_b32 s94, -2
	s_add_u32 s30, s4, 0xfff80080
	s_addc_u32 s31, s5, -1
	s_add_i32 s95, 0, 0x10000
	s_cmp_eq_u32 s94, 28
	s_cselect_b32 s41, s27, s31
	s_cselect_b32 s40, s26, s30
	v_add_u32_e32 v149, s95, v147
	s_cselect_b32 s31, s2, s21
	s_cselect_b32 s30, s3, s15
	s_add_i32 vcc_lo, 0, 0x14000
	ds_read_b128 v[142:145], v149
	ds_read_b128 v[150:153], v149 offset:1024
	ds_read_b128 v[154:157], v149 offset:2048
	ds_read_b128 v[158:161], v149 offset:3072
	v_add_u32_e32 v149, vcc_lo, v147
	ds_read_b128 v[162:165], v149
	ds_read_b128 v[166:169], v149 offset:1024
	ds_read_b128 v[170:173], v149 offset:2048
	ds_read_b128 v[174:177], v149 offset:3072
	v_lshl_add_u64 v[210:211], s[4:5], 0, v[138:139]
	s_add_i32 m0, s35, 0xc000
	ds_read_b128 v[178:181], v148
	ds_read_b128 v[182:185], v148 offset:1024
	ds_read_b128 v[186:189], v148 offset:2048
	ds_read_b128 v[190:193], v148 offset:3072
	ds_read_b128 v[194:197], v148 offset:4096
	ds_read_b128 v[198:201], v148 offset:5120
	ds_read_b128 v[202:205], v148 offset:6144
	ds_read_b128 v[206:209], v148 offset:7168
	global_load_lds_dwordx4 v[210:211], off
	v_lshl_add_u64 v[210:211], s[4:5], 0, v[140:141]
	s_add_i32 m0, s35, 0xe000
	s_nop 0
	global_load_lds_dwordx4 v[210:211], off
	s_waitcnt vmcnt(8)
	s_waitcnt lgkmcnt(0)
	s_barrier
	s_waitcnt lgkmcnt(0)
	v_mfma_f32_16x16x32_bf16 v[126:129], v[142:145], v[178:181], 0
	v_mfma_f32_16x16x32_bf16 v[122:125], v[154:157], v[178:181], 0
	v_mfma_f32_16x16x32_bf16 v[110:113], v[142:145], v[186:189], 0
	v_mfma_f32_16x16x32_bf16 v[106:109], v[154:157], v[186:189], 0
	v_mfma_f32_16x16x32_bf16 v[94:97], v[142:145], v[194:197], 0
	v_mfma_f32_16x16x32_bf16 v[90:93], v[154:157], v[194:197], 0
	v_mfma_f32_16x16x32_bf16 v[78:81], v[142:145], v[202:205], 0
	v_mfma_f32_16x16x32_bf16 v[74:77], v[154:157], v[202:205], 0
	v_mfma_f32_16x16x32_bf16 v[126:129], v[150:153], v[182:185], v[126:129]
	v_mfma_f32_16x16x32_bf16 v[122:125], v[158:161], v[182:185], v[122:125]
	v_mfma_f32_16x16x32_bf16 v[110:113], v[150:153], v[190:193], v[110:113]
	v_mfma_f32_16x16x32_bf16 v[106:109], v[158:161], v[190:193], v[106:109]
	v_mfma_f32_16x16x32_bf16 v[94:97], v[150:153], v[198:201], v[94:97]
	v_mfma_f32_16x16x32_bf16 v[90:93], v[158:161], v[198:201], v[90:93]
	v_mfma_f32_16x16x32_bf16 v[78:81], v[150:153], v[206:209], v[78:81]
	v_mfma_f32_16x16x32_bf16 v[74:77], v[158:161], v[206:209], v[74:77]
	v_mfma_f32_16x16x32_bf16 v[118:121], v[162:165], v[178:181], 0
	v_mfma_f32_16x16x32_bf16 v[114:117], v[170:173], v[178:181], 0
	v_mfma_f32_16x16x32_bf16 v[102:105], v[162:165], v[186:189], 0
	v_mfma_f32_16x16x32_bf16 v[98:101], v[170:173], v[186:189], 0
	v_mfma_f32_16x16x32_bf16 v[86:89], v[162:165], v[194:197], 0
	v_mfma_f32_16x16x32_bf16 v[82:85], v[170:173], v[194:197], 0
	v_mfma_f32_16x16x32_bf16 v[70:73], v[162:165], v[202:205], 0
	v_mfma_f32_16x16x32_bf16 v[66:69], v[170:173], v[202:205], 0
	v_mfma_f32_16x16x32_bf16 v[118:121], v[166:169], v[182:185], v[118:121]
	v_mfma_f32_16x16x32_bf16 v[114:117], v[174:177], v[182:185], v[114:117]
	v_mfma_f32_16x16x32_bf16 v[102:105], v[166:169], v[190:193], v[102:105]
	v_mfma_f32_16x16x32_bf16 v[98:101], v[174:177], v[190:193], v[98:101]
	v_mfma_f32_16x16x32_bf16 v[86:89], v[166:169], v[198:201], v[86:89]
	v_mfma_f32_16x16x32_bf16 v[82:85], v[174:177], v[198:201], v[82:85]
	v_mfma_f32_16x16x32_bf16 v[70:73], v[166:169], v[206:209], v[70:73]
	v_mfma_f32_16x16x32_bf16 v[66:69], v[174:177], v[206:209], v[66:69]
	s_barrier
	s_add_i32 s95, s95, s34
	v_lshl_add_u64 v[210:211], s[30:31], 0, v[132:133]
	s_mov_b32 m0, s95
	ds_read_b128 v[178:181], v148 offset:16384
	ds_read_b128 v[182:185], v148 offset:17408
	ds_read_b128 v[186:189], v148 offset:18432
	ds_read_b128 v[190:193], v148 offset:19456
	ds_read_b128 v[194:197], v148 offset:20480
	ds_read_b128 v[198:201], v148 offset:21504
	ds_read_b128 v[202:205], v148 offset:22528
	ds_read_b128 v[206:209], v148 offset:23552
	global_load_lds_dwordx4 v[210:211], off
	s_add_i32 m0, s95, 0x2000
	s_add_u32 s96, s30, 0x80000
	v_lshl_add_u64 v[212:213], s[30:31], 0, v[136:137]
	s_addc_u32 s97, s31, 0
	s_add_i32 s95, vcc_lo, s34
	global_load_lds_dwordx4 v[212:213], off
	v_lshl_add_u64 v[214:215], s[96:97], 0, v[132:133]
	s_mov_b32 m0, s95
	v_lshl_add_u64 v[216:217], s[40:41], 0, v[134:135]
	global_load_lds_dwordx4 v[214:215], off
	v_lshl_add_u64 v[214:215], s[96:97], 0, v[136:137]
	s_add_i32 m0, s95, 0x2000
	s_nop 0
	global_load_lds_dwordx4 v[214:215], off
	v_lshl_add_u64 v[214:215], s[40:41], 0, v[130:131]
	s_mov_b32 m0, s35
	s_nop 0
	global_load_lds_dwordx4 v[214:215], off
	s_mov_b32 m0, s36
	s_nop 0
	global_load_lds_dwordx4 v[216:217], off
	s_waitcnt vmcnt(8)
	s_waitcnt lgkmcnt(0)
	s_barrier
; #define PG8_STAGE(bufoff, gbase, voff) do { _Pragma("unroll") for (int _i = 0; _i < 2; ++_i) \
;         __builtin_amdgcn_global_load_lds((const unsigned*)((const char*)(gbase) + (voff)[_i]), (PG8_LAS unsigned*)(lds + (bufoff) + ldsw + _i * 8192), 16, 0, 0); } while (0)
; #define PG8_LDA(dst, b, h) do { _Pragma("unroll") for (int m = 0; m < 4; ++m) _Pragma("unroll") for (int k = 0; k < 2; ++k) dst[m][k] = *(const PG8_LAS bf16x8*)(lds + PG8_SA(b, h) + aoff + m * 2048 + k * 1024); } while (0)
; #define PG8_LDB(dst, b, h) do { _Pragma("unroll") for (int n = 0; n < 2; ++n) _Pragma("unroll") for (int k = 0; k < 2; ++k) dst[n][k] = *(const PG8_LAS bf16x8*)(lds + PG8_SB(b, h) + boff + n * 2048 + k * 1024); } while (0)
; #define PG8_MMA(ai, bj, At, Bt) do { __builtin_amdgcn_s_setprio(1); _Pragma("unroll") for (int m = 0; m < 4; ++m) _Pragma("unroll") for (int n = 0; n < 2; ++n) _Pragma("unroll") for (int k = 0; k < 2; ++k) \
;         acc[ai][bj][m][n] = __builtin_amdgcn_mfma_f32_16x16x32_bf16(Bt[n][k], At[m][k], acc[ai][bj][m][n], 0, 0, 0); __builtin_amdgcn_s_setprio(0); } while (0)
; #define PG8_WAIT_V(n) asm volatile("s_waitcnt vmcnt(" #n ")" ::: "memory")
; #define PG8_WAIT_L(n) asm volatile("s_waitcnt lgkmcnt(" #n ")" ::: "memory")
; #define PG8_BAR __builtin_amdgcn_s_barrier()
; #define PG8_SCHED __builtin_amdgcn_sched_barrier(0)
; template <class Epi, class Sched, bool ALIGN_EPI = false, bool SP2 = false>
; __device__ __forceinline__ void gemm_phase(PG8_LAS unsigned char* lds, const Gemm g, const Sched& S, const Epi& E, int wave_s) {
;     ...
;             PG8_WAIT_V(8); PG8_WAIT_L(0); PG8_BAR; PG8_MMA(1, 0, At, B0); PG8_MMA(1, 1, At, B1); PG8_BAR; PG8_SCHED;
;             PG8_LDB(B0, 1, 0); PG8_LDB(B1, 1, 1); PG8_SCHED; PG8_LDA(At, 1, 0); PG8_STAGE(PG8_SA(0, 1), a2 + hstepA, voffA);
;             PG8_WAIT_V(8); PG8_WAIT_L(0); PG8_BAR; PG8_MMA(0, 0, At, B0); PG8_MMA(0, 1, At, B1); PG8_BAR; PG8_SCHED;
	s_waitcnt lgkmcnt(0)
	v_mfma_f32_16x16x32_bf16 v[62:65], v[142:145], v[178:181], 0
	v_mfma_f32_16x16x32_bf16 v[58:61], v[154:157], v[178:181], 0
	v_mfma_f32_16x16x32_bf16 v[46:49], v[142:145], v[186:189], 0
	v_mfma_f32_16x16x32_bf16 v[42:45], v[154:157], v[186:189], 0
	v_mfma_f32_16x16x32_bf16 v[30:33], v[142:145], v[194:197], 0
	v_mfma_f32_16x16x32_bf16 v[26:29], v[154:157], v[194:197], 0
	v_mfma_f32_16x16x32_bf16 v[14:17], v[142:145], v[202:205], 0
	v_mfma_f32_16x16x32_bf16 v[10:13], v[154:157], v[202:205], 0
	v_mfma_f32_16x16x32_bf16 v[62:65], v[150:153], v[182:185], v[62:65]
	v_mfma_f32_16x16x32_bf16 v[58:61], v[158:161], v[182:185], v[58:61]
	v_mfma_f32_16x16x32_bf16 v[46:49], v[150:153], v[190:193], v[46:49]
	v_mfma_f32_16x16x32_bf16 v[42:45], v[158:161], v[190:193], v[42:45]
	v_mfma_f32_16x16x32_bf16 v[30:33], v[150:153], v[198:201], v[30:33]
	v_mfma_f32_16x16x32_bf16 v[26:29], v[158:161], v[198:201], v[26:29]
	v_mfma_f32_16x16x32_bf16 v[14:17], v[150:153], v[206:209], v[14:17]
	v_mfma_f32_16x16x32_bf16 v[10:13], v[158:161], v[206:209], v[10:13]
	v_mfma_f32_16x16x32_bf16 v[54:57], v[162:165], v[178:181], 0
	v_mfma_f32_16x16x32_bf16 v[50:53], v[170:173], v[178:181], 0
	v_mfma_f32_16x16x32_bf16 v[38:41], v[162:165], v[186:189], 0
	v_mfma_f32_16x16x32_bf16 v[34:37], v[170:173], v[186:189], 0
	v_mfma_f32_16x16x32_bf16 v[22:25], v[162:165], v[194:197], 0
	v_mfma_f32_16x16x32_bf16 v[18:21], v[170:173], v[194:197], 0
	v_mfma_f32_16x16x32_bf16 v[6:9], v[162:165], v[202:205], 0
	v_mfma_f32_16x16x32_bf16 v[2:5], v[170:173], v[202:205], 0
	v_mfma_f32_16x16x32_bf16 v[54:57], v[166:169], v[182:185], v[54:57]
	v_mfma_f32_16x16x32_bf16 v[50:53], v[174:177], v[182:185], v[50:53]
	v_mfma_f32_16x16x32_bf16 v[38:41], v[166:169], v[190:193], v[38:41]
	v_mfma_f32_16x16x32_bf16 v[34:37], v[174:177], v[190:193], v[34:37]
	v_mfma_f32_16x16x32_bf16 v[22:25], v[166:169], v[198:201], v[22:25]
	v_mfma_f32_16x16x32_bf16 v[18:21], v[174:177], v[198:201], v[18:21]
	v_mfma_f32_16x16x32_bf16 v[6:9], v[166:169], v[206:209], v[6:9]
	v_mfma_f32_16x16x32_bf16 v[2:5], v[174:177], v[206:209], v[2:5]
	s_barrier
	s_add_i32 s95, 0, 0x18000
	v_add_u32_e32 v149, s95, v147
	s_add_i32 s96, 0, 0x1c000
	ds_read_b128 v[142:145], v149
	ds_read_b128 v[150:153], v149 offset:1024
	ds_read_b128 v[154:157], v149 offset:2048
	ds_read_b128 v[158:161], v149 offset:3072
	v_add_u32_e32 v149, s96, v147
	ds_read_b128 v[162:165], v149
	ds_read_b128 v[166:169], v149 offset:1024
	ds_read_b128 v[170:173], v149 offset:2048
	ds_read_b128 v[174:177], v149 offset:3072
	s_add_u32 s40, s40, 0x80000
	s_addc_u32 s41, s41, 0
	s_mov_b32 m0, s37
	v_lshl_add_u64 v[218:219], s[40:41], 0, v[130:131]
	ds_read_b128 v[178:181], v148 offset:32768
	ds_read_b128 v[182:185], v148 offset:33792
	ds_read_b128 v[186:189], v148 offset:34816
	ds_read_b128 v[190:193], v148 offset:35840
	ds_read_b128 v[194:197], v148 offset:36864
	ds_read_b128 v[198:201], v148 offset:37888
	ds_read_b128 v[202:205], v148 offset:38912
	ds_read_b128 v[206:209], v148 offset:39936
	global_load_lds_dwordx4 v[218:219], off
	v_lshl_add_u64 v[218:219], s[40:41], 0, v[134:135]
	s_mov_b32 m0, s42
	s_nop 0
	global_load_lds_dwordx4 v[218:219], off
	s_waitcnt vmcnt(8)
	s_waitcnt lgkmcnt(0)
	s_barrier
	s_waitcnt lgkmcnt(0)
	v_mfma_f32_16x16x32_bf16 v[126:129], v[142:145], v[178:181], v[126:129]
	v_mfma_f32_16x16x32_bf16 v[122:125], v[154:157], v[178:181], v[122:125]
	v_mfma_f32_16x16x32_bf16 v[110:113], v[142:145], v[186:189], v[110:113]
	v_mfma_f32_16x16x32_bf16 v[106:109], v[154:157], v[186:189], v[106:109]
	v_mfma_f32_16x16x32_bf16 v[94:97], v[142:145], v[194:197], v[94:97]
	v_mfma_f32_16x16x32_bf16 v[90:93], v[154:157], v[194:197], v[90:93]
	v_mfma_f32_16x16x32_bf16 v[78:81], v[142:145], v[202:205], v[78:81]
	v_mfma_f32_16x16x32_bf16 v[74:77], v[154:157], v[202:205], v[74:77]
	v_mfma_f32_16x16x32_bf16 v[126:129], v[150:153], v[182:185], v[126:129]
	v_mfma_f32_16x16x32_bf16 v[122:125], v[158:161], v[182:185], v[122:125]
	v_mfma_f32_16x16x32_bf16 v[110:113], v[150:153], v[190:193], v[110:113]
	v_mfma_f32_16x16x32_bf16 v[106:109], v[158:161], v[190:193], v[106:109]
	v_mfma_f32_16x16x32_bf16 v[94:97], v[150:153], v[198:201], v[94:97]
	v_mfma_f32_16x16x32_bf16 v[90:93], v[158:161], v[198:201], v[90:93]
	v_mfma_f32_16x16x32_bf16 v[78:81], v[150:153], v[206:209], v[78:81]
	v_mfma_f32_16x16x32_bf16 v[74:77], v[158:161], v[206:209], v[74:77]
	v_mfma_f32_16x16x32_bf16 v[118:121], v[162:165], v[178:181], v[118:121]
	v_mfma_f32_16x16x32_bf16 v[114:117], v[170:173], v[178:181], v[114:117]
	v_mfma_f32_16x16x32_bf16 v[102:105], v[162:165], v[186:189], v[102:105]
	v_mfma_f32_16x16x32_bf16 v[98:101], v[170:173], v[186:189], v[98:101]
	v_mfma_f32_16x16x32_bf16 v[86:89], v[162:165], v[194:197], v[86:89]
	v_mfma_f32_16x16x32_bf16 v[82:85], v[170:173], v[194:197], v[82:85]
	v_mfma_f32_16x16x32_bf16 v[70:73], v[162:165], v[202:205], v[70:73]
	v_mfma_f32_16x16x32_bf16 v[66:69], v[170:173], v[202:205], v[66:69]
	v_mfma_f32_16x16x32_bf16 v[118:121], v[166:169], v[182:185], v[118:121]
	v_mfma_f32_16x16x32_bf16 v[114:117], v[174:177], v[182:185], v[114:117]
	v_mfma_f32_16x16x32_bf16 v[102:105], v[166:169], v[190:193], v[102:105]
	v_mfma_f32_16x16x32_bf16 v[98:101], v[174:177], v[190:193], v[98:101]
	v_mfma_f32_16x16x32_bf16 v[86:89], v[166:169], v[198:201], v[86:89]
	v_mfma_f32_16x16x32_bf16 v[82:85], v[174:177], v[198:201], v[82:85]
	v_mfma_f32_16x16x32_bf16 v[70:73], v[166:169], v[206:209], v[70:73]
	v_mfma_f32_16x16x32_bf16 v[66:69], v[174:177], v[206:209], v[66:69]
	s_barrier
; #define PG8_STAGE(bufoff, gbase, voff) do { _Pragma("unroll") for (int _i = 0; _i < 2; ++_i) \
;         __builtin_amdgcn_global_load_lds((const unsigned*)((const char*)(gbase) + (voff)[_i]), (PG8_LAS unsigned*)(lds + (bufoff) + ldsw + _i * 8192), 16, 0, 0); } while (0)
; #define PG8_LDA(dst, b, h) do { _Pragma("unroll") for (int m = 0; m < 4; ++m) _Pragma("unroll") for (int k = 0; k < 2; ++k) dst[m][k] = *(const PG8_LAS bf16x8*)(lds + PG8_SA(b, h) + aoff + m * 2048 + k * 1024); } while (0)
; #define PG8_LDB(dst, b, h) do { _Pragma("unroll") for (int n = 0; n < 2; ++n) _Pragma("unroll") for (int k = 0; k < 2; ++k) dst[n][k] = *(const PG8_LAS bf16x8*)(lds + PG8_SB(b, h) + boff + n * 2048 + k * 1024); } while (0)
; #define PG8_MMA(ai, bj, At, Bt) do { __builtin_amdgcn_s_setprio(1); _Pragma("unroll") for (int m = 0; m < 4; ++m) _Pragma("unroll") for (int n = 0; n < 2; ++n) _Pragma("unroll") for (int k = 0; k < 2; ++k) \
;         acc[ai][bj][m][n] = __builtin_amdgcn_mfma_f32_16x16x32_bf16(Bt[n][k], At[m][k], acc[ai][bj][m][n], 0, 0, 0); __builtin_amdgcn_s_setprio(0); } while (0)
; #define PG8_WAIT_V(n) asm volatile("s_waitcnt vmcnt(" #n ")" ::: "memory")
; #define PG8_BAR __builtin_amdgcn_s_barrier()
; template <class Epi, class Sched, bool ALIGN_EPI = false, bool SP2 = false>
; __device__ __forceinline__ void gemm_phase(PG8_LAS unsigned char* lds, const Gemm g, const Sched& S, const Epi& E, int wave_s) {
;     ...
;         for (int t = 0; t < nt; t += 2) {
;             const bool last = (t == nt - 2);
;             const char* a1 = cA + (size_t)(t + 1) * kstep;
;             const char* a2 = last ? nA : cA + (size_t)(t + 2) * kstep; const char* b2 = last ? nB : cB + (size_t)(t + 2) * kstep;
;             const char* a3 = a2 + kstep; const char* b3 = b2 + kstep;
;             if (last && has_next) S.a_ready(nxt);
;             if constexpr (SP2) {
;             PG8_LDB(B0, 0, 0); PG8_LDB(B1, 0, 1); PG8_SCHED; PG8_LDA(At, 0, 0); PG8_STAGE(PG8_SA(1, 1), a1 + hstepA, voffA);
;             PG8_WAIT_V(8); PG8_WAIT_L(0); PG8_BAR; PG8_MMA(0, 0, At, B0); PG8_MMA(0, 1, At, B1); PG8_BAR; PG8_SCHED;
;     ...
;             PG8_LDA(At, 1, 1); PG8_STAGE(PG8_SB(1, 0), b3, voffB); PG8_STAGE(PG8_SB(1, 1), b3 + hstepB, voffB); PG8_STAGE(PG8_SA(1, 0), a3, voffA);
;             PG8_WAIT_V(8); PG8_WAIT_L(0); PG8_BAR; PG8_MMA(1, 0, At, B0); PG8_MMA(1, 1, At, B1); PG8_BAR; PG8_SCHED;
	s_add_i32 s40, s95, s34
	v_lshl_add_u64 v[210:211], v[210:211], 0, s[60:61]
	s_mov_b32 m0, s40
	ds_read_b128 v[178:181], v148 offset:49152
	ds_read_b128 v[182:185], v148 offset:50176
	ds_read_b128 v[186:189], v148 offset:51200
	ds_read_b128 v[190:193], v148 offset:52224
	ds_read_b128 v[194:197], v148 offset:53248
	ds_read_b128 v[198:201], v148 offset:54272
	ds_read_b128 v[202:205], v148 offset:55296
	ds_read_b128 v[206:209], v148 offset:56320
	global_load_lds_dwordx4 v[210:211], off
	s_add_i32 m0, s40, 0x2000
	s_add_u32 s30, s30, 0x80080
	v_lshl_add_u64 v[210:211], v[212:213], 0, s[60:61]
	s_addc_u32 s31, s31, 0
	s_add_i32 s40, s96, s34
	global_load_lds_dwordx4 v[210:211], off
	v_lshl_add_u64 v[210:211], s[30:31], 0, v[132:133]
	s_mov_b32 m0, s40
	s_nop 0
	global_load_lds_dwordx4 v[210:211], off
	v_lshl_add_u64 v[210:211], s[30:31], 0, v[136:137]
	s_add_i32 m0, s40, 0x2000
	s_nop 0
	global_load_lds_dwordx4 v[210:211], off
	v_lshl_add_u64 v[210:211], v[214:215], 0, s[60:61]
	s_mov_b32 m0, s45
	s_nop 0
	global_load_lds_dwordx4 v[210:211], off
	v_lshl_add_u64 v[210:211], v[216:217], 0, s[60:61]
	s_mov_b32 m0, s46
	s_nop 0
	global_load_lds_dwordx4 v[210:211], off
	s_waitcnt vmcnt(8)
	s_waitcnt lgkmcnt(0)
	s_barrier
	s_waitcnt lgkmcnt(0)
	v_mfma_f32_16x16x32_bf16 v[62:65], v[142:145], v[178:181], v[62:65]
	v_mfma_f32_16x16x32_bf16 v[58:61], v[154:157], v[178:181], v[58:61]
	v_mfma_f32_16x16x32_bf16 v[46:49], v[142:145], v[186:189], v[46:49]
	v_mfma_f32_16x16x32_bf16 v[42:45], v[154:157], v[186:189], v[42:45]
	v_mfma_f32_16x16x32_bf16 v[30:33], v[142:145], v[194:197], v[30:33]
	v_mfma_f32_16x16x32_bf16 v[26:29], v[154:157], v[194:197], v[26:29]
	v_mfma_f32_16x16x32_bf16 v[14:17], v[142:145], v[202:205], v[14:17]
	v_mfma_f32_16x16x32_bf16 v[10:13], v[154:157], v[202:205], v[10:13]
	v_mfma_f32_16x16x32_bf16 v[62:65], v[150:153], v[182:185], v[62:65]
	v_mfma_f32_16x16x32_bf16 v[58:61], v[158:161], v[182:185], v[58:61]
	v_mfma_f32_16x16x32_bf16 v[46:49], v[150:153], v[190:193], v[46:49]
	v_mfma_f32_16x16x32_bf16 v[42:45], v[158:161], v[190:193], v[42:45]
	v_mfma_f32_16x16x32_bf16 v[30:33], v[150:153], v[198:201], v[30:33]
	v_mfma_f32_16x16x32_bf16 v[26:29], v[158:161], v[198:201], v[26:29]
	v_mfma_f32_16x16x32_bf16 v[14:17], v[150:153], v[206:209], v[14:17]
	v_mfma_f32_16x16x32_bf16 v[10:13], v[158:161], v[206:209], v[10:13]
	v_mfma_f32_16x16x32_bf16 v[54:57], v[162:165], v[178:181], v[54:57]
	v_mfma_f32_16x16x32_bf16 v[50:53], v[170:173], v[178:181], v[50:53]
	v_mfma_f32_16x16x32_bf16 v[38:41], v[162:165], v[186:189], v[38:41]
	v_mfma_f32_16x16x32_bf16 v[34:37], v[170:173], v[186:189], v[34:37]
	v_mfma_f32_16x16x32_bf16 v[22:25], v[162:165], v[194:197], v[22:25]
	v_mfma_f32_16x16x32_bf16 v[18:21], v[170:173], v[194:197], v[18:21]
	v_mfma_f32_16x16x32_bf16 v[6:9], v[162:165], v[202:205], v[6:9]
	v_mfma_f32_16x16x32_bf16 v[2:5], v[170:173], v[202:205], v[2:5]
	v_mfma_f32_16x16x32_bf16 v[54:57], v[166:169], v[182:185], v[54:57]
	v_mfma_f32_16x16x32_bf16 v[50:53], v[174:177], v[182:185], v[50:53]
	v_mfma_f32_16x16x32_bf16 v[38:41], v[166:169], v[190:193], v[38:41]
	v_mfma_f32_16x16x32_bf16 v[34:37], v[174:177], v[190:193], v[34:37]
	v_mfma_f32_16x16x32_bf16 v[22:25], v[166:169], v[198:201], v[22:25]
	v_mfma_f32_16x16x32_bf16 v[18:21], v[174:177], v[198:201], v[18:21]
	v_mfma_f32_16x16x32_bf16 v[6:9], v[166:169], v[206:209], v[6:9]
	v_mfma_f32_16x16x32_bf16 v[2:5], v[174:177], v[206:209], v[2:5]
	s_barrier
	s_add_i32 s94, s94, 2
	s_add_u32 s4, s4, 0x100
	s_addc_u32 s5, s5, 0
	s_add_u32 s15, s15, 0x100
	s_addc_u32 s21, s21, 0
	s_cmp_gt_u32 s94, 29
.LBB0_412:
	s_add_u32 s30, s4, 0xfff80080
	s_addc_u32 s31, s5, -1
	s_add_i32 s95, 0, 0x10000
	s_cmp_eq_u32 s94, 28
	s_cselect_b32 s41, s27, s31
	s_cselect_b32 s40, s26, s30
	v_add_u32_e32 v149, s95, v147
	s_cselect_b32 s31, s2, s21
	s_cselect_b32 s30, s3, s15
	s_add_i32 vcc_lo, 0, 0x14000
	ds_read_b128 v[142:145], v149
	ds_read_b128 v[150:153], v149 offset:1024
	ds_read_b128 v[154:157], v149 offset:2048
	ds_read_b128 v[158:161], v149 offset:3072
	v_add_u32_e32 v149, vcc_lo, v147
	ds_read_b128 v[162:165], v149
	ds_read_b128 v[166:169], v149 offset:1024
	ds_read_b128 v[170:173], v149 offset:2048
	ds_read_b128 v[174:177], v149 offset:3072
	v_lshl_add_u64 v[210:211], s[4:5], 0, v[138:139]
	s_add_i32 m0, s35, 0xc000
	ds_read_b128 v[178:181], v148
	ds_read_b128 v[182:185], v148 offset:1024
	ds_read_b128 v[186:189], v148 offset:2048
	ds_read_b128 v[190:193], v148 offset:3072
	ds_read_b128 v[194:197], v148 offset:4096
	ds_read_b128 v[198:201], v148 offset:5120
	ds_read_b128 v[202:205], v148 offset:6144
	ds_read_b128 v[206:209], v148 offset:7168
	global_load_lds_dwordx4 v[210:211], off
	v_lshl_add_u64 v[210:211], s[4:5], 0, v[140:141]
	s_add_i32 m0, s35, 0xe000
	s_nop 0
	global_load_lds_dwordx4 v[210:211], off
	s_waitcnt vmcnt(8)
	s_waitcnt lgkmcnt(0)
	s_barrier
; #define PG8_STAGE(bufoff, gbase, voff) do { _Pragma("unroll") for (int _i = 0; _i < 2; ++_i) \
;         __builtin_amdgcn_global_load_lds((const unsigned*)((const char*)(gbase) + (voff)[_i]), (PG8_LAS unsigned*)(lds + (bufoff) + ldsw + _i * 8192), 16, 0, 0); } while (0)
; #define PG8_LDA(dst, b, h) do { _Pragma("unroll") for (int m = 0; m < 4; ++m) _Pragma("unroll") for (int k = 0; k < 2; ++k) dst[m][k] = *(const PG8_LAS bf16x8*)(lds + PG8_SA(b, h) + aoff + m * 2048 + k * 1024); } while (0)
; #define PG8_LDB(dst, b, h) do { _Pragma("unroll") for (int n = 0; n < 2; ++n) _Pragma("unroll") for (int k = 0; k < 2; ++k) dst[n][k] = *(const PG8_LAS bf16x8*)(lds + PG8_SB(b, h) + boff + n * 2048 + k * 1024); } while (0)
; #define PG8_MMA(ai, bj, At, Bt) do { __builtin_amdgcn_s_setprio(1); _Pragma("unroll") for (int m = 0; m < 4; ++m) _Pragma("unroll") for (int n = 0; n < 2; ++n) _Pragma("unroll") for (int k = 0; k < 2; ++k) \
;         acc[ai][bj][m][n] = __builtin_amdgcn_mfma_f32_16x16x32_bf16(Bt[n][k], At[m][k], acc[ai][bj][m][n], 0, 0, 0); __builtin_amdgcn_s_setprio(0); } while (0)
; #define PG8_WAIT_V(n) asm volatile("s_waitcnt vmcnt(" #n ")" ::: "memory")
; #define PG8_WAIT_L(n) asm volatile("s_waitcnt lgkmcnt(" #n ")" ::: "memory")
; #define PG8_BAR __builtin_amdgcn_s_barrier()
; #define PG8_SCHED __builtin_amdgcn_sched_barrier(0)
; template <class Epi, class Sched, bool ALIGN_EPI = false, bool SP2 = false>
; __device__ __forceinline__ void gemm_phase(PG8_LAS unsigned char* lds, const Gemm g, const Sched& S, const Epi& E, int wave_s) {
;     ...
;             PG8_LDB(B0, 0, 0); PG8_LDB(B1, 0, 1); PG8_SCHED; PG8_LDA(At, 0, 0); PG8_STAGE(PG8_SA(1, 1), a1 + hstepA, voffA);
;             PG8_WAIT_V(8); PG8_WAIT_L(0); PG8_BAR; PG8_MMA(0, 0, At, B0); PG8_MMA(0, 1, At, B1); PG8_BAR; PG8_SCHED;
;             PG8_LDA(At, 0, 1); PG8_STAGE(PG8_SB(0, 0), b2, voffB); PG8_STAGE(PG8_SB(0, 1), b2 + hstepB, voffB); PG8_STAGE(PG8_SA(0, 0), a2, voffA);
;             PG8_WAIT_V(8); PG8_WAIT_L(0); PG8_BAR; PG8_MMA(1, 0, At, B0); PG8_MMA(1, 1, At, B1); PG8_BAR; PG8_SCHED;
	s_waitcnt lgkmcnt(0)
	v_mfma_f32_16x16x32_bf16 v[126:129], v[142:145], v[178:181], v[126:129]
	v_mfma_f32_16x16x32_bf16 v[122:125], v[154:157], v[178:181], v[122:125]
	v_mfma_f32_16x16x32_bf16 v[110:113], v[142:145], v[186:189], v[110:113]
	v_mfma_f32_16x16x32_bf16 v[106:109], v[154:157], v[186:189], v[106:109]
	v_mfma_f32_16x16x32_bf16 v[94:97], v[142:145], v[194:197], v[94:97]
	v_mfma_f32_16x16x32_bf16 v[90:93], v[154:157], v[194:197], v[90:93]
	v_mfma_f32_16x16x32_bf16 v[78:81], v[142:145], v[202:205], v[78:81]
	v_mfma_f32_16x16x32_bf16 v[74:77], v[154:157], v[202:205], v[74:77]
	v_mfma_f32_16x16x32_bf16 v[126:129], v[150:153], v[182:185], v[126:129]
	v_mfma_f32_16x16x32_bf16 v[122:125], v[158:161], v[182:185], v[122:125]
	v_mfma_f32_16x16x32_bf16 v[110:113], v[150:153], v[190:193], v[110:113]
	v_mfma_f32_16x16x32_bf16 v[106:109], v[158:161], v[190:193], v[106:109]
	v_mfma_f32_16x16x32_bf16 v[94:97], v[150:153], v[198:201], v[94:97]
	v_mfma_f32_16x16x32_bf16 v[90:93], v[158:161], v[198:201], v[90:93]
	v_mfma_f32_16x16x32_bf16 v[78:81], v[150:153], v[206:209], v[78:81]
	v_mfma_f32_16x16x32_bf16 v[74:77], v[158:161], v[206:209], v[74:77]
	v_mfma_f32_16x16x32_bf16 v[118:121], v[162:165], v[178:181], v[118:121]
	v_mfma_f32_16x16x32_bf16 v[114:117], v[170:173], v[178:181], v[114:117]
	v_mfma_f32_16x16x32_bf16 v[102:105], v[162:165], v[186:189], v[102:105]
	v_mfma_f32_16x16x32_bf16 v[98:101], v[170:173], v[186:189], v[98:101]
	v_mfma_f32_16x16x32_bf16 v[86:89], v[162:165], v[194:197], v[86:89]
	v_mfma_f32_16x16x32_bf16 v[82:85], v[170:173], v[194:197], v[82:85]
	v_mfma_f32_16x16x32_bf16 v[70:73], v[162:165], v[202:205], v[70:73]
	v_mfma_f32_16x16x32_bf16 v[66:69], v[170:173], v[202:205], v[66:69]
	v_mfma_f32_16x16x32_bf16 v[118:121], v[166:169], v[182:185], v[118:121]
	v_mfma_f32_16x16x32_bf16 v[114:117], v[174:177], v[182:185], v[114:117]
	v_mfma_f32_16x16x32_bf16 v[102:105], v[166:169], v[190:193], v[102:105]
	v_mfma_f32_16x16x32_bf16 v[98:101], v[174:177], v[190:193], v[98:101]
	v_mfma_f32_16x16x32_bf16 v[86:89], v[166:169], v[198:201], v[86:89]
	v_mfma_f32_16x16x32_bf16 v[82:85], v[174:177], v[198:201], v[82:85]
	v_mfma_f32_16x16x32_bf16 v[70:73], v[166:169], v[206:209], v[70:73]
	v_mfma_f32_16x16x32_bf16 v[66:69], v[174:177], v[206:209], v[66:69]
	s_barrier
	s_add_i32 s95, s95, s34
	v_lshl_add_u64 v[210:211], s[30:31], 0, v[132:133]
	s_mov_b32 m0, s95
	ds_read_b128 v[178:181], v148 offset:16384
	ds_read_b128 v[182:185], v148 offset:17408
	ds_read_b128 v[186:189], v148 offset:18432
	ds_read_b128 v[190:193], v148 offset:19456
	ds_read_b128 v[194:197], v148 offset:20480
	ds_read_b128 v[198:201], v148 offset:21504
	ds_read_b128 v[202:205], v148 offset:22528
	ds_read_b128 v[206:209], v148 offset:23552
	global_load_lds_dwordx4 v[210:211], off
	s_add_i32 m0, s95, 0x2000
	s_add_u32 s96, s30, 0x80000
	v_lshl_add_u64 v[212:213], s[30:31], 0, v[136:137]
	s_addc_u32 s97, s31, 0
	s_add_i32 s95, vcc_lo, s34
	global_load_lds_dwordx4 v[212:213], off
	v_lshl_add_u64 v[214:215], s[96:97], 0, v[132:133]
	s_mov_b32 m0, s95
	v_lshl_add_u64 v[216:217], s[40:41], 0, v[134:135]
	global_load_lds_dwordx4 v[214:215], off
	v_lshl_add_u64 v[214:215], s[96:97], 0, v[136:137]
	s_add_i32 m0, s95, 0x2000
	s_nop 0
	global_load_lds_dwordx4 v[214:215], off
	v_lshl_add_u64 v[214:215], s[40:41], 0, v[130:131]
	s_mov_b32 m0, s35
	s_nop 0
	global_load_lds_dwordx4 v[214:215], off
	s_mov_b32 m0, s36
	s_nop 0
	global_load_lds_dwordx4 v[216:217], off
	s_waitcnt vmcnt(8)
	s_waitcnt lgkmcnt(0)
	s_barrier
	s_waitcnt lgkmcnt(0)
	v_mfma_f32_16x16x32_bf16 v[62:65], v[142:145], v[178:181], v[62:65]
	v_mfma_f32_16x16x32_bf16 v[58:61], v[154:157], v[178:181], v[58:61]
	v_mfma_f32_16x16x32_bf16 v[46:49], v[142:145], v[186:189], v[46:49]
	v_mfma_f32_16x16x32_bf16 v[42:45], v[154:157], v[186:189], v[42:45]
	v_mfma_f32_16x16x32_bf16 v[30:33], v[142:145], v[194:197], v[30:33]
	v_mfma_f32_16x16x32_bf16 v[26:29], v[154:157], v[194:197], v[26:29]
	v_mfma_f32_16x16x32_bf16 v[14:17], v[142:145], v[202:205], v[14:17]
	v_mfma_f32_16x16x32_bf16 v[10:13], v[154:157], v[202:205], v[10:13]
	v_mfma_f32_16x16x32_bf16 v[62:65], v[150:153], v[182:185], v[62:65]
	v_mfma_f32_16x16x32_bf16 v[58:61], v[158:161], v[182:185], v[58:61]
	v_mfma_f32_16x16x32_bf16 v[46:49], v[150:153], v[190:193], v[46:49]
	v_mfma_f32_16x16x32_bf16 v[42:45], v[158:161], v[190:193], v[42:45]
	v_mfma_f32_16x16x32_bf16 v[30:33], v[150:153], v[198:201], v[30:33]
	v_mfma_f32_16x16x32_bf16 v[26:29], v[158:161], v[198:201], v[26:29]
	v_mfma_f32_16x16x32_bf16 v[14:17], v[150:153], v[206:209], v[14:17]
	v_mfma_f32_16x16x32_bf16 v[10:13], v[158:161], v[206:209], v[10:13]
	v_mfma_f32_16x16x32_bf16 v[54:57], v[162:165], v[178:181], v[54:57]
	v_mfma_f32_16x16x32_bf16 v[50:53], v[170:173], v[178:181], v[50:53]
	v_mfma_f32_16x16x32_bf16 v[38:41], v[162:165], v[186:189], v[38:41]
	v_mfma_f32_16x16x32_bf16 v[34:37], v[170:173], v[186:189], v[34:37]
	v_mfma_f32_16x16x32_bf16 v[22:25], v[162:165], v[194:197], v[22:25]
	v_mfma_f32_16x16x32_bf16 v[18:21], v[170:173], v[194:197], v[18:21]
	v_mfma_f32_16x16x32_bf16 v[6:9], v[162:165], v[202:205], v[6:9]
	v_mfma_f32_16x16x32_bf16 v[2:5], v[170:173], v[202:205], v[2:5]
	v_mfma_f32_16x16x32_bf16 v[54:57], v[166:169], v[182:185], v[54:57]
	v_mfma_f32_16x16x32_bf16 v[50:53], v[174:177], v[182:185], v[50:53]
	v_mfma_f32_16x16x32_bf16 v[38:41], v[166:169], v[190:193], v[38:41]
	v_mfma_f32_16x16x32_bf16 v[34:37], v[174:177], v[190:193], v[34:37]
	v_mfma_f32_16x16x32_bf16 v[22:25], v[166:169], v[198:201], v[22:25]
	v_mfma_f32_16x16x32_bf16 v[18:21], v[174:177], v[198:201], v[18:21]
	v_mfma_f32_16x16x32_bf16 v[6:9], v[166:169], v[206:209], v[6:9]
	v_mfma_f32_16x16x32_bf16 v[2:5], v[174:177], v[206:209], v[2:5]
	s_barrier
; #define PG8_STAGE(bufoff, gbase, voff) do { _Pragma("unroll") for (int _i = 0; _i < 2; ++_i) \
;         __builtin_amdgcn_global_load_lds((const unsigned*)((const char*)(gbase) + (voff)[_i]), (PG8_LAS unsigned*)(lds + (bufoff) + ldsw + _i * 8192), 16, 0, 0); } while (0)
; #define PG8_LDA(dst, b, h) do { _Pragma("unroll") for (int m = 0; m < 4; ++m) _Pragma("unroll") for (int k = 0; k < 2; ++k) dst[m][k] = *(const PG8_LAS bf16x8*)(lds + PG8_SA(b, h) + aoff + m * 2048 + k * 1024); } while (0)
; #define PG8_LDB(dst, b, h) do { _Pragma("unroll") for (int n = 0; n < 2; ++n) _Pragma("unroll") for (int k = 0; k < 2; ++k) dst[n][k] = *(const PG8_LAS bf16x8*)(lds + PG8_SB(b, h) + boff + n * 2048 + k * 1024); } while (0)
; #define PG8_MMA(ai, bj, At, Bt) do { __builtin_amdgcn_s_setprio(1); _Pragma("unroll") for (int m = 0; m < 4; ++m) _Pragma("unroll") for (int n = 0; n < 2; ++n) _Pragma("unroll") for (int k = 0; k < 2; ++k) \
;         acc[ai][bj][m][n] = __builtin_amdgcn_mfma_f32_16x16x32_bf16(Bt[n][k], At[m][k], acc[ai][bj][m][n], 0, 0, 0); __builtin_amdgcn_s_setprio(0); } while (0)
; #define PG8_WAIT_V(n) asm volatile("s_waitcnt vmcnt(" #n ")" ::: "memory")
; #define PG8_WAIT_L(n) asm volatile("s_waitcnt lgkmcnt(" #n ")" ::: "memory")
; #define PG8_BAR __builtin_amdgcn_s_barrier()
; #define PG8_SCHED __builtin_amdgcn_sched_barrier(0)
; template <class Epi, class Sched, bool ALIGN_EPI = false, bool SP2 = false>
; __device__ __forceinline__ void gemm_phase(PG8_LAS unsigned char* lds, const Gemm g, const Sched& S, const Epi& E, int wave_s) {
;     ...
;             PG8_LDB(B0, 1, 0); PG8_LDB(B1, 1, 1); PG8_SCHED; PG8_LDA(At, 1, 0); PG8_STAGE(PG8_SA(0, 1), a2 + hstepA, voffA);
;             PG8_WAIT_V(8); PG8_WAIT_L(0); PG8_BAR; PG8_MMA(0, 0, At, B0); PG8_MMA(0, 1, At, B1); PG8_BAR; PG8_SCHED;
	s_add_i32 s95, 0, 0x18000
	v_add_u32_e32 v149, s95, v147
	s_add_i32 s96, 0, 0x1c000
	ds_read_b128 v[142:145], v149
	ds_read_b128 v[150:153], v149 offset:1024
	ds_read_b128 v[154:157], v149 offset:2048
	ds_read_b128 v[158:161], v149 offset:3072
	v_add_u32_e32 v149, s96, v147
	ds_read_b128 v[162:165], v149
	ds_read_b128 v[166:169], v149 offset:1024
	ds_read_b128 v[170:173], v149 offset:2048
	ds_read_b128 v[174:177], v149 offset:3072
	s_add_u32 s40, s40, 0x80000
	s_addc_u32 s41, s41, 0
	s_mov_b32 m0, s37
	v_lshl_add_u64 v[218:219], s[40:41], 0, v[130:131]
	ds_read_b128 v[178:181], v148 offset:32768
	ds_read_b128 v[182:185], v148 offset:33792
	ds_read_b128 v[186:189], v148 offset:34816
	ds_read_b128 v[190:193], v148 offset:35840
	ds_read_b128 v[194:197], v148 offset:36864
	ds_read_b128 v[198:201], v148 offset:37888
	ds_read_b128 v[202:205], v148 offset:38912
	ds_read_b128 v[206:209], v148 offset:39936
	global_load_lds_dwordx4 v[218:219], off
	v_lshl_add_u64 v[218:219], s[40:41], 0, v[134:135]
	s_mov_b32 m0, s42
	s_nop 0
	global_load_lds_dwordx4 v[218:219], off
	s_waitcnt vmcnt(8)
	s_waitcnt lgkmcnt(0)
	s_barrier
	s_waitcnt lgkmcnt(0)
	v_mfma_f32_16x16x32_bf16 v[126:129], v[142:145], v[178:181], v[126:129]
	v_mfma_f32_16x16x32_bf16 v[122:125], v[154:157], v[178:181], v[122:125]
	v_mfma_f32_16x16x32_bf16 v[110:113], v[142:145], v[186:189], v[110:113]
	v_mfma_f32_16x16x32_bf16 v[106:109], v[154:157], v[186:189], v[106:109]
	v_mfma_f32_16x16x32_bf16 v[94:97], v[142:145], v[194:197], v[94:97]
	v_mfma_f32_16x16x32_bf16 v[90:93], v[154:157], v[194:197], v[90:93]
	v_mfma_f32_16x16x32_bf16 v[78:81], v[142:145], v[202:205], v[78:81]
	v_mfma_f32_16x16x32_bf16 v[74:77], v[154:157], v[202:205], v[74:77]
	v_mfma_f32_16x16x32_bf16 v[126:129], v[150:153], v[182:185], v[126:129]
	v_mfma_f32_16x16x32_bf16 v[122:125], v[158:161], v[182:185], v[122:125]
	v_mfma_f32_16x16x32_bf16 v[110:113], v[150:153], v[190:193], v[110:113]
	v_mfma_f32_16x16x32_bf16 v[106:109], v[158:161], v[190:193], v[106:109]
	v_mfma_f32_16x16x32_bf16 v[94:97], v[150:153], v[198:201], v[94:97]
	v_mfma_f32_16x16x32_bf16 v[90:93], v[158:161], v[198:201], v[90:93]
	v_mfma_f32_16x16x32_bf16 v[78:81], v[150:153], v[206:209], v[78:81]
	v_mfma_f32_16x16x32_bf16 v[74:77], v[158:161], v[206:209], v[74:77]
	v_mfma_f32_16x16x32_bf16 v[118:121], v[162:165], v[178:181], v[118:121]
	v_mfma_f32_16x16x32_bf16 v[114:117], v[170:173], v[178:181], v[114:117]
	v_mfma_f32_16x16x32_bf16 v[102:105], v[162:165], v[186:189], v[102:105]
	v_mfma_f32_16x16x32_bf16 v[98:101], v[170:173], v[186:189], v[98:101]
	v_mfma_f32_16x16x32_bf16 v[86:89], v[162:165], v[194:197], v[86:89]
	v_mfma_f32_16x16x32_bf16 v[82:85], v[170:173], v[194:197], v[82:85]
	v_mfma_f32_16x16x32_bf16 v[70:73], v[162:165], v[202:205], v[70:73]
	v_mfma_f32_16x16x32_bf16 v[66:69], v[170:173], v[202:205], v[66:69]
	v_mfma_f32_16x16x32_bf16 v[118:121], v[166:169], v[182:185], v[118:121]
	v_mfma_f32_16x16x32_bf16 v[114:117], v[174:177], v[182:185], v[114:117]
	v_mfma_f32_16x16x32_bf16 v[102:105], v[166:169], v[190:193], v[102:105]
	v_mfma_f32_16x16x32_bf16 v[98:101], v[174:177], v[190:193], v[98:101]
	v_mfma_f32_16x16x32_bf16 v[86:89], v[166:169], v[198:201], v[86:89]
	v_mfma_f32_16x16x32_bf16 v[82:85], v[174:177], v[198:201], v[82:85]
	v_mfma_f32_16x16x32_bf16 v[70:73], v[166:169], v[206:209], v[70:73]
	v_mfma_f32_16x16x32_bf16 v[66:69], v[174:177], v[206:209], v[66:69]
	s_barrier
; #define PG8_STAGE(bufoff, gbase, voff) do { _Pragma("unroll") for (int _i = 0; _i < 2; ++_i) \
;         __builtin_amdgcn_global_load_lds((const unsigned*)((const char*)(gbase) + (voff)[_i]), (PG8_LAS unsigned*)(lds + (bufoff) + ldsw + _i * 8192), 16, 0, 0); } while (0)
; #define PG8_LDA(dst, b, h) do { _Pragma("unroll") for (int m = 0; m < 4; ++m) _Pragma("unroll") for (int k = 0; k < 2; ++k) dst[m][k] = *(const PG8_LAS bf16x8*)(lds + PG8_SA(b, h) + aoff + m * 2048 + k * 1024); } while (0)
; #define PG8_MMA(ai, bj, At, Bt) do { __builtin_amdgcn_s_setprio(1); _Pragma("unroll") for (int m = 0; m < 4; ++m) _Pragma("unroll") for (int n = 0; n < 2; ++n) _Pragma("unroll") for (int k = 0; k < 2; ++k) \
;         acc[ai][bj][m][n] = __builtin_amdgcn_mfma_f32_16x16x32_bf16(Bt[n][k], At[m][k], acc[ai][bj][m][n], 0, 0, 0); __builtin_amdgcn_s_setprio(0); } while (0)
; #define PG8_WAIT_V(n) asm volatile("s_waitcnt vmcnt(" #n ")" ::: "memory")
; #define PG8_WAIT_L(n) asm volatile("s_waitcnt lgkmcnt(" #n ")" ::: "memory")
; #define PG8_BAR __builtin_amdgcn_s_barrier()
; #define PG8_SCHED __builtin_amdgcn_sched_barrier(0)
; template <class Epi, class Sched, bool ALIGN_EPI = false, bool SP2 = false>
; __device__ __forceinline__ void gemm_phase(PG8_LAS unsigned char* lds, const Gemm g, const Sched& S, const Epi& E, int wave_s) {
;     ...
;             PG8_LDA(At, 1, 1); PG8_STAGE(PG8_SB(1, 0), b3, voffB); PG8_STAGE(PG8_SB(1, 1), b3 + hstepB, voffB); PG8_STAGE(PG8_SA(1, 0), a3, voffA);
;             PG8_WAIT_V(8); PG8_WAIT_L(0); PG8_BAR; PG8_MMA(1, 0, At, B0); PG8_MMA(1, 1, At, B1); PG8_BAR; PG8_SCHED;
;     ...
;         if constexpr (ALIGN_EPI) { if (wr == 0) PG8_BAR; }
	s_add_i32 s40, s95, s34
	v_lshl_add_u64 v[210:211], v[210:211], 0, s[60:61]
	s_mov_b32 m0, s40
	ds_read_b128 v[178:181], v148 offset:49152
	ds_read_b128 v[182:185], v148 offset:50176
	ds_read_b128 v[186:189], v148 offset:51200
	ds_read_b128 v[190:193], v148 offset:52224
	ds_read_b128 v[194:197], v148 offset:53248
	ds_read_b128 v[198:201], v148 offset:54272
	ds_read_b128 v[202:205], v148 offset:55296
	ds_read_b128 v[206:209], v148 offset:56320
	global_load_lds_dwordx4 v[210:211], off
	s_add_i32 m0, s40, 0x2000
	s_add_u32 s30, s30, 0x80080
	v_lshl_add_u64 v[210:211], v[212:213], 0, s[60:61]
	s_addc_u32 s31, s31, 0
	s_add_i32 s40, s96, s34
	global_load_lds_dwordx4 v[210:211], off
	v_lshl_add_u64 v[210:211], s[30:31], 0, v[132:133]
	s_mov_b32 m0, s40
	s_nop 0
	global_load_lds_dwordx4 v[210:211], off
	v_lshl_add_u64 v[210:211], s[30:31], 0, v[136:137]
	s_add_i32 m0, s40, 0x2000
	s_nop 0
	global_load_lds_dwordx4 v[210:211], off
	v_lshl_add_u64 v[210:211], v[214:215], 0, s[60:61]
	s_mov_b32 m0, s45
	s_nop 0
	global_load_lds_dwordx4 v[210:211], off
	v_lshl_add_u64 v[210:211], v[216:217], 0, s[60:61]
	s_mov_b32 m0, s46
	s_nop 0
	global_load_lds_dwordx4 v[210:211], off
	s_waitcnt vmcnt(8)
	s_waitcnt lgkmcnt(0)
	s_barrier
	s_waitcnt lgkmcnt(0)
	v_mfma_f32_16x16x32_bf16 v[62:65], v[142:145], v[178:181], v[62:65]
	v_mfma_f32_16x16x32_bf16 v[58:61], v[154:157], v[178:181], v[58:61]
	v_mfma_f32_16x16x32_bf16 v[46:49], v[142:145], v[186:189], v[46:49]
	v_mfma_f32_16x16x32_bf16 v[42:45], v[154:157], v[186:189], v[42:45]
	v_mfma_f32_16x16x32_bf16 v[30:33], v[142:145], v[194:197], v[30:33]
	v_mfma_f32_16x16x32_bf16 v[26:29], v[154:157], v[194:197], v[26:29]
	v_mfma_f32_16x16x32_bf16 v[14:17], v[142:145], v[202:205], v[14:17]
	v_mfma_f32_16x16x32_bf16 v[10:13], v[154:157], v[202:205], v[10:13]
	v_mfma_f32_16x16x32_bf16 v[62:65], v[150:153], v[182:185], v[62:65]
	v_mfma_f32_16x16x32_bf16 v[58:61], v[158:161], v[182:185], v[58:61]
	v_mfma_f32_16x16x32_bf16 v[46:49], v[150:153], v[190:193], v[46:49]
	v_mfma_f32_16x16x32_bf16 v[42:45], v[158:161], v[190:193], v[42:45]
	v_mfma_f32_16x16x32_bf16 v[30:33], v[150:153], v[198:201], v[30:33]
	v_mfma_f32_16x16x32_bf16 v[26:29], v[158:161], v[198:201], v[26:29]
	v_mfma_f32_16x16x32_bf16 v[14:17], v[150:153], v[206:209], v[14:17]
	v_mfma_f32_16x16x32_bf16 v[10:13], v[158:161], v[206:209], v[10:13]
	v_mfma_f32_16x16x32_bf16 v[54:57], v[162:165], v[178:181], v[54:57]
	v_mfma_f32_16x16x32_bf16 v[50:53], v[170:173], v[178:181], v[50:53]
	v_mfma_f32_16x16x32_bf16 v[38:41], v[162:165], v[186:189], v[38:41]
	v_mfma_f32_16x16x32_bf16 v[34:37], v[170:173], v[186:189], v[34:37]
	v_mfma_f32_16x16x32_bf16 v[22:25], v[162:165], v[194:197], v[22:25]
	v_mfma_f32_16x16x32_bf16 v[18:21], v[170:173], v[194:197], v[18:21]
	v_mfma_f32_16x16x32_bf16 v[6:9], v[162:165], v[202:205], v[6:9]
	v_mfma_f32_16x16x32_bf16 v[2:5], v[170:173], v[202:205], v[2:5]
	v_mfma_f32_16x16x32_bf16 v[54:57], v[166:169], v[182:185], v[54:57]
	v_mfma_f32_16x16x32_bf16 v[50:53], v[174:177], v[182:185], v[50:53]
	v_mfma_f32_16x16x32_bf16 v[38:41], v[166:169], v[190:193], v[38:41]
	v_mfma_f32_16x16x32_bf16 v[34:37], v[174:177], v[190:193], v[34:37]
	v_mfma_f32_16x16x32_bf16 v[22:25], v[166:169], v[198:201], v[22:25]
	v_mfma_f32_16x16x32_bf16 v[18:21], v[174:177], v[198:201], v[18:21]
	v_mfma_f32_16x16x32_bf16 v[6:9], v[166:169], v[206:209], v[6:9]
	v_mfma_f32_16x16x32_bf16 v[2:5], v[174:177], v[206:209], v[2:5]
	s_barrier
	s_add_i32 s94, s94, 2
	s_add_u32 s4, s4, 0x100
	s_addc_u32 s5, s5, 0
	s_add_u32 s15, s15, 0x100
	s_addc_u32 s21, s21, 0
	s_cmp_gt_u32 s94, 29
	s_cbranch_scc0 .LBB0_412
	s_and_b64 vcc, exec, s[12:13]
	s_cbranch_vccz .LBB0_415
	s_barrier

; #define PG8_STAGE(bufoff, gbase, voff) do { _Pragma("unroll") for (int _i = 0; _i < 2; ++_i) \
;         __builtin_amdgcn_global_load_lds((const unsigned*)((const char*)(gbase) + (voff)[_i]), (PG8_LAS unsigned*)(lds + (bufoff) + ldsw + _i * 8192), 16, 0, 0); } while (0)
; #define PG8_LDA(dst, b, h) do { _Pragma("unroll") for (int m = 0; m < 4; ++m) _Pragma("unroll") for (int k = 0; k < 2; ++k) dst[m][k] = *(const PG8_LAS bf16x8*)(lds + PG8_SA(b, h) + aoff + m * 2048 + k * 1024); } while (0)
; #define PG8_LDB(dst, b, h) do { _Pragma("unroll") for (int n = 0; n < 2; ++n) _Pragma("unroll") for (int k = 0; k < 2; ++k) dst[n][k] = *(const PG8_LAS bf16x8*)(lds + PG8_SB(b, h) + boff + n * 2048 + k * 1024); } while (0)
; #define PG8_WAIT_V(n) asm volatile("s_waitcnt vmcnt(" #n ")" ::: "memory")
; #define PG8_WAIT_L(n) asm volatile("s_waitcnt lgkmcnt(" #n ")" ::: "memory")
; #define PG8_BAR __builtin_amdgcn_s_barrier()
; template <class Epi, class Sched, bool ALIGN_EPI = false, bool SP2 = false>
; __device__ __forceinline__ void gemm_phase(PG8_LAS unsigned char* lds, const Gemm g, const Sched& S, const Epi& E, int wave_s) {
;     ...
;         const bool has_next = S.next(ui + 1, nxt);
;         const char* nA = has_next ? (const char*)g.A + (size_t)nxt.pm * tstepA + (size_t)(nxt.pn / g.npg) * (size_t)(K * 2) : cA; const char* nB = has_next ? (const char*)g.Bt + (size_t)nxt.pn * tstepB : cB;
;         for (int t = 0; t < nt; t += 2) {
;             const bool last = (t == nt - 2);
;             const char* a1 = cA + (size_t)(t + 1) * kstep;
;             const char* a2 = last ? nA : cA + (size_t)(t + 2) * kstep; const char* b2 = last ? nB : cB + (size_t)(t + 2) * kstep;
;             const char* a3 = a2 + kstep; const char* b3 = b2 + kstep;
;             if (last && has_next) S.a_ready(nxt);
;             if constexpr (SP2) {
;             PG8_LDB(B0, 0, 0); PG8_LDB(B1, 0, 1); PG8_SCHED; PG8_LDA(At, 0, 0); PG8_STAGE(PG8_SA(1, 1), a1 + hstepA, voffA);
;             PG8_WAIT_V(8); PG8_WAIT_L(0); PG8_BAR; PG8_MMA(0, 0, At, B0); PG8_MMA(0, 1, At, B1); PG8_BAR; PG8_SCHED;
;             PG8_LDA(At, 0, 1); PG8_STAGE(PG8_SB(0, 0), b2, voffB); PG8_STAGE(PG8_SB(0, 1), b2 + hstepB, voffB); PG8_STAGE(PG8_SA(0, 0), a2, voffA);
;             PG8_WAIT_V(8); PG8_WAIT_L(0); PG8_BAR; PG8_MMA(1, 0, At, B0); PG8_MMA(1, 1, At, B1); PG8_BAR; PG8_SCHED;
.LBB0_601:
	s_ashr_i32 s21, s20, 31
	s_lshl_b64 s[2:3], s[20:21], 20
	s_add_u32 s88, s22, s2
	s_addc_u32 s89, s23, s3
	s_and_b64 s[2:3], s[4:5], exec
	s_cselect_b32 s2, s89, s31
	s_cselect_b32 s3, s88, s30
	s_add_u32 s4, s40, 0x80080
	s_addc_u32 s5, s41, 0
	s_add_u32 s21, s30, 0x100
	s_addc_u32 s27, s31, 0
	s_mov_b32 s81, -2
	s_add_u32 s30, s4, 0xfff80080
	s_addc_u32 s31, s5, -1
	s_add_i32 s84, 0, 0x10000
	s_cmp_eq_u32 s81, 28
	s_cselect_b32 s41, s29, s31
	s_cselect_b32 s40, s28, s30
	s_cselect_b32 s31, s2, s27
	s_cselect_b32 s30, s3, s21
	s_add_i32 s90, 0, 0x14000
	v_add_u32_e32 v134, s84, v207
	v_add_u32_e32 v158, s90, v207
	ds_read_b128 v[118:121], v134
	ds_read_b128 v[126:129], v134 offset:1024
	ds_read_b128 v[130:133], v134 offset:2048
	ds_read_b128 v[134:137], v134 offset:3072
	ds_read_b128 v[138:141], v158
	ds_read_b128 v[142:145], v158 offset:1024
	ds_read_b128 v[154:157], v158 offset:2048
	ds_read_b128 v[158:161], v158 offset:3072
	v_lshl_add_u64 v[210:211], s[4:5], 0, v[198:199]
	s_add_i32 m0, s35, 0xc000
	ds_read_b128 v[162:165], v208
	ds_read_b128 v[166:169], v208 offset:1024
	ds_read_b128 v[170:173], v208 offset:2048
	ds_read_b128 v[174:177], v208 offset:3072
	ds_read_b128 v[178:181], v208 offset:4096
	ds_read_b128 v[182:185], v208 offset:5120
	ds_read_b128 v[186:189], v208 offset:6144
	ds_read_b128 v[202:205], v208 offset:7168
	global_load_lds_dwordx4 v[210:211], off
	v_lshl_add_u64 v[210:211], s[4:5], 0, v[200:201]
	s_add_i32 m0, s35, 0xe000
	s_nop 0
	global_load_lds_dwordx4 v[210:211], off
	s_waitcnt vmcnt(8)
	s_waitcnt lgkmcnt(0)
	s_barrier
	s_waitcnt lgkmcnt(0)
	v_mfma_f32_16x16x32_bf16 v[150:153], v[118:121], v[162:165], 0
	v_mfma_f32_16x16x32_bf16 v[146:149], v[130:133], v[162:165], 0
	v_mfma_f32_16x16x32_bf16 v[110:113], v[118:121], v[170:173], 0
	v_mfma_f32_16x16x32_bf16 v[106:109], v[130:133], v[170:173], 0
	v_mfma_f32_16x16x32_bf16 v[94:97], v[118:121], v[178:181], 0
	v_mfma_f32_16x16x32_bf16 v[90:93], v[130:133], v[178:181], 0
	v_mfma_f32_16x16x32_bf16 v[78:81], v[118:121], v[186:189], 0
	v_mfma_f32_16x16x32_bf16 v[74:77], v[130:133], v[186:189], 0
	v_mfma_f32_16x16x32_bf16 v[150:153], v[126:129], v[166:169], v[150:153]
	v_mfma_f32_16x16x32_bf16 v[146:149], v[134:137], v[166:169], v[146:149]
	v_mfma_f32_16x16x32_bf16 v[110:113], v[126:129], v[174:177], v[110:113]
	v_mfma_f32_16x16x32_bf16 v[106:109], v[134:137], v[174:177], v[106:109]
	v_mfma_f32_16x16x32_bf16 v[94:97], v[126:129], v[182:185], v[94:97]
	v_mfma_f32_16x16x32_bf16 v[90:93], v[134:137], v[182:185], v[90:93]
	v_mfma_f32_16x16x32_bf16 v[78:81], v[126:129], v[202:205], v[78:81]
	v_mfma_f32_16x16x32_bf16 v[74:77], v[134:137], v[202:205], v[74:77]
	v_mfma_f32_16x16x32_bf16 v[122:125], v[138:141], v[162:165], 0
	v_mfma_f32_16x16x32_bf16 v[114:117], v[154:157], v[162:165], 0
	v_mfma_f32_16x16x32_bf16 v[102:105], v[138:141], v[170:173], 0
	v_mfma_f32_16x16x32_bf16 v[98:101], v[154:157], v[170:173], 0
	v_mfma_f32_16x16x32_bf16 v[86:89], v[138:141], v[178:181], 0
	v_mfma_f32_16x16x32_bf16 v[82:85], v[154:157], v[178:181], 0
	v_mfma_f32_16x16x32_bf16 v[70:73], v[138:141], v[186:189], 0
	v_mfma_f32_16x16x32_bf16 v[66:69], v[154:157], v[186:189], 0
	v_mfma_f32_16x16x32_bf16 v[122:125], v[142:145], v[166:169], v[122:125]
	v_mfma_f32_16x16x32_bf16 v[114:117], v[158:161], v[166:169], v[114:117]
	v_mfma_f32_16x16x32_bf16 v[102:105], v[142:145], v[174:177], v[102:105]
	v_mfma_f32_16x16x32_bf16 v[98:101], v[158:161], v[174:177], v[98:101]
	v_mfma_f32_16x16x32_bf16 v[86:89], v[142:145], v[182:185], v[86:89]
	v_mfma_f32_16x16x32_bf16 v[82:85], v[158:161], v[182:185], v[82:85]
	v_mfma_f32_16x16x32_bf16 v[70:73], v[142:145], v[202:205], v[70:73]
	v_mfma_f32_16x16x32_bf16 v[66:69], v[158:161], v[202:205], v[66:69]
	s_barrier
	s_add_i32 s84, s84, s34
	v_lshl_add_u64 v[210:211], s[30:31], 0, v[194:195]
	s_mov_b32 m0, s84
	ds_read_b128 v[162:165], v208 offset:16384
	ds_read_b128 v[166:169], v208 offset:17408
	ds_read_b128 v[170:173], v208 offset:18432
	ds_read_b128 v[174:177], v208 offset:19456
	ds_read_b128 v[178:181], v208 offset:20480
	ds_read_b128 v[182:185], v208 offset:21504
	ds_read_b128 v[186:189], v208 offset:22528
	ds_read_b128 v[202:205], v208 offset:23552
	global_load_lds_dwordx4 v[210:211], off
	s_add_i32 m0, s84, 0x2000
	s_add_u32 s84, s30, 0x80000
	v_lshl_add_u64 v[212:213], s[30:31], 0, v[190:191]
	s_addc_u32 s85, s31, 0
	s_add_i32 s90, s90, s34
	global_load_lds_dwordx4 v[212:213], off
	v_lshl_add_u64 v[214:215], s[84:85], 0, v[194:195]
	s_mov_b32 m0, s90
	v_lshl_add_u64 v[216:217], s[40:41], 0, v[192:193]
	global_load_lds_dwordx4 v[214:215], off
	v_lshl_add_u64 v[214:215], s[84:85], 0, v[190:191]
	s_add_i32 m0, s90, 0x2000
	s_nop 0
	global_load_lds_dwordx4 v[214:215], off
	v_lshl_add_u64 v[214:215], s[40:41], 0, v[196:197]
	s_mov_b32 m0, s35
	s_nop 0
	global_load_lds_dwordx4 v[214:215], off
	s_mov_b32 m0, s36
	s_nop 0
	global_load_lds_dwordx4 v[216:217], off
	s_waitcnt vmcnt(8)
	s_waitcnt lgkmcnt(0)
	s_barrier
; #define PG8_STAGE(bufoff, gbase, voff) do { _Pragma("unroll") for (int _i = 0; _i < 2; ++_i) \
;         __builtin_amdgcn_global_load_lds((const unsigned*)((const char*)(gbase) + (voff)[_i]), (PG8_LAS unsigned*)(lds + (bufoff) + ldsw + _i * 8192), 16, 0, 0); } while (0)
; #define PG8_LDA(dst, b, h) do { _Pragma("unroll") for (int m = 0; m < 4; ++m) _Pragma("unroll") for (int k = 0; k < 2; ++k) dst[m][k] = *(const PG8_LAS bf16x8*)(lds + PG8_SA(b, h) + aoff + m * 2048 + k * 1024); } while (0)
; #define PG8_LDB(dst, b, h) do { _Pragma("unroll") for (int n = 0; n < 2; ++n) _Pragma("unroll") for (int k = 0; k < 2; ++k) dst[n][k] = *(const PG8_LAS bf16x8*)(lds + PG8_SB(b, h) + boff + n * 2048 + k * 1024); } while (0)
; #define PG8_MMA(ai, bj, At, Bt) do { __builtin_amdgcn_s_setprio(1); _Pragma("unroll") for (int m = 0; m < 4; ++m) _Pragma("unroll") for (int n = 0; n < 2; ++n) _Pragma("unroll") for (int k = 0; k < 2; ++k) \
;         acc[ai][bj][m][n] = __builtin_amdgcn_mfma_f32_16x16x32_bf16(Bt[n][k], At[m][k], acc[ai][bj][m][n], 0, 0, 0); __builtin_amdgcn_s_setprio(0); } while (0)
; #define PG8_WAIT_V(n) asm volatile("s_waitcnt vmcnt(" #n ")" ::: "memory")
; #define PG8_WAIT_L(n) asm volatile("s_waitcnt lgkmcnt(" #n ")" ::: "memory")
; #define PG8_BAR __builtin_amdgcn_s_barrier()
; #define PG8_SCHED __builtin_amdgcn_sched_barrier(0)
; template <class Epi, class Sched, bool ALIGN_EPI = false, bool SP2 = false>
; __device__ __forceinline__ void gemm_phase(PG8_LAS unsigned char* lds, const Gemm g, const Sched& S, const Epi& E, int wave_s) {
;     ...
;             PG8_WAIT_V(8); PG8_WAIT_L(0); PG8_BAR; PG8_MMA(1, 0, At, B0); PG8_MMA(1, 1, At, B1); PG8_BAR; PG8_SCHED;
;             PG8_LDB(B0, 1, 0); PG8_LDB(B1, 1, 1); PG8_SCHED; PG8_LDA(At, 1, 0); PG8_STAGE(PG8_SA(0, 1), a2 + hstepA, voffA);
;             PG8_WAIT_V(8); PG8_WAIT_L(0); PG8_BAR; PG8_MMA(0, 0, At, B0); PG8_MMA(0, 1, At, B1); PG8_BAR; PG8_SCHED;
	s_waitcnt lgkmcnt(0)
	v_mfma_f32_16x16x32_bf16 v[62:65], v[118:121], v[162:165], 0
	v_mfma_f32_16x16x32_bf16 v[58:61], v[130:133], v[162:165], 0
	v_mfma_f32_16x16x32_bf16 v[46:49], v[118:121], v[170:173], 0
	v_mfma_f32_16x16x32_bf16 v[42:45], v[130:133], v[170:173], 0
	v_mfma_f32_16x16x32_bf16 v[30:33], v[118:121], v[178:181], 0
	v_mfma_f32_16x16x32_bf16 v[26:29], v[130:133], v[178:181], 0
	v_mfma_f32_16x16x32_bf16 v[14:17], v[118:121], v[186:189], 0
	v_mfma_f32_16x16x32_bf16 v[10:13], v[130:133], v[186:189], 0
	v_mfma_f32_16x16x32_bf16 v[62:65], v[126:129], v[166:169], v[62:65]
	v_mfma_f32_16x16x32_bf16 v[58:61], v[134:137], v[166:169], v[58:61]
	v_mfma_f32_16x16x32_bf16 v[46:49], v[126:129], v[174:177], v[46:49]
	v_mfma_f32_16x16x32_bf16 v[42:45], v[134:137], v[174:177], v[42:45]
	v_mfma_f32_16x16x32_bf16 v[30:33], v[126:129], v[182:185], v[30:33]
	v_mfma_f32_16x16x32_bf16 v[26:29], v[134:137], v[182:185], v[26:29]
	v_mfma_f32_16x16x32_bf16 v[14:17], v[126:129], v[202:205], v[14:17]
	v_mfma_f32_16x16x32_bf16 v[10:13], v[134:137], v[202:205], v[10:13]
	v_mfma_f32_16x16x32_bf16 v[54:57], v[138:141], v[162:165], 0
	v_mfma_f32_16x16x32_bf16 v[50:53], v[154:157], v[162:165], 0
	v_mfma_f32_16x16x32_bf16 v[38:41], v[138:141], v[170:173], 0
	v_mfma_f32_16x16x32_bf16 v[34:37], v[154:157], v[170:173], 0
	v_mfma_f32_16x16x32_bf16 v[22:25], v[138:141], v[178:181], 0
	v_mfma_f32_16x16x32_bf16 v[18:21], v[154:157], v[178:181], 0
	v_mfma_f32_16x16x32_bf16 v[6:9], v[138:141], v[186:189], 0
	v_mfma_f32_16x16x32_bf16 v[2:5], v[154:157], v[186:189], 0
	v_mfma_f32_16x16x32_bf16 v[54:57], v[142:145], v[166:169], v[54:57]
	v_mfma_f32_16x16x32_bf16 v[50:53], v[158:161], v[166:169], v[50:53]
	v_mfma_f32_16x16x32_bf16 v[38:41], v[142:145], v[174:177], v[38:41]
	v_mfma_f32_16x16x32_bf16 v[34:37], v[158:161], v[174:177], v[34:37]
	v_mfma_f32_16x16x32_bf16 v[22:25], v[142:145], v[182:185], v[22:25]
	v_mfma_f32_16x16x32_bf16 v[18:21], v[158:161], v[182:185], v[18:21]
	v_mfma_f32_16x16x32_bf16 v[6:9], v[142:145], v[202:205], v[6:9]
	v_mfma_f32_16x16x32_bf16 v[2:5], v[158:161], v[202:205], v[2:5]
	s_barrier
	s_add_i32 s84, 0, 0x18000
	s_add_i32 s85, 0, 0x1c000
	v_add_u32_e32 v134, s84, v207
	v_add_u32_e32 v158, s85, v207
	ds_read_b128 v[118:121], v134
	ds_read_b128 v[126:129], v134 offset:1024
	ds_read_b128 v[130:133], v134 offset:2048
	ds_read_b128 v[134:137], v134 offset:3072
	ds_read_b128 v[138:141], v158
	ds_read_b128 v[142:145], v158 offset:1024
	ds_read_b128 v[154:157], v158 offset:2048
	ds_read_b128 v[158:161], v158 offset:3072
	s_add_u32 s40, s40, 0x80000
	s_addc_u32 s41, s41, 0
	s_mov_b32 m0, s37
	v_lshl_add_u64 v[218:219], s[40:41], 0, v[196:197]
	ds_read_b128 v[162:165], v208 offset:32768
	ds_read_b128 v[166:169], v208 offset:33792
	ds_read_b128 v[170:173], v208 offset:34816
	ds_read_b128 v[174:177], v208 offset:35840
	ds_read_b128 v[178:181], v208 offset:36864
	ds_read_b128 v[182:185], v208 offset:37888
	ds_read_b128 v[186:189], v208 offset:38912
	ds_read_b128 v[202:205], v208 offset:39936
	global_load_lds_dwordx4 v[218:219], off
	v_lshl_add_u64 v[218:219], s[40:41], 0, v[192:193]
	s_mov_b32 m0, s42
	s_nop 0
	global_load_lds_dwordx4 v[218:219], off
	s_waitcnt vmcnt(8)
	s_waitcnt lgkmcnt(0)
	s_barrier
	s_waitcnt lgkmcnt(0)
	v_mfma_f32_16x16x32_bf16 v[150:153], v[118:121], v[162:165], v[150:153]
	v_mfma_f32_16x16x32_bf16 v[146:149], v[130:133], v[162:165], v[146:149]
	v_mfma_f32_16x16x32_bf16 v[110:113], v[118:121], v[170:173], v[110:113]
	v_mfma_f32_16x16x32_bf16 v[106:109], v[130:133], v[170:173], v[106:109]
	v_mfma_f32_16x16x32_bf16 v[94:97], v[118:121], v[178:181], v[94:97]
	v_mfma_f32_16x16x32_bf16 v[90:93], v[130:133], v[178:181], v[90:93]
	v_mfma_f32_16x16x32_bf16 v[78:81], v[118:121], v[186:189], v[78:81]
	v_mfma_f32_16x16x32_bf16 v[74:77], v[130:133], v[186:189], v[74:77]
	v_mfma_f32_16x16x32_bf16 v[150:153], v[126:129], v[166:169], v[150:153]
	v_mfma_f32_16x16x32_bf16 v[146:149], v[134:137], v[166:169], v[146:149]
	v_mfma_f32_16x16x32_bf16 v[110:113], v[126:129], v[174:177], v[110:113]
	v_mfma_f32_16x16x32_bf16 v[106:109], v[134:137], v[174:177], v[106:109]
	v_mfma_f32_16x16x32_bf16 v[94:97], v[126:129], v[182:185], v[94:97]
	v_mfma_f32_16x16x32_bf16 v[90:93], v[134:137], v[182:185], v[90:93]
	v_mfma_f32_16x16x32_bf16 v[78:81], v[126:129], v[202:205], v[78:81]
	v_mfma_f32_16x16x32_bf16 v[74:77], v[134:137], v[202:205], v[74:77]
	v_mfma_f32_16x16x32_bf16 v[122:125], v[138:141], v[162:165], v[122:125]
	v_mfma_f32_16x16x32_bf16 v[114:117], v[154:157], v[162:165], v[114:117]
	v_mfma_f32_16x16x32_bf16 v[102:105], v[138:141], v[170:173], v[102:105]
	v_mfma_f32_16x16x32_bf16 v[98:101], v[154:157], v[170:173], v[98:101]
	v_mfma_f32_16x16x32_bf16 v[86:89], v[138:141], v[178:181], v[86:89]
	v_mfma_f32_16x16x32_bf16 v[82:85], v[154:157], v[178:181], v[82:85]
	v_mfma_f32_16x16x32_bf16 v[70:73], v[138:141], v[186:189], v[70:73]
	v_mfma_f32_16x16x32_bf16 v[66:69], v[154:157], v[186:189], v[66:69]
	v_mfma_f32_16x16x32_bf16 v[122:125], v[142:145], v[166:169], v[122:125]
	v_mfma_f32_16x16x32_bf16 v[114:117], v[158:161], v[166:169], v[114:117]
	v_mfma_f32_16x16x32_bf16 v[102:105], v[142:145], v[174:177], v[102:105]
	v_mfma_f32_16x16x32_bf16 v[98:101], v[158:161], v[174:177], v[98:101]
	v_mfma_f32_16x16x32_bf16 v[86:89], v[142:145], v[182:185], v[86:89]
	v_mfma_f32_16x16x32_bf16 v[82:85], v[158:161], v[182:185], v[82:85]
	v_mfma_f32_16x16x32_bf16 v[70:73], v[142:145], v[202:205], v[70:73]
	v_mfma_f32_16x16x32_bf16 v[66:69], v[158:161], v[202:205], v[66:69]
	s_barrier
; #define PG8_STAGE(bufoff, gbase, voff) do { _Pragma("unroll") for (int _i = 0; _i < 2; ++_i) \
;         __builtin_amdgcn_global_load_lds((const unsigned*)((const char*)(gbase) + (voff)[_i]), (PG8_LAS unsigned*)(lds + (bufoff) + ldsw + _i * 8192), 16, 0, 0); } while (0)
; #define PG8_LDA(dst, b, h) do { _Pragma("unroll") for (int m = 0; m < 4; ++m) _Pragma("unroll") for (int k = 0; k < 2; ++k) dst[m][k] = *(const PG8_LAS bf16x8*)(lds + PG8_SA(b, h) + aoff + m * 2048 + k * 1024); } while (0)
; #define PG8_LDB(dst, b, h) do { _Pragma("unroll") for (int n = 0; n < 2; ++n) _Pragma("unroll") for (int k = 0; k < 2; ++k) dst[n][k] = *(const PG8_LAS bf16x8*)(lds + PG8_SB(b, h) + boff + n * 2048 + k * 1024); } while (0)
; #define PG8_MMA(ai, bj, At, Bt) do { __builtin_amdgcn_s_setprio(1); _Pragma("unroll") for (int m = 0; m < 4; ++m) _Pragma("unroll") for (int n = 0; n < 2; ++n) _Pragma("unroll") for (int k = 0; k < 2; ++k) \
;         acc[ai][bj][m][n] = __builtin_amdgcn_mfma_f32_16x16x32_bf16(Bt[n][k], At[m][k], acc[ai][bj][m][n], 0, 0, 0); __builtin_amdgcn_s_setprio(0); } while (0)
; #define PG8_WAIT_V(n) asm volatile("s_waitcnt vmcnt(" #n ")" ::: "memory")
; #define PG8_BAR __builtin_amdgcn_s_barrier()
; template <class Epi, class Sched, bool ALIGN_EPI = false, bool SP2 = false>
; __device__ __forceinline__ void gemm_phase(PG8_LAS unsigned char* lds, const Gemm g, const Sched& S, const Epi& E, int wave_s) {
;     ...
;         for (int t = 0; t < nt; t += 2) {
;             const bool last = (t == nt - 2);
;             const char* a1 = cA + (size_t)(t + 1) * kstep;
;             const char* a2 = last ? nA : cA + (size_t)(t + 2) * kstep; const char* b2 = last ? nB : cB + (size_t)(t + 2) * kstep;
;             const char* a3 = a2 + kstep; const char* b3 = b2 + kstep;
;             if (last && has_next) S.a_ready(nxt);
;             if constexpr (SP2) {
;             PG8_LDB(B0, 0, 0); PG8_LDB(B1, 0, 1); PG8_SCHED; PG8_LDA(At, 0, 0); PG8_STAGE(PG8_SA(1, 1), a1 + hstepA, voffA);
;             PG8_WAIT_V(8); PG8_WAIT_L(0); PG8_BAR; PG8_MMA(0, 0, At, B0); PG8_MMA(0, 1, At, B1); PG8_BAR; PG8_SCHED;
;     ...
;             PG8_LDA(At, 1, 1); PG8_STAGE(PG8_SB(1, 0), b3, voffB); PG8_STAGE(PG8_SB(1, 1), b3 + hstepB, voffB); PG8_STAGE(PG8_SA(1, 0), a3, voffA);
;             PG8_WAIT_V(8); PG8_WAIT_L(0); PG8_BAR; PG8_MMA(1, 0, At, B0); PG8_MMA(1, 1, At, B1); PG8_BAR; PG8_SCHED;
	s_add_i32 s40, s84, s34
	v_lshl_add_u64 v[210:211], v[210:211], 0, s[60:61]
	s_mov_b32 m0, s40
	ds_read_b128 v[162:165], v208 offset:49152
	ds_read_b128 v[166:169], v208 offset:50176
	ds_read_b128 v[170:173], v208 offset:51200
	ds_read_b128 v[174:177], v208 offset:52224
	ds_read_b128 v[178:181], v208 offset:53248
	ds_read_b128 v[182:185], v208 offset:54272
	ds_read_b128 v[186:189], v208 offset:55296
	ds_read_b128 v[202:205], v208 offset:56320
	global_load_lds_dwordx4 v[210:211], off
	s_add_i32 m0, s40, 0x2000
	s_add_u32 s30, s30, 0x80080
	v_lshl_add_u64 v[210:211], v[212:213], 0, s[60:61]
	s_addc_u32 s31, s31, 0
	s_add_i32 s40, s85, s34
	global_load_lds_dwordx4 v[210:211], off
	v_lshl_add_u64 v[210:211], s[30:31], 0, v[194:195]
	s_mov_b32 m0, s40
	s_nop 0
	global_load_lds_dwordx4 v[210:211], off
	v_lshl_add_u64 v[210:211], s[30:31], 0, v[190:191]
	s_add_i32 m0, s40, 0x2000
	s_nop 0
	global_load_lds_dwordx4 v[210:211], off
	v_lshl_add_u64 v[210:211], v[214:215], 0, s[60:61]
	s_mov_b32 m0, s46
	s_nop 0
	global_load_lds_dwordx4 v[210:211], off
	v_lshl_add_u64 v[210:211], v[216:217], 0, s[60:61]
	s_mov_b32 m0, s47
	s_nop 0
	global_load_lds_dwordx4 v[210:211], off
	s_waitcnt vmcnt(8)
	s_waitcnt lgkmcnt(0)
	s_barrier
	s_waitcnt lgkmcnt(0)
	v_mfma_f32_16x16x32_bf16 v[62:65], v[118:121], v[162:165], v[62:65]
	v_mfma_f32_16x16x32_bf16 v[58:61], v[130:133], v[162:165], v[58:61]
	v_mfma_f32_16x16x32_bf16 v[46:49], v[118:121], v[170:173], v[46:49]
	v_mfma_f32_16x16x32_bf16 v[42:45], v[130:133], v[170:173], v[42:45]
	v_mfma_f32_16x16x32_bf16 v[30:33], v[118:121], v[178:181], v[30:33]
	v_mfma_f32_16x16x32_bf16 v[26:29], v[130:133], v[178:181], v[26:29]
	v_mfma_f32_16x16x32_bf16 v[14:17], v[118:121], v[186:189], v[14:17]
	v_mfma_f32_16x16x32_bf16 v[10:13], v[130:133], v[186:189], v[10:13]
	v_mfma_f32_16x16x32_bf16 v[62:65], v[126:129], v[166:169], v[62:65]
	v_mfma_f32_16x16x32_bf16 v[58:61], v[134:137], v[166:169], v[58:61]
	v_mfma_f32_16x16x32_bf16 v[46:49], v[126:129], v[174:177], v[46:49]
	v_mfma_f32_16x16x32_bf16 v[42:45], v[134:137], v[174:177], v[42:45]
	v_mfma_f32_16x16x32_bf16 v[30:33], v[126:129], v[182:185], v[30:33]
	v_mfma_f32_16x16x32_bf16 v[26:29], v[134:137], v[182:185], v[26:29]
	v_mfma_f32_16x16x32_bf16 v[14:17], v[126:129], v[202:205], v[14:17]
	v_mfma_f32_16x16x32_bf16 v[10:13], v[134:137], v[202:205], v[10:13]
	v_mfma_f32_16x16x32_bf16 v[54:57], v[138:141], v[162:165], v[54:57]
	v_mfma_f32_16x16x32_bf16 v[50:53], v[154:157], v[162:165], v[50:53]
	v_mfma_f32_16x16x32_bf16 v[38:41], v[138:141], v[170:173], v[38:41]
	v_mfma_f32_16x16x32_bf16 v[34:37], v[154:157], v[170:173], v[34:37]
	v_mfma_f32_16x16x32_bf16 v[22:25], v[138:141], v[178:181], v[22:25]
	v_mfma_f32_16x16x32_bf16 v[18:21], v[154:157], v[178:181], v[18:21]
	v_mfma_f32_16x16x32_bf16 v[6:9], v[138:141], v[186:189], v[6:9]
	v_mfma_f32_16x16x32_bf16 v[2:5], v[154:157], v[186:189], v[2:5]
	v_mfma_f32_16x16x32_bf16 v[54:57], v[142:145], v[166:169], v[54:57]
	v_mfma_f32_16x16x32_bf16 v[50:53], v[158:161], v[166:169], v[50:53]
	v_mfma_f32_16x16x32_bf16 v[38:41], v[142:145], v[174:177], v[38:41]
	v_mfma_f32_16x16x32_bf16 v[34:37], v[158:161], v[174:177], v[34:37]
	v_mfma_f32_16x16x32_bf16 v[22:25], v[142:145], v[182:185], v[22:25]
	v_mfma_f32_16x16x32_bf16 v[18:21], v[158:161], v[182:185], v[18:21]
	v_mfma_f32_16x16x32_bf16 v[6:9], v[142:145], v[202:205], v[6:9]
	v_mfma_f32_16x16x32_bf16 v[2:5], v[158:161], v[202:205], v[2:5]
	s_barrier
	s_add_i32 s81, s81, 2
	s_add_u32 s4, s4, 0x100
	s_addc_u32 s5, s5, 0
	s_add_u32 s21, s21, 0x100
	s_addc_u32 s27, s27, 0
	s_cmp_gt_u32 s81, 29
.LBB0_602:
	s_add_u32 s30, s4, 0xfff80080
	s_addc_u32 s31, s5, -1
	s_add_i32 s84, 0, 0x10000
	s_cmp_eq_u32 s81, 28
	s_cselect_b32 s41, s29, s31
	s_cselect_b32 s40, s28, s30
	s_cselect_b32 s31, s2, s27
	s_cselect_b32 s30, s3, s21
	s_add_i32 s90, 0, 0x14000
	v_add_u32_e32 v134, s84, v207
	v_add_u32_e32 v158, s90, v207
	ds_read_b128 v[118:121], v134
	ds_read_b128 v[126:129], v134 offset:1024
	ds_read_b128 v[130:133], v134 offset:2048
	ds_read_b128 v[134:137], v134 offset:3072
	ds_read_b128 v[138:141], v158
	ds_read_b128 v[142:145], v158 offset:1024
	ds_read_b128 v[154:157], v158 offset:2048
	ds_read_b128 v[158:161], v158 offset:3072
	v_lshl_add_u64 v[210:211], s[4:5], 0, v[198:199]
	s_add_i32 m0, s35, 0xc000
	ds_read_b128 v[162:165], v208
	ds_read_b128 v[166:169], v208 offset:1024
	ds_read_b128 v[170:173], v208 offset:2048
	ds_read_b128 v[174:177], v208 offset:3072
	ds_read_b128 v[178:181], v208 offset:4096
	ds_read_b128 v[182:185], v208 offset:5120
	ds_read_b128 v[186:189], v208 offset:6144
	ds_read_b128 v[202:205], v208 offset:7168
	global_load_lds_dwordx4 v[210:211], off
	v_lshl_add_u64 v[210:211], s[4:5], 0, v[200:201]
	s_add_i32 m0, s35, 0xe000
	s_nop 0
	global_load_lds_dwordx4 v[210:211], off
	s_waitcnt vmcnt(8)
	s_waitcnt lgkmcnt(0)
	s_barrier
; #define PG8_STAGE(bufoff, gbase, voff) do { _Pragma("unroll") for (int _i = 0; _i < 2; ++_i) \
;         __builtin_amdgcn_global_load_lds((const unsigned*)((const char*)(gbase) + (voff)[_i]), (PG8_LAS unsigned*)(lds + (bufoff) + ldsw + _i * 8192), 16, 0, 0); } while (0)
; #define PG8_LDA(dst, b, h) do { _Pragma("unroll") for (int m = 0; m < 4; ++m) _Pragma("unroll") for (int k = 0; k < 2; ++k) dst[m][k] = *(const PG8_LAS bf16x8*)(lds + PG8_SA(b, h) + aoff + m * 2048 + k * 1024); } while (0)
; #define PG8_LDB(dst, b, h) do { _Pragma("unroll") for (int n = 0; n < 2; ++n) _Pragma("unroll") for (int k = 0; k < 2; ++k) dst[n][k] = *(const PG8_LAS bf16x8*)(lds + PG8_SB(b, h) + boff + n * 2048 + k * 1024); } while (0)
; #define PG8_MMA(ai, bj, At, Bt) do { __builtin_amdgcn_s_setprio(1); _Pragma("unroll") for (int m = 0; m < 4; ++m) _Pragma("unroll") for (int n = 0; n < 2; ++n) _Pragma("unroll") for (int k = 0; k < 2; ++k) \
;         acc[ai][bj][m][n] = __builtin_amdgcn_mfma_f32_16x16x32_bf16(Bt[n][k], At[m][k], acc[ai][bj][m][n], 0, 0, 0); __builtin_amdgcn_s_setprio(0); } while (0)
; #define PG8_WAIT_V(n) asm volatile("s_waitcnt vmcnt(" #n ")" ::: "memory")
; #define PG8_WAIT_L(n) asm volatile("s_waitcnt lgkmcnt(" #n ")" ::: "memory")
; #define PG8_BAR __builtin_amdgcn_s_barrier()
; #define PG8_SCHED __builtin_amdgcn_sched_barrier(0)
; template <class Epi, class Sched, bool ALIGN_EPI = false, bool SP2 = false>
; __device__ __forceinline__ void gemm_phase(PG8_LAS unsigned char* lds, const Gemm g, const Sched& S, const Epi& E, int wave_s) {
;     ...
;             PG8_LDB(B0, 0, 0); PG8_LDB(B1, 0, 1); PG8_SCHED; PG8_LDA(At, 0, 0); PG8_STAGE(PG8_SA(1, 1), a1 + hstepA, voffA);
;             PG8_WAIT_V(8); PG8_WAIT_L(0); PG8_BAR; PG8_MMA(0, 0, At, B0); PG8_MMA(0, 1, At, B1); PG8_BAR; PG8_SCHED;
;             PG8_LDA(At, 0, 1); PG8_STAGE(PG8_SB(0, 0), b2, voffB); PG8_STAGE(PG8_SB(0, 1), b2 + hstepB, voffB); PG8_STAGE(PG8_SA(0, 0), a2, voffA);
;             PG8_WAIT_V(8); PG8_WAIT_L(0); PG8_BAR; PG8_MMA(1, 0, At, B0); PG8_MMA(1, 1, At, B1); PG8_BAR; PG8_SCHED;
	s_waitcnt lgkmcnt(0)
	v_mfma_f32_16x16x32_bf16 v[150:153], v[118:121], v[162:165], v[150:153]
	v_mfma_f32_16x16x32_bf16 v[146:149], v[130:133], v[162:165], v[146:149]
	v_mfma_f32_16x16x32_bf16 v[110:113], v[118:121], v[170:173], v[110:113]
	v_mfma_f32_16x16x32_bf16 v[106:109], v[130:133], v[170:173], v[106:109]
	v_mfma_f32_16x16x32_bf16 v[94:97], v[118:121], v[178:181], v[94:97]
	v_mfma_f32_16x16x32_bf16 v[90:93], v[130:133], v[178:181], v[90:93]
	v_mfma_f32_16x16x32_bf16 v[78:81], v[118:121], v[186:189], v[78:81]
	v_mfma_f32_16x16x32_bf16 v[74:77], v[130:133], v[186:189], v[74:77]
	v_mfma_f32_16x16x32_bf16 v[150:153], v[126:129], v[166:169], v[150:153]
	v_mfma_f32_16x16x32_bf16 v[146:149], v[134:137], v[166:169], v[146:149]
	v_mfma_f32_16x16x32_bf16 v[110:113], v[126:129], v[174:177], v[110:113]
	v_mfma_f32_16x16x32_bf16 v[106:109], v[134:137], v[174:177], v[106:109]
	v_mfma_f32_16x16x32_bf16 v[94:97], v[126:129], v[182:185], v[94:97]
	v_mfma_f32_16x16x32_bf16 v[90:93], v[134:137], v[182:185], v[90:93]
	v_mfma_f32_16x16x32_bf16 v[78:81], v[126:129], v[202:205], v[78:81]
	v_mfma_f32_16x16x32_bf16 v[74:77], v[134:137], v[202:205], v[74:77]
	v_mfma_f32_16x16x32_bf16 v[122:125], v[138:141], v[162:165], v[122:125]
	v_mfma_f32_16x16x32_bf16 v[114:117], v[154:157], v[162:165], v[114:117]
	v_mfma_f32_16x16x32_bf16 v[102:105], v[138:141], v[170:173], v[102:105]
	v_mfma_f32_16x16x32_bf16 v[98:101], v[154:157], v[170:173], v[98:101]
	v_mfma_f32_16x16x32_bf16 v[86:89], v[138:141], v[178:181], v[86:89]
	v_mfma_f32_16x16x32_bf16 v[82:85], v[154:157], v[178:181], v[82:85]
	v_mfma_f32_16x16x32_bf16 v[70:73], v[138:141], v[186:189], v[70:73]
	v_mfma_f32_16x16x32_bf16 v[66:69], v[154:157], v[186:189], v[66:69]
	v_mfma_f32_16x16x32_bf16 v[122:125], v[142:145], v[166:169], v[122:125]
	v_mfma_f32_16x16x32_bf16 v[114:117], v[158:161], v[166:169], v[114:117]
	v_mfma_f32_16x16x32_bf16 v[102:105], v[142:145], v[174:177], v[102:105]
	v_mfma_f32_16x16x32_bf16 v[98:101], v[158:161], v[174:177], v[98:101]
	v_mfma_f32_16x16x32_bf16 v[86:89], v[142:145], v[182:185], v[86:89]
	v_mfma_f32_16x16x32_bf16 v[82:85], v[158:161], v[182:185], v[82:85]
	v_mfma_f32_16x16x32_bf16 v[70:73], v[142:145], v[202:205], v[70:73]
	v_mfma_f32_16x16x32_bf16 v[66:69], v[158:161], v[202:205], v[66:69]
	s_barrier
	s_add_i32 s84, s84, s34
	v_lshl_add_u64 v[210:211], s[30:31], 0, v[194:195]
	s_mov_b32 m0, s84
	ds_read_b128 v[162:165], v208 offset:16384
	ds_read_b128 v[166:169], v208 offset:17408
	ds_read_b128 v[170:173], v208 offset:18432
	ds_read_b128 v[174:177], v208 offset:19456
	ds_read_b128 v[178:181], v208 offset:20480
	ds_read_b128 v[182:185], v208 offset:21504
	ds_read_b128 v[186:189], v208 offset:22528
	ds_read_b128 v[202:205], v208 offset:23552
	global_load_lds_dwordx4 v[210:211], off
	s_add_i32 m0, s84, 0x2000
	s_add_u32 s84, s30, 0x80000
	v_lshl_add_u64 v[212:213], s[30:31], 0, v[190:191]
	s_addc_u32 s85, s31, 0
	s_add_i32 s90, s90, s34
	global_load_lds_dwordx4 v[212:213], off
	v_lshl_add_u64 v[214:215], s[84:85], 0, v[194:195]
	s_mov_b32 m0, s90
	v_lshl_add_u64 v[216:217], s[40:41], 0, v[192:193]
	global_load_lds_dwordx4 v[214:215], off
	v_lshl_add_u64 v[214:215], s[84:85], 0, v[190:191]
	s_add_i32 m0, s90, 0x2000
	s_nop 0
	global_load_lds_dwordx4 v[214:215], off
	v_lshl_add_u64 v[214:215], s[40:41], 0, v[196:197]
	s_mov_b32 m0, s35
	s_nop 0
	global_load_lds_dwordx4 v[214:215], off
	s_mov_b32 m0, s36
	s_nop 0
	global_load_lds_dwordx4 v[216:217], off
	s_waitcnt vmcnt(8)
	s_waitcnt lgkmcnt(0)
	s_barrier
	s_waitcnt lgkmcnt(0)
	v_mfma_f32_16x16x32_bf16 v[62:65], v[118:121], v[162:165], v[62:65]
	v_mfma_f32_16x16x32_bf16 v[58:61], v[130:133], v[162:165], v[58:61]
	v_mfma_f32_16x16x32_bf16 v[46:49], v[118:121], v[170:173], v[46:49]
	v_mfma_f32_16x16x32_bf16 v[42:45], v[130:133], v[170:173], v[42:45]
	v_mfma_f32_16x16x32_bf16 v[30:33], v[118:121], v[178:181], v[30:33]
	v_mfma_f32_16x16x32_bf16 v[26:29], v[130:133], v[178:181], v[26:29]
	v_mfma_f32_16x16x32_bf16 v[14:17], v[118:121], v[186:189], v[14:17]
	v_mfma_f32_16x16x32_bf16 v[10:13], v[130:133], v[186:189], v[10:13]
	v_mfma_f32_16x16x32_bf16 v[62:65], v[126:129], v[166:169], v[62:65]
	v_mfma_f32_16x16x32_bf16 v[58:61], v[134:137], v[166:169], v[58:61]
	v_mfma_f32_16x16x32_bf16 v[46:49], v[126:129], v[174:177], v[46:49]
	v_mfma_f32_16x16x32_bf16 v[42:45], v[134:137], v[174:177], v[42:45]
	v_mfma_f32_16x16x32_bf16 v[30:33], v[126:129], v[182:185], v[30:33]
	v_mfma_f32_16x16x32_bf16 v[26:29], v[134:137], v[182:185], v[26:29]
	v_mfma_f32_16x16x32_bf16 v[14:17], v[126:129], v[202:205], v[14:17]
	v_mfma_f32_16x16x32_bf16 v[10:13], v[134:137], v[202:205], v[10:13]
	v_mfma_f32_16x16x32_bf16 v[54:57], v[138:141], v[162:165], v[54:57]
	v_mfma_f32_16x16x32_bf16 v[50:53], v[154:157], v[162:165], v[50:53]
	v_mfma_f32_16x16x32_bf16 v[38:41], v[138:141], v[170:173], v[38:41]
	v_mfma_f32_16x16x32_bf16 v[34:37], v[154:157], v[170:173], v[34:37]
	v_mfma_f32_16x16x32_bf16 v[22:25], v[138:141], v[178:181], v[22:25]
	v_mfma_f32_16x16x32_bf16 v[18:21], v[154:157], v[178:181], v[18:21]
	v_mfma_f32_16x16x32_bf16 v[6:9], v[138:141], v[186:189], v[6:9]
	v_mfma_f32_16x16x32_bf16 v[2:5], v[154:157], v[186:189], v[2:5]
	v_mfma_f32_16x16x32_bf16 v[54:57], v[142:145], v[166:169], v[54:57]
	v_mfma_f32_16x16x32_bf16 v[50:53], v[158:161], v[166:169], v[50:53]
	v_mfma_f32_16x16x32_bf16 v[38:41], v[142:145], v[174:177], v[38:41]
	v_mfma_f32_16x16x32_bf16 v[34:37], v[158:161], v[174:177], v[34:37]
	v_mfma_f32_16x16x32_bf16 v[22:25], v[142:145], v[182:185], v[22:25]
	v_mfma_f32_16x16x32_bf16 v[18:21], v[158:161], v[182:185], v[18:21]
	v_mfma_f32_16x16x32_bf16 v[6:9], v[142:145], v[202:205], v[6:9]
	v_mfma_f32_16x16x32_bf16 v[2:5], v[158:161], v[202:205], v[2:5]
	s_barrier
; #define PG8_STAGE(bufoff, gbase, voff) do { _Pragma("unroll") for (int _i = 0; _i < 2; ++_i) \
;         __builtin_amdgcn_global_load_lds((const unsigned*)((const char*)(gbase) + (voff)[_i]), (PG8_LAS unsigned*)(lds + (bufoff) + ldsw + _i * 8192), 16, 0, 0); } while (0)
; #define PG8_LDA(dst, b, h) do { _Pragma("unroll") for (int m = 0; m < 4; ++m) _Pragma("unroll") for (int k = 0; k < 2; ++k) dst[m][k] = *(const PG8_LAS bf16x8*)(lds + PG8_SA(b, h) + aoff + m * 2048 + k * 1024); } while (0)
; #define PG8_LDB(dst, b, h) do { _Pragma("unroll") for (int n = 0; n < 2; ++n) _Pragma("unroll") for (int k = 0; k < 2; ++k) dst[n][k] = *(const PG8_LAS bf16x8*)(lds + PG8_SB(b, h) + boff + n * 2048 + k * 1024); } while (0)
; #define PG8_MMA(ai, bj, At, Bt) do { __builtin_amdgcn_s_setprio(1); _Pragma("unroll") for (int m = 0; m < 4; ++m) _Pragma("unroll") for (int n = 0; n < 2; ++n) _Pragma("unroll") for (int k = 0; k < 2; ++k) \
;         acc[ai][bj][m][n] = __builtin_amdgcn_mfma_f32_16x16x32_bf16(Bt[n][k], At[m][k], acc[ai][bj][m][n], 0, 0, 0); __builtin_amdgcn_s_setprio(0); } while (0)
; #define PG8_WAIT_V(n) asm volatile("s_waitcnt vmcnt(" #n ")" ::: "memory")
; #define PG8_WAIT_L(n) asm volatile("s_waitcnt lgkmcnt(" #n ")" ::: "memory")
; #define PG8_BAR __builtin_amdgcn_s_barrier()
; #define PG8_SCHED __builtin_amdgcn_sched_barrier(0)
; template <class Epi, class Sched, bool ALIGN_EPI = false, bool SP2 = false>
; __device__ __forceinline__ void gemm_phase(PG8_LAS unsigned char* lds, const Gemm g, const Sched& S, const Epi& E, int wave_s) {
;     ...
;             PG8_LDB(B0, 1, 0); PG8_LDB(B1, 1, 1); PG8_SCHED; PG8_LDA(At, 1, 0); PG8_STAGE(PG8_SA(0, 1), a2 + hstepA, voffA);
;             PG8_WAIT_V(8); PG8_WAIT_L(0); PG8_BAR; PG8_MMA(0, 0, At, B0); PG8_MMA(0, 1, At, B1); PG8_BAR; PG8_SCHED;
	s_add_i32 s84, 0, 0x18000
	s_add_i32 s85, 0, 0x1c000
	v_add_u32_e32 v134, s84, v207
	v_add_u32_e32 v158, s85, v207
	ds_read_b128 v[118:121], v134
	ds_read_b128 v[126:129], v134 offset:1024
	ds_read_b128 v[130:133], v134 offset:2048
	ds_read_b128 v[134:137], v134 offset:3072
	ds_read_b128 v[138:141], v158
	ds_read_b128 v[142:145], v158 offset:1024
	ds_read_b128 v[154:157], v158 offset:2048
	ds_read_b128 v[158:161], v158 offset:3072
	s_add_u32 s40, s40, 0x80000
	s_addc_u32 s41, s41, 0
	s_mov_b32 m0, s37
	v_lshl_add_u64 v[218:219], s[40:41], 0, v[196:197]
	ds_read_b128 v[162:165], v208 offset:32768
	ds_read_b128 v[166:169], v208 offset:33792
	ds_read_b128 v[170:173], v208 offset:34816
	ds_read_b128 v[174:177], v208 offset:35840
	ds_read_b128 v[178:181], v208 offset:36864
	ds_read_b128 v[182:185], v208 offset:37888
	ds_read_b128 v[186:189], v208 offset:38912
	ds_read_b128 v[202:205], v208 offset:39936
	global_load_lds_dwordx4 v[218:219], off
	v_lshl_add_u64 v[218:219], s[40:41], 0, v[192:193]
	s_mov_b32 m0, s42
	s_nop 0
	global_load_lds_dwordx4 v[218:219], off
	s_waitcnt vmcnt(8)
	s_waitcnt lgkmcnt(0)
	s_barrier
	s_waitcnt lgkmcnt(0)
	v_mfma_f32_16x16x32_bf16 v[150:153], v[118:121], v[162:165], v[150:153]
	v_mfma_f32_16x16x32_bf16 v[146:149], v[130:133], v[162:165], v[146:149]
	v_mfma_f32_16x16x32_bf16 v[110:113], v[118:121], v[170:173], v[110:113]
	v_mfma_f32_16x16x32_bf16 v[106:109], v[130:133], v[170:173], v[106:109]
	v_mfma_f32_16x16x32_bf16 v[94:97], v[118:121], v[178:181], v[94:97]
	v_mfma_f32_16x16x32_bf16 v[90:93], v[130:133], v[178:181], v[90:93]
	v_mfma_f32_16x16x32_bf16 v[78:81], v[118:121], v[186:189], v[78:81]
	v_mfma_f32_16x16x32_bf16 v[74:77], v[130:133], v[186:189], v[74:77]
	v_mfma_f32_16x16x32_bf16 v[150:153], v[126:129], v[166:169], v[150:153]
	v_mfma_f32_16x16x32_bf16 v[146:149], v[134:137], v[166:169], v[146:149]
	v_mfma_f32_16x16x32_bf16 v[110:113], v[126:129], v[174:177], v[110:113]
	v_mfma_f32_16x16x32_bf16 v[106:109], v[134:137], v[174:177], v[106:109]
	v_mfma_f32_16x16x32_bf16 v[94:97], v[126:129], v[182:185], v[94:97]
	v_mfma_f32_16x16x32_bf16 v[90:93], v[134:137], v[182:185], v[90:93]
	v_mfma_f32_16x16x32_bf16 v[78:81], v[126:129], v[202:205], v[78:81]
	v_mfma_f32_16x16x32_bf16 v[74:77], v[134:137], v[202:205], v[74:77]
	v_mfma_f32_16x16x32_bf16 v[122:125], v[138:141], v[162:165], v[122:125]
	v_mfma_f32_16x16x32_bf16 v[114:117], v[154:157], v[162:165], v[114:117]
	v_mfma_f32_16x16x32_bf16 v[102:105], v[138:141], v[170:173], v[102:105]
	v_mfma_f32_16x16x32_bf16 v[98:101], v[154:157], v[170:173], v[98:101]
	v_mfma_f32_16x16x32_bf16 v[86:89], v[138:141], v[178:181], v[86:89]
	v_mfma_f32_16x16x32_bf16 v[82:85], v[154:157], v[178:181], v[82:85]
	v_mfma_f32_16x16x32_bf16 v[70:73], v[138:141], v[186:189], v[70:73]
	v_mfma_f32_16x16x32_bf16 v[66:69], v[154:157], v[186:189], v[66:69]
	v_mfma_f32_16x16x32_bf16 v[122:125], v[142:145], v[166:169], v[122:125]
	v_mfma_f32_16x16x32_bf16 v[114:117], v[158:161], v[166:169], v[114:117]
	v_mfma_f32_16x16x32_bf16 v[102:105], v[142:145], v[174:177], v[102:105]
	v_mfma_f32_16x16x32_bf16 v[98:101], v[158:161], v[174:177], v[98:101]
	v_mfma_f32_16x16x32_bf16 v[86:89], v[142:145], v[182:185], v[86:89]
	v_mfma_f32_16x16x32_bf16 v[82:85], v[158:161], v[182:185], v[82:85]
	v_mfma_f32_16x16x32_bf16 v[70:73], v[142:145], v[202:205], v[70:73]
	v_mfma_f32_16x16x32_bf16 v[66:69], v[158:161], v[202:205], v[66:69]
	s_barrier
; #define PG8_STAGE(bufoff, gbase, voff) do { _Pragma("unroll") for (int _i = 0; _i < 2; ++_i) \
;         __builtin_amdgcn_global_load_lds((const unsigned*)((const char*)(gbase) + (voff)[_i]), (PG8_LAS unsigned*)(lds + (bufoff) + ldsw + _i * 8192), 16, 0, 0); } while (0)
; #define PG8_LDA(dst, b, h) do { _Pragma("unroll") for (int m = 0; m < 4; ++m) _Pragma("unroll") for (int k = 0; k < 2; ++k) dst[m][k] = *(const PG8_LAS bf16x8*)(lds + PG8_SA(b, h) + aoff + m * 2048 + k * 1024); } while (0)
; #define PG8_MMA(ai, bj, At, Bt) do { __builtin_amdgcn_s_setprio(1); _Pragma("unroll") for (int m = 0; m < 4; ++m) _Pragma("unroll") for (int n = 0; n < 2; ++n) _Pragma("unroll") for (int k = 0; k < 2; ++k) \
;         acc[ai][bj][m][n] = __builtin_amdgcn_mfma_f32_16x16x32_bf16(Bt[n][k], At[m][k], acc[ai][bj][m][n], 0, 0, 0); __builtin_amdgcn_s_setprio(0); } while (0)
; #define PG8_WAIT_V(n) asm volatile("s_waitcnt vmcnt(" #n ")" ::: "memory")
; #define PG8_WAIT_L(n) asm volatile("s_waitcnt lgkmcnt(" #n ")" ::: "memory")
; #define PG8_BAR __builtin_amdgcn_s_barrier()
; #define PG8_SCHED __builtin_amdgcn_sched_barrier(0)
; template <class Epi, class Sched, bool ALIGN_EPI = false, bool SP2 = false>
; __device__ __forceinline__ void gemm_phase(PG8_LAS unsigned char* lds, const Gemm g, const Sched& S, const Epi& E, int wave_s) {
;     ...
;             PG8_LDA(At, 1, 1); PG8_STAGE(PG8_SB(1, 0), b3, voffB); PG8_STAGE(PG8_SB(1, 1), b3 + hstepB, voffB); PG8_STAGE(PG8_SA(1, 0), a3, voffA);
;             PG8_WAIT_V(8); PG8_WAIT_L(0); PG8_BAR; PG8_MMA(1, 0, At, B0); PG8_MMA(1, 1, At, B1); PG8_BAR; PG8_SCHED;
;     ...
;         if constexpr (ALIGN_EPI) { if (wr == 0) PG8_BAR; }
	s_add_i32 s40, s84, s34
	v_lshl_add_u64 v[210:211], v[210:211], 0, s[60:61]
	s_mov_b32 m0, s40
	ds_read_b128 v[162:165], v208 offset:49152
	ds_read_b128 v[166:169], v208 offset:50176
	ds_read_b128 v[170:173], v208 offset:51200
	ds_read_b128 v[174:177], v208 offset:52224
	ds_read_b128 v[178:181], v208 offset:53248
	ds_read_b128 v[182:185], v208 offset:54272
	ds_read_b128 v[186:189], v208 offset:55296
	ds_read_b128 v[202:205], v208 offset:56320
	global_load_lds_dwordx4 v[210:211], off
	s_add_i32 m0, s40, 0x2000
	s_add_u32 s30, s30, 0x80080
	v_lshl_add_u64 v[210:211], v[212:213], 0, s[60:61]
	s_addc_u32 s31, s31, 0
	s_add_i32 s40, s85, s34
	global_load_lds_dwordx4 v[210:211], off
	v_lshl_add_u64 v[210:211], s[30:31], 0, v[194:195]
	s_mov_b32 m0, s40
	s_nop 0
	global_load_lds_dwordx4 v[210:211], off
	v_lshl_add_u64 v[210:211], s[30:31], 0, v[190:191]
	s_add_i32 m0, s40, 0x2000
	s_nop 0
	global_load_lds_dwordx4 v[210:211], off
	v_lshl_add_u64 v[210:211], v[214:215], 0, s[60:61]
	s_mov_b32 m0, s46
	s_nop 0
	global_load_lds_dwordx4 v[210:211], off
	v_lshl_add_u64 v[210:211], v[216:217], 0, s[60:61]
	s_mov_b32 m0, s47
	s_nop 0
	global_load_lds_dwordx4 v[210:211], off
	s_waitcnt vmcnt(8)
	s_waitcnt lgkmcnt(0)
	s_barrier
	s_waitcnt lgkmcnt(0)
	v_mfma_f32_16x16x32_bf16 v[62:65], v[118:121], v[162:165], v[62:65]
	v_mfma_f32_16x16x32_bf16 v[58:61], v[130:133], v[162:165], v[58:61]
	v_mfma_f32_16x16x32_bf16 v[46:49], v[118:121], v[170:173], v[46:49]
	v_mfma_f32_16x16x32_bf16 v[42:45], v[130:133], v[170:173], v[42:45]
	v_mfma_f32_16x16x32_bf16 v[30:33], v[118:121], v[178:181], v[30:33]
	v_mfma_f32_16x16x32_bf16 v[26:29], v[130:133], v[178:181], v[26:29]
	v_mfma_f32_16x16x32_bf16 v[14:17], v[118:121], v[186:189], v[14:17]
	v_mfma_f32_16x16x32_bf16 v[10:13], v[130:133], v[186:189], v[10:13]
	v_mfma_f32_16x16x32_bf16 v[62:65], v[126:129], v[166:169], v[62:65]
	v_mfma_f32_16x16x32_bf16 v[58:61], v[134:137], v[166:169], v[58:61]
	v_mfma_f32_16x16x32_bf16 v[46:49], v[126:129], v[174:177], v[46:49]
	v_mfma_f32_16x16x32_bf16 v[42:45], v[134:137], v[174:177], v[42:45]
	v_mfma_f32_16x16x32_bf16 v[30:33], v[126:129], v[182:185], v[30:33]
	v_mfma_f32_16x16x32_bf16 v[26:29], v[134:137], v[182:185], v[26:29]
	v_mfma_f32_16x16x32_bf16 v[14:17], v[126:129], v[202:205], v[14:17]
	v_mfma_f32_16x16x32_bf16 v[10:13], v[134:137], v[202:205], v[10:13]
	v_mfma_f32_16x16x32_bf16 v[54:57], v[138:141], v[162:165], v[54:57]
	v_mfma_f32_16x16x32_bf16 v[50:53], v[154:157], v[162:165], v[50:53]
	v_mfma_f32_16x16x32_bf16 v[38:41], v[138:141], v[170:173], v[38:41]
	v_mfma_f32_16x16x32_bf16 v[34:37], v[154:157], v[170:173], v[34:37]
	v_mfma_f32_16x16x32_bf16 v[22:25], v[138:141], v[178:181], v[22:25]
	v_mfma_f32_16x16x32_bf16 v[18:21], v[154:157], v[178:181], v[18:21]
	v_mfma_f32_16x16x32_bf16 v[6:9], v[138:141], v[186:189], v[6:9]
	v_mfma_f32_16x16x32_bf16 v[2:5], v[154:157], v[186:189], v[2:5]
	v_mfma_f32_16x16x32_bf16 v[54:57], v[142:145], v[166:169], v[54:57]
	v_mfma_f32_16x16x32_bf16 v[50:53], v[158:161], v[166:169], v[50:53]
	v_mfma_f32_16x16x32_bf16 v[38:41], v[142:145], v[174:177], v[38:41]
	v_mfma_f32_16x16x32_bf16 v[34:37], v[158:161], v[174:177], v[34:37]
	v_mfma_f32_16x16x32_bf16 v[22:25], v[142:145], v[182:185], v[22:25]
	v_mfma_f32_16x16x32_bf16 v[18:21], v[158:161], v[182:185], v[18:21]
	v_mfma_f32_16x16x32_bf16 v[6:9], v[142:145], v[202:205], v[6:9]
	v_mfma_f32_16x16x32_bf16 v[2:5], v[158:161], v[202:205], v[2:5]
	s_barrier
	s_add_i32 s81, s81, 2
	s_add_u32 s4, s4, 0x100
	s_addc_u32 s5, s5, 0
	s_add_u32 s21, s21, 0x100
	s_addc_u32 s27, s27, 0
	s_cmp_gt_u32 s81, 29
	s_cbranch_scc0 .LBB0_602
	s_and_b64 vcc, exec, s[14:15]
	s_cbranch_vccz .LBB0_605
	s_barrier

; #define PG8_STAGE(bufoff, gbase, voff) do { _Pragma("unroll") for (int _i = 0; _i < 2; ++_i) \
;         __builtin_amdgcn_global_load_lds((const unsigned*)((const char*)(gbase) + (voff)[_i]), (PG8_LAS unsigned*)(lds + (bufoff) + ldsw + _i * 8192), 16, 0, 0); } while (0)
; #define PG8_LDA(dst, b, h) do { _Pragma("unroll") for (int m = 0; m < 4; ++m) _Pragma("unroll") for (int k = 0; k < 2; ++k) dst[m][k] = *(const PG8_LAS bf16x8*)(lds + PG8_SA(b, h) + aoff + m * 2048 + k * 1024); } while (0)
; #define PG8_LDB(dst, b, h) do { _Pragma("unroll") for (int n = 0; n < 2; ++n) _Pragma("unroll") for (int k = 0; k < 2; ++k) dst[n][k] = *(const PG8_LAS bf16x8*)(lds + PG8_SB(b, h) + boff + n * 2048 + k * 1024); } while (0)
; #define PG8_MMA(ai, bj, At, Bt) do { __builtin_amdgcn_s_setprio(1); _Pragma("unroll") for (int m = 0; m < 4; ++m) _Pragma("unroll") for (int n = 0; n < 2; ++n) _Pragma("unroll") for (int k = 0; k < 2; ++k) \
;         acc[ai][bj][m][n] = __builtin_amdgcn_mfma_f32_16x16x32_bf16(Bt[n][k], At[m][k], acc[ai][bj][m][n], 0, 0, 0); __builtin_amdgcn_s_setprio(0); } while (0)
; #define PG8_BAR __builtin_amdgcn_s_barrier()
; template <class Epi, class Sched, bool ALIGN_EPI = false, bool SP2 = false>
; __device__ __forceinline__ void gemm_phase(PG8_LAS unsigned char* lds, const Gemm g, const Sched& S, const Epi& E, int wave_s) {
;     ...
;         const char* nA = has_next ? (const char*)g.A + (size_t)nxt.pm * tstepA + (size_t)(nxt.pn / g.npg) * (size_t)(K * 2) : cA; const char* nB = has_next ? (const char*)g.Bt + (size_t)nxt.pn * tstepB : cB;
;         for (int t = 0; t < nt; t += 2) {
;             const bool last = (t == nt - 2);
;             const char* a1 = cA + (size_t)(t + 1) * kstep;
;             const char* a2 = last ? nA : cA + (size_t)(t + 2) * kstep; const char* b2 = last ? nB : cB + (size_t)(t + 2) * kstep;
;             const char* a3 = a2 + kstep; const char* b3 = b2 + kstep;
;             if (last && has_next) S.a_ready(nxt);
;             if constexpr (SP2) {
;             PG8_LDB(B0, 0, 0); PG8_LDB(B1, 0, 1); PG8_SCHED; PG8_LDA(At, 0, 0); PG8_STAGE(PG8_SA(1, 1), a1 + hstepA, voffA);
;             PG8_WAIT_V(8); PG8_WAIT_L(0); PG8_BAR; PG8_MMA(0, 0, At, B0); PG8_MMA(0, 1, At, B1); PG8_BAR; PG8_SCHED;
;             PG8_LDA(At, 0, 1); PG8_STAGE(PG8_SB(0, 0), b2, voffB); PG8_STAGE(PG8_SB(0, 1), b2 + hstepB, voffB); PG8_STAGE(PG8_SA(0, 0), a2, voffA);
.LBB0_690:
	s_ashr_i32 s89, s88, 31
	s_lshl_b64 s[2:3], s[88:89], 20
	s_add_u32 s28, s22, s2
	s_addc_u32 s29, s23, s3
	s_and_b64 s[2:3], s[4:5], exec
	s_cselect_b32 s2, s29, s41
	s_cselect_b32 s3, s28, s40
	s_add_u32 s89, s40, 0x100
	s_addc_u32 s91, s41, 0
	s_mov_b32 vcc_lo, -2
	s_add_u32 s4, s30, 0x100
	s_addc_u32 s5, s31, 0
	s_add_i32 vcc_hi, 0, 0x10000
	s_cmp_eq_u32 vcc_lo, 28
	s_cselect_b32 s41, s21, s5
	s_cselect_b32 s40, s20, s4
	s_cselect_b32 s7, s2, s91
	s_cselect_b32 s6, s3, s89
	s_add_i32 s86, 0, 0x14000
	v_add_u32_e32 v142, vcc_hi, v251
	v_add_u32_e32 v158, s86, v251
	ds_read_b128 v[126:129], v142
	ds_read_b128 v[134:137], v142 offset:1024
	ds_read_b128 v[138:141], v142 offset:2048
	ds_read_b128 v[142:145], v142 offset:3072
	ds_read_b128 v[146:149], v158
	ds_read_b128 v[150:153], v158 offset:1024
	ds_read_b128 v[154:157], v158 offset:2048
	ds_read_b128 v[158:161], v158 offset:3072
	v_lshl_add_u64 v[194:195], s[30:31], 0, v[244:245]
	s_add_i32 m0, s36, 0xc000
	ds_read_b128 v[162:165], v252
	ds_read_b128 v[166:169], v252 offset:1024
	ds_read_b128 v[170:173], v252 offset:2048
	ds_read_b128 v[174:177], v252 offset:3072
	ds_read_b128 v[178:181], v252 offset:4096
	ds_read_b128 v[182:185], v252 offset:5120
	ds_read_b128 v[186:189], v252 offset:6144
	ds_read_b128 v[190:193], v252 offset:7168
	global_load_lds_dwordx4 v[194:195], off
	v_lshl_add_u64 v[194:195], s[30:31], 0, v[246:247]
	s_add_i32 m0, s36, 0xe000
	s_nop 0
	global_load_lds_dwordx4 v[194:195], off
	s_waitcnt vmcnt(8)
	s_waitcnt lgkmcnt(0)
	s_barrier
	s_waitcnt lgkmcnt(0)
	v_mfma_f32_16x16x32_bf16 v[130:133], v[126:129], v[162:165], 0
	v_mfma_f32_16x16x32_bf16 v[118:121], v[138:141], v[162:165], 0
	v_mfma_f32_16x16x32_bf16 v[110:113], v[126:129], v[170:173], 0
	v_mfma_f32_16x16x32_bf16 v[98:101], v[138:141], v[170:173], 0
	v_mfma_f32_16x16x32_bf16 v[62:65], v[126:129], v[178:181], 0
	v_mfma_f32_16x16x32_bf16 v[58:61], v[138:141], v[178:181], 0
	v_mfma_f32_16x16x32_bf16 v[46:49], v[126:129], v[186:189], 0
	v_mfma_f32_16x16x32_bf16 v[42:45], v[138:141], v[186:189], 0
	v_mfma_f32_16x16x32_bf16 v[130:133], v[134:137], v[166:169], v[130:133]
	v_mfma_f32_16x16x32_bf16 v[118:121], v[142:145], v[166:169], v[118:121]
	v_mfma_f32_16x16x32_bf16 v[110:113], v[134:137], v[174:177], v[110:113]
	v_mfma_f32_16x16x32_bf16 v[98:101], v[142:145], v[174:177], v[98:101]
	v_mfma_f32_16x16x32_bf16 v[62:65], v[134:137], v[182:185], v[62:65]
	v_mfma_f32_16x16x32_bf16 v[58:61], v[142:145], v[182:185], v[58:61]
	v_mfma_f32_16x16x32_bf16 v[46:49], v[134:137], v[190:193], v[46:49]
	v_mfma_f32_16x16x32_bf16 v[42:45], v[142:145], v[190:193], v[42:45]
	v_mfma_f32_16x16x32_bf16 v[102:105], v[146:149], v[162:165], 0
	v_mfma_f32_16x16x32_bf16 v[74:77], v[154:157], v[162:165], 0
	v_mfma_f32_16x16x32_bf16 v[78:81], v[146:149], v[170:173], 0
	v_mfma_f32_16x16x32_bf16 v[90:93], v[154:157], v[170:173], 0
	v_mfma_f32_16x16x32_bf16 v[34:37], v[146:149], v[178:181], 0
	v_mfma_f32_16x16x32_bf16 v[26:29], v[154:157], v[178:181], 0
	v_mfma_f32_16x16x32_bf16 v[14:17], v[146:149], v[186:189], 0
	v_mfma_f32_16x16x32_bf16 v[2:5], v[154:157], v[186:189], 0
	v_mfma_f32_16x16x32_bf16 v[102:105], v[150:153], v[166:169], v[102:105]
	v_mfma_f32_16x16x32_bf16 v[74:77], v[158:161], v[166:169], v[74:77]
	v_mfma_f32_16x16x32_bf16 v[78:81], v[150:153], v[174:177], v[78:81]
	v_mfma_f32_16x16x32_bf16 v[90:93], v[158:161], v[174:177], v[90:93]
	v_mfma_f32_16x16x32_bf16 v[34:37], v[150:153], v[182:185], v[34:37]
	v_mfma_f32_16x16x32_bf16 v[26:29], v[158:161], v[182:185], v[26:29]
	v_mfma_f32_16x16x32_bf16 v[14:17], v[150:153], v[190:193], v[14:17]
	v_mfma_f32_16x16x32_bf16 v[2:5], v[158:161], v[190:193], v[2:5]
	s_barrier
	s_add_i32 s30, vcc_hi, s35
	v_lshl_add_u64 v[194:195], s[6:7], 0, v[238:239]
	s_mov_b32 m0, s30
	ds_read_b128 v[162:165], v252 offset:16384
	ds_read_b128 v[166:169], v252 offset:17408
	ds_read_b128 v[170:173], v252 offset:18432
	ds_read_b128 v[174:177], v252 offset:19456
	ds_read_b128 v[178:181], v252 offset:20480
	ds_read_b128 v[182:185], v252 offset:21504
	ds_read_b128 v[186:189], v252 offset:22528
	ds_read_b128 v[190:193], v252 offset:23552
	global_load_lds_dwordx4 v[194:195], off
	s_add_i32 m0, s30, 0x2000
	s_add_u32 s30, s6, 0x80000
	v_lshl_add_u64 v[196:197], s[6:7], 0, v[242:243]
	s_addc_u32 s31, s7, 0
	s_add_i32 s86, s86, s35
	global_load_lds_dwordx4 v[196:197], off
	v_lshl_add_u64 v[198:199], s[30:31], 0, v[238:239]
	s_mov_b32 m0, s86
	v_lshl_add_u64 v[200:201], s[40:41], 0, v[240:241]
	global_load_lds_dwordx4 v[198:199], off
	v_lshl_add_u64 v[198:199], s[30:31], 0, v[242:243]
	s_add_i32 m0, s86, 0x2000
	s_nop 0
	global_load_lds_dwordx4 v[198:199], off
	v_lshl_add_u64 v[198:199], s[40:41], 0, v[236:237]
	s_mov_b32 m0, s36
	s_nop 0
	global_load_lds_dwordx4 v[198:199], off
	s_mov_b32 m0, s37
	s_nop 0
	global_load_lds_dwordx4 v[200:201], off
	s_waitcnt vmcnt(8)
	s_waitcnt lgkmcnt(0)
	s_barrier
; #define PG8_STAGE(bufoff, gbase, voff) do { _Pragma("unroll") for (int _i = 0; _i < 2; ++_i) \
;         __builtin_amdgcn_global_load_lds((const unsigned*)((const char*)(gbase) + (voff)[_i]), (PG8_LAS unsigned*)(lds + (bufoff) + ldsw + _i * 8192), 16, 0, 0); } while (0)
; #define PG8_LDA(dst, b, h) do { _Pragma("unroll") for (int m = 0; m < 4; ++m) _Pragma("unroll") for (int k = 0; k < 2; ++k) dst[m][k] = *(const PG8_LAS bf16x8*)(lds + PG8_SA(b, h) + aoff + m * 2048 + k * 1024); } while (0)
; #define PG8_LDB(dst, b, h) do { _Pragma("unroll") for (int n = 0; n < 2; ++n) _Pragma("unroll") for (int k = 0; k < 2; ++k) dst[n][k] = *(const PG8_LAS bf16x8*)(lds + PG8_SB(b, h) + boff + n * 2048 + k * 1024); } while (0)
; #define PG8_MMA(ai, bj, At, Bt) do { __builtin_amdgcn_s_setprio(1); _Pragma("unroll") for (int m = 0; m < 4; ++m) _Pragma("unroll") for (int n = 0; n < 2; ++n) _Pragma("unroll") for (int k = 0; k < 2; ++k) \
;         acc[ai][bj][m][n] = __builtin_amdgcn_mfma_f32_16x16x32_bf16(Bt[n][k], At[m][k], acc[ai][bj][m][n], 0, 0, 0); __builtin_amdgcn_s_setprio(0); } while (0)
; #define PG8_WAIT_V(n) asm volatile("s_waitcnt vmcnt(" #n ")" ::: "memory")
; #define PG8_WAIT_L(n) asm volatile("s_waitcnt lgkmcnt(" #n ")" ::: "memory")
; #define PG8_BAR __builtin_amdgcn_s_barrier()
; #define PG8_SCHED __builtin_amdgcn_sched_barrier(0)
; template <class Epi, class Sched, bool ALIGN_EPI = false, bool SP2 = false>
; __device__ __forceinline__ void gemm_phase(PG8_LAS unsigned char* lds, const Gemm g, const Sched& S, const Epi& E, int wave_s) {
;     ...
;             PG8_WAIT_V(8); PG8_WAIT_L(0); PG8_BAR; PG8_MMA(1, 0, At, B0); PG8_MMA(1, 1, At, B1); PG8_BAR; PG8_SCHED;
;             PG8_LDB(B0, 1, 0); PG8_LDB(B1, 1, 1); PG8_SCHED; PG8_LDA(At, 1, 0); PG8_STAGE(PG8_SA(0, 1), a2 + hstepA, voffA);
;             PG8_WAIT_V(8); PG8_WAIT_L(0); PG8_BAR; PG8_MMA(0, 0, At, B0); PG8_MMA(0, 1, At, B1); PG8_BAR; PG8_SCHED;
	s_waitcnt lgkmcnt(0)
	v_mfma_f32_16x16x32_bf16 v[54:57], v[126:129], v[162:165], 0
	v_mfma_f32_16x16x32_bf16 v[50:53], v[138:141], v[162:165], 0
	v_mfma_f32_16x16x32_bf16 v[38:41], v[126:129], v[170:173], 0
	v_mfma_f32_16x16x32_bf16 v[30:33], v[138:141], v[170:173], 0
	v_mfma_f32_16x16x32_bf16 v[86:89], v[126:129], v[178:181], 0
	v_mfma_f32_16x16x32_bf16 v[122:125], v[138:141], v[178:181], 0
	v_mfma_f32_16x16x32_bf16 v[114:117], v[126:129], v[186:189], 0
	v_mfma_f32_16x16x32_bf16 v[106:109], v[138:141], v[186:189], 0
	v_mfma_f32_16x16x32_bf16 v[54:57], v[134:137], v[166:169], v[54:57]
	v_mfma_f32_16x16x32_bf16 v[50:53], v[142:145], v[166:169], v[50:53]
	v_mfma_f32_16x16x32_bf16 v[38:41], v[134:137], v[174:177], v[38:41]
	v_mfma_f32_16x16x32_bf16 v[30:33], v[142:145], v[174:177], v[30:33]
	v_mfma_f32_16x16x32_bf16 v[86:89], v[134:137], v[182:185], v[86:89]
	v_mfma_f32_16x16x32_bf16 v[122:125], v[142:145], v[182:185], v[122:125]
	v_mfma_f32_16x16x32_bf16 v[114:117], v[134:137], v[190:193], v[114:117]
	v_mfma_f32_16x16x32_bf16 v[106:109], v[142:145], v[190:193], v[106:109]
	v_mfma_f32_16x16x32_bf16 v[22:25], v[146:149], v[162:165], 0
	v_mfma_f32_16x16x32_bf16 v[18:21], v[154:157], v[162:165], 0
	v_mfma_f32_16x16x32_bf16 v[10:13], v[146:149], v[170:173], 0
	v_mfma_f32_16x16x32_bf16 v[6:9], v[154:157], v[170:173], 0
	v_mfma_f32_16x16x32_bf16 v[82:85], v[146:149], v[178:181], 0
	v_mfma_f32_16x16x32_bf16 v[94:97], v[154:157], v[178:181], 0
	v_mfma_f32_16x16x32_bf16 v[70:73], v[146:149], v[186:189], 0
	v_mfma_f32_16x16x32_bf16 v[66:69], v[154:157], v[186:189], 0
	v_mfma_f32_16x16x32_bf16 v[22:25], v[150:153], v[166:169], v[22:25]
	v_mfma_f32_16x16x32_bf16 v[18:21], v[158:161], v[166:169], v[18:21]
	v_mfma_f32_16x16x32_bf16 v[10:13], v[150:153], v[174:177], v[10:13]
	v_mfma_f32_16x16x32_bf16 v[6:9], v[158:161], v[174:177], v[6:9]
	v_mfma_f32_16x16x32_bf16 v[82:85], v[150:153], v[182:185], v[82:85]
	v_mfma_f32_16x16x32_bf16 v[94:97], v[158:161], v[182:185], v[94:97]
	v_mfma_f32_16x16x32_bf16 v[70:73], v[150:153], v[190:193], v[70:73]
	v_mfma_f32_16x16x32_bf16 v[66:69], v[158:161], v[190:193], v[66:69]
	s_barrier
	s_add_i32 s86, 0, 0x18000
	s_add_i32 s87, 0, 0x1c000
	v_add_u32_e32 v142, s86, v251
	v_add_u32_e32 v158, s87, v251
	ds_read_b128 v[126:129], v142
	ds_read_b128 v[134:137], v142 offset:1024
	ds_read_b128 v[138:141], v142 offset:2048
	ds_read_b128 v[142:145], v142 offset:3072
	ds_read_b128 v[146:149], v158
	ds_read_b128 v[150:153], v158 offset:1024
	ds_read_b128 v[154:157], v158 offset:2048
	ds_read_b128 v[158:161], v158 offset:3072
	s_add_u32 s30, s40, 0x4000
	s_addc_u32 s31, s41, 0
	s_mov_b32 m0, s42
	v_lshl_add_u64 v[202:203], s[30:31], 0, v[236:237]
	ds_read_b128 v[162:165], v252 offset:32768
	ds_read_b128 v[166:169], v252 offset:33792
	ds_read_b128 v[170:173], v252 offset:34816
	ds_read_b128 v[174:177], v252 offset:35840
	ds_read_b128 v[178:181], v252 offset:36864
	ds_read_b128 v[182:185], v252 offset:37888
	ds_read_b128 v[186:189], v252 offset:38912
	ds_read_b128 v[190:193], v252 offset:39936
	global_load_lds_dwordx4 v[202:203], off
	v_lshl_add_u64 v[202:203], s[30:31], 0, v[240:241]
	s_mov_b32 m0, s43
	s_nop 0
	global_load_lds_dwordx4 v[202:203], off
	s_waitcnt vmcnt(8)
	s_waitcnt lgkmcnt(0)
	s_barrier
	s_waitcnt lgkmcnt(0)
	v_mfma_f32_16x16x32_bf16 v[130:133], v[126:129], v[162:165], v[130:133]
	v_mfma_f32_16x16x32_bf16 v[118:121], v[138:141], v[162:165], v[118:121]
	v_mfma_f32_16x16x32_bf16 v[110:113], v[126:129], v[170:173], v[110:113]
	v_mfma_f32_16x16x32_bf16 v[98:101], v[138:141], v[170:173], v[98:101]
	v_mfma_f32_16x16x32_bf16 v[62:65], v[126:129], v[178:181], v[62:65]
	v_mfma_f32_16x16x32_bf16 v[58:61], v[138:141], v[178:181], v[58:61]
	v_mfma_f32_16x16x32_bf16 v[46:49], v[126:129], v[186:189], v[46:49]
	v_mfma_f32_16x16x32_bf16 v[42:45], v[138:141], v[186:189], v[42:45]
	v_mfma_f32_16x16x32_bf16 v[130:133], v[134:137], v[166:169], v[130:133]
	v_mfma_f32_16x16x32_bf16 v[118:121], v[142:145], v[166:169], v[118:121]
	v_mfma_f32_16x16x32_bf16 v[110:113], v[134:137], v[174:177], v[110:113]
	v_mfma_f32_16x16x32_bf16 v[98:101], v[142:145], v[174:177], v[98:101]
	v_mfma_f32_16x16x32_bf16 v[62:65], v[134:137], v[182:185], v[62:65]
	v_mfma_f32_16x16x32_bf16 v[58:61], v[142:145], v[182:185], v[58:61]
	v_mfma_f32_16x16x32_bf16 v[46:49], v[134:137], v[190:193], v[46:49]
	v_mfma_f32_16x16x32_bf16 v[42:45], v[142:145], v[190:193], v[42:45]
	v_mfma_f32_16x16x32_bf16 v[102:105], v[146:149], v[162:165], v[102:105]
	v_mfma_f32_16x16x32_bf16 v[74:77], v[154:157], v[162:165], v[74:77]
	v_mfma_f32_16x16x32_bf16 v[78:81], v[146:149], v[170:173], v[78:81]
	v_mfma_f32_16x16x32_bf16 v[90:93], v[154:157], v[170:173], v[90:93]
	v_mfma_f32_16x16x32_bf16 v[34:37], v[146:149], v[178:181], v[34:37]
	v_mfma_f32_16x16x32_bf16 v[26:29], v[154:157], v[178:181], v[26:29]
	v_mfma_f32_16x16x32_bf16 v[14:17], v[146:149], v[186:189], v[14:17]
	v_mfma_f32_16x16x32_bf16 v[2:5], v[154:157], v[186:189], v[2:5]
	v_mfma_f32_16x16x32_bf16 v[102:105], v[150:153], v[166:169], v[102:105]
	v_mfma_f32_16x16x32_bf16 v[74:77], v[158:161], v[166:169], v[74:77]
	v_mfma_f32_16x16x32_bf16 v[78:81], v[150:153], v[174:177], v[78:81]
	v_mfma_f32_16x16x32_bf16 v[90:93], v[158:161], v[174:177], v[90:93]
	v_mfma_f32_16x16x32_bf16 v[34:37], v[150:153], v[182:185], v[34:37]
	v_mfma_f32_16x16x32_bf16 v[26:29], v[158:161], v[182:185], v[26:29]
	v_mfma_f32_16x16x32_bf16 v[14:17], v[150:153], v[190:193], v[14:17]
	v_mfma_f32_16x16x32_bf16 v[2:5], v[158:161], v[190:193], v[2:5]
	s_barrier
; #define PG8_STAGE(bufoff, gbase, voff) do { _Pragma("unroll") for (int _i = 0; _i < 2; ++_i) \
;         __builtin_amdgcn_global_load_lds((const unsigned*)((const char*)(gbase) + (voff)[_i]), (PG8_LAS unsigned*)(lds + (bufoff) + ldsw + _i * 8192), 16, 0, 0); } while (0)
; #define PG8_LDA(dst, b, h) do { _Pragma("unroll") for (int m = 0; m < 4; ++m) _Pragma("unroll") for (int k = 0; k < 2; ++k) dst[m][k] = *(const PG8_LAS bf16x8*)(lds + PG8_SA(b, h) + aoff + m * 2048 + k * 1024); } while (0)
; #define PG8_LDB(dst, b, h) do { _Pragma("unroll") for (int n = 0; n < 2; ++n) _Pragma("unroll") for (int k = 0; k < 2; ++k) dst[n][k] = *(const PG8_LAS bf16x8*)(lds + PG8_SB(b, h) + boff + n * 2048 + k * 1024); } while (0)
; #define PG8_MMA(ai, bj, At, Bt) do { __builtin_amdgcn_s_setprio(1); _Pragma("unroll") for (int m = 0; m < 4; ++m) _Pragma("unroll") for (int n = 0; n < 2; ++n) _Pragma("unroll") for (int k = 0; k < 2; ++k) \
;         acc[ai][bj][m][n] = __builtin_amdgcn_mfma_f32_16x16x32_bf16(Bt[n][k], At[m][k], acc[ai][bj][m][n], 0, 0, 0); __builtin_amdgcn_s_setprio(0); } while (0)
; #define PG8_WAIT_V(n) asm volatile("s_waitcnt vmcnt(" #n ")" ::: "memory")
; #define PG8_WAIT_L(n) asm volatile("s_waitcnt lgkmcnt(" #n ")" ::: "memory")
; #define PG8_BAR __builtin_amdgcn_s_barrier()
; #define PG8_SCHED __builtin_amdgcn_sched_barrier(0)
; template <class Epi, class Sched, bool ALIGN_EPI = false, bool SP2 = false>
; __device__ __forceinline__ void gemm_phase(PG8_LAS unsigned char* lds, const Gemm g, const Sched& S, const Epi& E, int wave_s) {
;     ...
;             const bool last = (t == nt - 2);
;             const char* a1 = cA + (size_t)(t + 1) * kstep;
;             const char* a2 = last ? nA : cA + (size_t)(t + 2) * kstep; const char* b2 = last ? nB : cB + (size_t)(t + 2) * kstep;
;             const char* a3 = a2 + kstep; const char* b3 = b2 + kstep;
;             if (last && has_next) S.a_ready(nxt);
;             if constexpr (SP2) {
;             PG8_LDB(B0, 0, 0); PG8_LDB(B1, 0, 1); PG8_SCHED; PG8_LDA(At, 0, 0); PG8_STAGE(PG8_SA(1, 1), a1 + hstepA, voffA);
;     ...
;             PG8_LDA(At, 1, 1); PG8_STAGE(PG8_SB(1, 0), b3, voffB); PG8_STAGE(PG8_SB(1, 1), b3 + hstepB, voffB); PG8_STAGE(PG8_SA(1, 0), a3, voffA);
;             PG8_WAIT_V(8); PG8_WAIT_L(0); PG8_BAR; PG8_MMA(1, 0, At, B0); PG8_MMA(1, 1, At, B1); PG8_BAR; PG8_SCHED;
	s_add_i32 s30, s86, s35
	v_lshl_add_u64 v[194:195], v[194:195], 0, s[60:61]
	s_mov_b32 m0, s30
	ds_read_b128 v[162:165], v252 offset:49152
	ds_read_b128 v[166:169], v252 offset:50176
	ds_read_b128 v[170:173], v252 offset:51200
	ds_read_b128 v[174:177], v252 offset:52224
	ds_read_b128 v[178:181], v252 offset:53248
	ds_read_b128 v[182:185], v252 offset:54272
	ds_read_b128 v[186:189], v252 offset:55296
	ds_read_b128 v[190:193], v252 offset:56320
	global_load_lds_dwordx4 v[194:195], off
	s_add_i32 m0, s30, 0x2000
	s_add_u32 s6, s6, 0x80080
	v_lshl_add_u64 v[194:195], v[196:197], 0, s[60:61]
	s_addc_u32 s7, s7, 0
	s_add_i32 s30, s87, s35
	global_load_lds_dwordx4 v[194:195], off
	v_lshl_add_u64 v[194:195], s[6:7], 0, v[238:239]
	s_mov_b32 m0, s30
	s_nop 0
	global_load_lds_dwordx4 v[194:195], off
	v_lshl_add_u64 v[194:195], s[6:7], 0, v[242:243]
	s_add_i32 m0, s30, 0x2000
	s_nop 0
	global_load_lds_dwordx4 v[194:195], off
	v_lshl_add_u64 v[194:195], v[198:199], 0, s[60:61]
	s_mov_b32 m0, s77
	s_nop 0
	global_load_lds_dwordx4 v[194:195], off
	v_lshl_add_u64 v[194:195], v[200:201], 0, s[60:61]
	s_mov_b32 m0, s94
	s_nop 0
	global_load_lds_dwordx4 v[194:195], off
	s_waitcnt vmcnt(8)
	s_waitcnt lgkmcnt(0)
	s_barrier
	s_waitcnt lgkmcnt(0)
	v_mfma_f32_16x16x32_bf16 v[54:57], v[126:129], v[162:165], v[54:57]
	v_mfma_f32_16x16x32_bf16 v[50:53], v[138:141], v[162:165], v[50:53]
	v_mfma_f32_16x16x32_bf16 v[38:41], v[126:129], v[170:173], v[38:41]
	v_mfma_f32_16x16x32_bf16 v[30:33], v[138:141], v[170:173], v[30:33]
	v_mfma_f32_16x16x32_bf16 v[86:89], v[126:129], v[178:181], v[86:89]
	v_mfma_f32_16x16x32_bf16 v[122:125], v[138:141], v[178:181], v[122:125]
	v_mfma_f32_16x16x32_bf16 v[114:117], v[126:129], v[186:189], v[114:117]
	v_mfma_f32_16x16x32_bf16 v[106:109], v[138:141], v[186:189], v[106:109]
	v_mfma_f32_16x16x32_bf16 v[54:57], v[134:137], v[166:169], v[54:57]
	v_mfma_f32_16x16x32_bf16 v[50:53], v[142:145], v[166:169], v[50:53]
	v_mfma_f32_16x16x32_bf16 v[38:41], v[134:137], v[174:177], v[38:41]
	v_mfma_f32_16x16x32_bf16 v[30:33], v[142:145], v[174:177], v[30:33]
	v_mfma_f32_16x16x32_bf16 v[86:89], v[134:137], v[182:185], v[86:89]
	v_mfma_f32_16x16x32_bf16 v[122:125], v[142:145], v[182:185], v[122:125]
	v_mfma_f32_16x16x32_bf16 v[114:117], v[134:137], v[190:193], v[114:117]
	v_mfma_f32_16x16x32_bf16 v[106:109], v[142:145], v[190:193], v[106:109]
	v_mfma_f32_16x16x32_bf16 v[22:25], v[146:149], v[162:165], v[22:25]
	v_mfma_f32_16x16x32_bf16 v[18:21], v[154:157], v[162:165], v[18:21]
	v_mfma_f32_16x16x32_bf16 v[10:13], v[146:149], v[170:173], v[10:13]
	v_mfma_f32_16x16x32_bf16 v[6:9], v[154:157], v[170:173], v[6:9]
	v_mfma_f32_16x16x32_bf16 v[82:85], v[146:149], v[178:181], v[82:85]
	v_mfma_f32_16x16x32_bf16 v[94:97], v[154:157], v[178:181], v[94:97]
	v_mfma_f32_16x16x32_bf16 v[70:73], v[146:149], v[186:189], v[70:73]
	v_mfma_f32_16x16x32_bf16 v[66:69], v[154:157], v[186:189], v[66:69]
	v_mfma_f32_16x16x32_bf16 v[22:25], v[150:153], v[166:169], v[22:25]
	v_mfma_f32_16x16x32_bf16 v[18:21], v[158:161], v[166:169], v[18:21]
	v_mfma_f32_16x16x32_bf16 v[10:13], v[150:153], v[174:177], v[10:13]
	v_mfma_f32_16x16x32_bf16 v[6:9], v[158:161], v[174:177], v[6:9]
	v_mfma_f32_16x16x32_bf16 v[82:85], v[150:153], v[182:185], v[82:85]
	v_mfma_f32_16x16x32_bf16 v[94:97], v[158:161], v[182:185], v[94:97]
	v_mfma_f32_16x16x32_bf16 v[70:73], v[150:153], v[190:193], v[70:73]
	v_mfma_f32_16x16x32_bf16 v[66:69], v[158:161], v[190:193], v[66:69]
	s_barrier
	s_add_i32 vcc_lo, vcc_lo, 2
	s_add_u32 s89, s89, 0x100
	s_addc_u32 s91, s91, 0
	s_cmp_gt_u32 vcc_lo, 29
	s_mov_b64 s[30:31], s[4:5]
.LBB0_691:
	s_add_u32 s4, s30, 0x100
	s_addc_u32 s5, s31, 0
	s_add_i32 vcc_hi, 0, 0x10000
	s_cmp_eq_u32 vcc_lo, 28
	s_cselect_b32 s41, s21, s5
	s_cselect_b32 s40, s20, s4
	s_cselect_b32 s7, s2, s91
	s_cselect_b32 s6, s3, s89
	s_add_i32 s86, 0, 0x14000
	v_add_u32_e32 v142, vcc_hi, v251
	v_add_u32_e32 v158, s86, v251
	ds_read_b128 v[126:129], v142
	ds_read_b128 v[134:137], v142 offset:1024
	ds_read_b128 v[138:141], v142 offset:2048
	ds_read_b128 v[142:145], v142 offset:3072
	ds_read_b128 v[146:149], v158
	ds_read_b128 v[150:153], v158 offset:1024
	ds_read_b128 v[154:157], v158 offset:2048
	ds_read_b128 v[158:161], v158 offset:3072
	v_lshl_add_u64 v[194:195], s[30:31], 0, v[244:245]
	s_add_i32 m0, s36, 0xc000
	ds_read_b128 v[162:165], v252
	ds_read_b128 v[166:169], v252 offset:1024
	ds_read_b128 v[170:173], v252 offset:2048
	ds_read_b128 v[174:177], v252 offset:3072
	ds_read_b128 v[178:181], v252 offset:4096
	ds_read_b128 v[182:185], v252 offset:5120
	ds_read_b128 v[186:189], v252 offset:6144
	ds_read_b128 v[190:193], v252 offset:7168
	global_load_lds_dwordx4 v[194:195], off
	v_lshl_add_u64 v[194:195], s[30:31], 0, v[246:247]
	s_add_i32 m0, s36, 0xe000
	s_nop 0
	global_load_lds_dwordx4 v[194:195], off
	s_waitcnt vmcnt(8)
	s_waitcnt lgkmcnt(0)
	s_barrier
; #define PG8_STAGE(bufoff, gbase, voff) do { _Pragma("unroll") for (int _i = 0; _i < 2; ++_i) \
;         __builtin_amdgcn_global_load_lds((const unsigned*)((const char*)(gbase) + (voff)[_i]), (PG8_LAS unsigned*)(lds + (bufoff) + ldsw + _i * 8192), 16, 0, 0); } while (0)
; #define PG8_LDA(dst, b, h) do { _Pragma("unroll") for (int m = 0; m < 4; ++m) _Pragma("unroll") for (int k = 0; k < 2; ++k) dst[m][k] = *(const PG8_LAS bf16x8*)(lds + PG8_SA(b, h) + aoff + m * 2048 + k * 1024); } while (0)
; #define PG8_MMA(ai, bj, At, Bt) do { __builtin_amdgcn_s_setprio(1); _Pragma("unroll") for (int m = 0; m < 4; ++m) _Pragma("unroll") for (int n = 0; n < 2; ++n) _Pragma("unroll") for (int k = 0; k < 2; ++k) \
;         acc[ai][bj][m][n] = __builtin_amdgcn_mfma_f32_16x16x32_bf16(Bt[n][k], At[m][k], acc[ai][bj][m][n], 0, 0, 0); __builtin_amdgcn_s_setprio(0); } while (0)
; #define PG8_WAIT_V(n) asm volatile("s_waitcnt vmcnt(" #n ")" ::: "memory")
; #define PG8_WAIT_L(n) asm volatile("s_waitcnt lgkmcnt(" #n ")" ::: "memory")
; #define PG8_BAR __builtin_amdgcn_s_barrier()
; #define PG8_SCHED __builtin_amdgcn_sched_barrier(0)
; template <class Epi, class Sched, bool ALIGN_EPI = false, bool SP2 = false>
; __device__ __forceinline__ void gemm_phase(PG8_LAS unsigned char* lds, const Gemm g, const Sched& S, const Epi& E, int wave_s) {
;     ...
;             PG8_WAIT_V(8); PG8_WAIT_L(0); PG8_BAR; PG8_MMA(0, 0, At, B0); PG8_MMA(0, 1, At, B1); PG8_BAR; PG8_SCHED;
;             PG8_LDA(At, 0, 1); PG8_STAGE(PG8_SB(0, 0), b2, voffB); PG8_STAGE(PG8_SB(0, 1), b2 + hstepB, voffB); PG8_STAGE(PG8_SA(0, 0), a2, voffA);
;             PG8_WAIT_V(8); PG8_WAIT_L(0); PG8_BAR; PG8_MMA(1, 0, At, B0); PG8_MMA(1, 1, At, B1); PG8_BAR; PG8_SCHED;
	s_waitcnt lgkmcnt(0)
	v_mfma_f32_16x16x32_bf16 v[130:133], v[126:129], v[162:165], v[130:133]
	v_mfma_f32_16x16x32_bf16 v[118:121], v[138:141], v[162:165], v[118:121]
	v_mfma_f32_16x16x32_bf16 v[110:113], v[126:129], v[170:173], v[110:113]
	v_mfma_f32_16x16x32_bf16 v[98:101], v[138:141], v[170:173], v[98:101]
	v_mfma_f32_16x16x32_bf16 v[62:65], v[126:129], v[178:181], v[62:65]
	v_mfma_f32_16x16x32_bf16 v[58:61], v[138:141], v[178:181], v[58:61]
	v_mfma_f32_16x16x32_bf16 v[46:49], v[126:129], v[186:189], v[46:49]
	v_mfma_f32_16x16x32_bf16 v[42:45], v[138:141], v[186:189], v[42:45]
	v_mfma_f32_16x16x32_bf16 v[130:133], v[134:137], v[166:169], v[130:133]
	v_mfma_f32_16x16x32_bf16 v[118:121], v[142:145], v[166:169], v[118:121]
	v_mfma_f32_16x16x32_bf16 v[110:113], v[134:137], v[174:177], v[110:113]
	v_mfma_f32_16x16x32_bf16 v[98:101], v[142:145], v[174:177], v[98:101]
	v_mfma_f32_16x16x32_bf16 v[62:65], v[134:137], v[182:185], v[62:65]
	v_mfma_f32_16x16x32_bf16 v[58:61], v[142:145], v[182:185], v[58:61]
	v_mfma_f32_16x16x32_bf16 v[46:49], v[134:137], v[190:193], v[46:49]
	v_mfma_f32_16x16x32_bf16 v[42:45], v[142:145], v[190:193], v[42:45]
	v_mfma_f32_16x16x32_bf16 v[102:105], v[146:149], v[162:165], v[102:105]
	v_mfma_f32_16x16x32_bf16 v[74:77], v[154:157], v[162:165], v[74:77]
	v_mfma_f32_16x16x32_bf16 v[78:81], v[146:149], v[170:173], v[78:81]
	v_mfma_f32_16x16x32_bf16 v[90:93], v[154:157], v[170:173], v[90:93]
	v_mfma_f32_16x16x32_bf16 v[34:37], v[146:149], v[178:181], v[34:37]
	v_mfma_f32_16x16x32_bf16 v[26:29], v[154:157], v[178:181], v[26:29]
	v_mfma_f32_16x16x32_bf16 v[14:17], v[146:149], v[186:189], v[14:17]
	v_mfma_f32_16x16x32_bf16 v[2:5], v[154:157], v[186:189], v[2:5]
	v_mfma_f32_16x16x32_bf16 v[102:105], v[150:153], v[166:169], v[102:105]
	v_mfma_f32_16x16x32_bf16 v[74:77], v[158:161], v[166:169], v[74:77]
	v_mfma_f32_16x16x32_bf16 v[78:81], v[150:153], v[174:177], v[78:81]
	v_mfma_f32_16x16x32_bf16 v[90:93], v[158:161], v[174:177], v[90:93]
	v_mfma_f32_16x16x32_bf16 v[34:37], v[150:153], v[182:185], v[34:37]
	v_mfma_f32_16x16x32_bf16 v[26:29], v[158:161], v[182:185], v[26:29]
	v_mfma_f32_16x16x32_bf16 v[14:17], v[150:153], v[190:193], v[14:17]
	v_mfma_f32_16x16x32_bf16 v[2:5], v[158:161], v[190:193], v[2:5]
	s_barrier
	s_add_i32 s30, vcc_hi, s35
	v_lshl_add_u64 v[194:195], s[6:7], 0, v[238:239]
	s_mov_b32 m0, s30
	ds_read_b128 v[162:165], v252 offset:16384
	ds_read_b128 v[166:169], v252 offset:17408
	ds_read_b128 v[170:173], v252 offset:18432
	ds_read_b128 v[174:177], v252 offset:19456
	ds_read_b128 v[178:181], v252 offset:20480
	ds_read_b128 v[182:185], v252 offset:21504
	ds_read_b128 v[186:189], v252 offset:22528
	ds_read_b128 v[190:193], v252 offset:23552
	global_load_lds_dwordx4 v[194:195], off
	s_add_i32 m0, s30, 0x2000
	s_add_u32 s30, s6, 0x80000
	v_lshl_add_u64 v[196:197], s[6:7], 0, v[242:243]
	s_addc_u32 s31, s7, 0
	s_add_i32 s86, s86, s35
	global_load_lds_dwordx4 v[196:197], off
	v_lshl_add_u64 v[198:199], s[30:31], 0, v[238:239]
	s_mov_b32 m0, s86
	v_lshl_add_u64 v[200:201], s[40:41], 0, v[240:241]
	global_load_lds_dwordx4 v[198:199], off
	v_lshl_add_u64 v[198:199], s[30:31], 0, v[242:243]
	s_add_i32 m0, s86, 0x2000
	s_nop 0
	global_load_lds_dwordx4 v[198:199], off
	v_lshl_add_u64 v[198:199], s[40:41], 0, v[236:237]
	s_mov_b32 m0, s36
	s_nop 0
	global_load_lds_dwordx4 v[198:199], off
	s_mov_b32 m0, s37
	s_nop 0
	global_load_lds_dwordx4 v[200:201], off
	s_waitcnt vmcnt(8)
	s_waitcnt lgkmcnt(0)
	s_barrier
	s_waitcnt lgkmcnt(0)
	v_mfma_f32_16x16x32_bf16 v[54:57], v[126:129], v[162:165], v[54:57]
	v_mfma_f32_16x16x32_bf16 v[50:53], v[138:141], v[162:165], v[50:53]
	v_mfma_f32_16x16x32_bf16 v[38:41], v[126:129], v[170:173], v[38:41]
	v_mfma_f32_16x16x32_bf16 v[30:33], v[138:141], v[170:173], v[30:33]
	v_mfma_f32_16x16x32_bf16 v[86:89], v[126:129], v[178:181], v[86:89]
	v_mfma_f32_16x16x32_bf16 v[122:125], v[138:141], v[178:181], v[122:125]
	v_mfma_f32_16x16x32_bf16 v[114:117], v[126:129], v[186:189], v[114:117]
	v_mfma_f32_16x16x32_bf16 v[106:109], v[138:141], v[186:189], v[106:109]
	v_mfma_f32_16x16x32_bf16 v[54:57], v[134:137], v[166:169], v[54:57]
	v_mfma_f32_16x16x32_bf16 v[50:53], v[142:145], v[166:169], v[50:53]
	v_mfma_f32_16x16x32_bf16 v[38:41], v[134:137], v[174:177], v[38:41]
	v_mfma_f32_16x16x32_bf16 v[30:33], v[142:145], v[174:177], v[30:33]
	v_mfma_f32_16x16x32_bf16 v[86:89], v[134:137], v[182:185], v[86:89]
	v_mfma_f32_16x16x32_bf16 v[122:125], v[142:145], v[182:185], v[122:125]
	v_mfma_f32_16x16x32_bf16 v[114:117], v[134:137], v[190:193], v[114:117]
	v_mfma_f32_16x16x32_bf16 v[106:109], v[142:145], v[190:193], v[106:109]
	v_mfma_f32_16x16x32_bf16 v[22:25], v[146:149], v[162:165], v[22:25]
	v_mfma_f32_16x16x32_bf16 v[18:21], v[154:157], v[162:165], v[18:21]
	v_mfma_f32_16x16x32_bf16 v[10:13], v[146:149], v[170:173], v[10:13]
	v_mfma_f32_16x16x32_bf16 v[6:9], v[154:157], v[170:173], v[6:9]
	v_mfma_f32_16x16x32_bf16 v[82:85], v[146:149], v[178:181], v[82:85]
	v_mfma_f32_16x16x32_bf16 v[94:97], v[154:157], v[178:181], v[94:97]
	v_mfma_f32_16x16x32_bf16 v[70:73], v[146:149], v[186:189], v[70:73]
	v_mfma_f32_16x16x32_bf16 v[66:69], v[154:157], v[186:189], v[66:69]
	v_mfma_f32_16x16x32_bf16 v[22:25], v[150:153], v[166:169], v[22:25]
	v_mfma_f32_16x16x32_bf16 v[18:21], v[158:161], v[166:169], v[18:21]
	v_mfma_f32_16x16x32_bf16 v[10:13], v[150:153], v[174:177], v[10:13]
	v_mfma_f32_16x16x32_bf16 v[6:9], v[158:161], v[174:177], v[6:9]
	v_mfma_f32_16x16x32_bf16 v[82:85], v[150:153], v[182:185], v[82:85]
	v_mfma_f32_16x16x32_bf16 v[94:97], v[158:161], v[182:185], v[94:97]
	v_mfma_f32_16x16x32_bf16 v[70:73], v[150:153], v[190:193], v[70:73]
	v_mfma_f32_16x16x32_bf16 v[66:69], v[158:161], v[190:193], v[66:69]
	s_barrier
; #define PG8_STAGE(bufoff, gbase, voff) do { _Pragma("unroll") for (int _i = 0; _i < 2; ++_i) \
;         __builtin_amdgcn_global_load_lds((const unsigned*)((const char*)(gbase) + (voff)[_i]), (PG8_LAS unsigned*)(lds + (bufoff) + ldsw + _i * 8192), 16, 0, 0); } while (0)
; #define PG8_LDA(dst, b, h) do { _Pragma("unroll") for (int m = 0; m < 4; ++m) _Pragma("unroll") for (int k = 0; k < 2; ++k) dst[m][k] = *(const PG8_LAS bf16x8*)(lds + PG8_SA(b, h) + aoff + m * 2048 + k * 1024); } while (0)
; #define PG8_LDB(dst, b, h) do { _Pragma("unroll") for (int n = 0; n < 2; ++n) _Pragma("unroll") for (int k = 0; k < 2; ++k) dst[n][k] = *(const PG8_LAS bf16x8*)(lds + PG8_SB(b, h) + boff + n * 2048 + k * 1024); } while (0)
; #define PG8_MMA(ai, bj, At, Bt) do { __builtin_amdgcn_s_setprio(1); _Pragma("unroll") for (int m = 0; m < 4; ++m) _Pragma("unroll") for (int n = 0; n < 2; ++n) _Pragma("unroll") for (int k = 0; k < 2; ++k) \
;         acc[ai][bj][m][n] = __builtin_amdgcn_mfma_f32_16x16x32_bf16(Bt[n][k], At[m][k], acc[ai][bj][m][n], 0, 0, 0); __builtin_amdgcn_s_setprio(0); } while (0)
; #define PG8_WAIT_V(n) asm volatile("s_waitcnt vmcnt(" #n ")" ::: "memory")
; #define PG8_WAIT_L(n) asm volatile("s_waitcnt lgkmcnt(" #n ")" ::: "memory")
; #define PG8_BAR __builtin_amdgcn_s_barrier()
; #define PG8_SCHED __builtin_amdgcn_sched_barrier(0)
; template <class Epi, class Sched, bool ALIGN_EPI = false, bool SP2 = false>
; __device__ __forceinline__ void gemm_phase(PG8_LAS unsigned char* lds, const Gemm g, const Sched& S, const Epi& E, int wave_s) {
;     ...
;             PG8_LDB(B0, 1, 0); PG8_LDB(B1, 1, 1); PG8_SCHED; PG8_LDA(At, 1, 0); PG8_STAGE(PG8_SA(0, 1), a2 + hstepA, voffA);
;             PG8_WAIT_V(8); PG8_WAIT_L(0); PG8_BAR; PG8_MMA(0, 0, At, B0); PG8_MMA(0, 1, At, B1); PG8_BAR; PG8_SCHED;
	s_add_i32 s86, 0, 0x18000
	s_add_i32 s87, 0, 0x1c000
	v_add_u32_e32 v142, s86, v251
	v_add_u32_e32 v158, s87, v251
	ds_read_b128 v[126:129], v142
	ds_read_b128 v[134:137], v142 offset:1024
	ds_read_b128 v[138:141], v142 offset:2048
	ds_read_b128 v[142:145], v142 offset:3072
	ds_read_b128 v[146:149], v158
	ds_read_b128 v[150:153], v158 offset:1024
	ds_read_b128 v[154:157], v158 offset:2048
	ds_read_b128 v[158:161], v158 offset:3072
	s_add_u32 s30, s40, 0x4000
	s_addc_u32 s31, s41, 0
	s_mov_b32 m0, s42
	v_lshl_add_u64 v[202:203], s[30:31], 0, v[236:237]
	ds_read_b128 v[162:165], v252 offset:32768
	ds_read_b128 v[166:169], v252 offset:33792
	ds_read_b128 v[170:173], v252 offset:34816
	ds_read_b128 v[174:177], v252 offset:35840
	ds_read_b128 v[178:181], v252 offset:36864
	ds_read_b128 v[182:185], v252 offset:37888
	ds_read_b128 v[186:189], v252 offset:38912
	ds_read_b128 v[190:193], v252 offset:39936
	global_load_lds_dwordx4 v[202:203], off
	v_lshl_add_u64 v[202:203], s[30:31], 0, v[240:241]
	s_mov_b32 m0, s43
	s_nop 0
	global_load_lds_dwordx4 v[202:203], off
	s_waitcnt vmcnt(8)
	s_waitcnt lgkmcnt(0)
	s_barrier
	s_waitcnt lgkmcnt(0)
	v_mfma_f32_16x16x32_bf16 v[130:133], v[126:129], v[162:165], v[130:133]
	v_mfma_f32_16x16x32_bf16 v[118:121], v[138:141], v[162:165], v[118:121]
	v_mfma_f32_16x16x32_bf16 v[110:113], v[126:129], v[170:173], v[110:113]
	v_mfma_f32_16x16x32_bf16 v[98:101], v[138:141], v[170:173], v[98:101]
	v_mfma_f32_16x16x32_bf16 v[62:65], v[126:129], v[178:181], v[62:65]
	v_mfma_f32_16x16x32_bf16 v[58:61], v[138:141], v[178:181], v[58:61]
	v_mfma_f32_16x16x32_bf16 v[46:49], v[126:129], v[186:189], v[46:49]
	v_mfma_f32_16x16x32_bf16 v[42:45], v[138:141], v[186:189], v[42:45]
	v_mfma_f32_16x16x32_bf16 v[130:133], v[134:137], v[166:169], v[130:133]
	v_mfma_f32_16x16x32_bf16 v[118:121], v[142:145], v[166:169], v[118:121]
	v_mfma_f32_16x16x32_bf16 v[110:113], v[134:137], v[174:177], v[110:113]
	v_mfma_f32_16x16x32_bf16 v[98:101], v[142:145], v[174:177], v[98:101]
	v_mfma_f32_16x16x32_bf16 v[62:65], v[134:137], v[182:185], v[62:65]
	v_mfma_f32_16x16x32_bf16 v[58:61], v[142:145], v[182:185], v[58:61]
	v_mfma_f32_16x16x32_bf16 v[46:49], v[134:137], v[190:193], v[46:49]
	v_mfma_f32_16x16x32_bf16 v[42:45], v[142:145], v[190:193], v[42:45]
	v_mfma_f32_16x16x32_bf16 v[102:105], v[146:149], v[162:165], v[102:105]
	v_mfma_f32_16x16x32_bf16 v[74:77], v[154:157], v[162:165], v[74:77]
	v_mfma_f32_16x16x32_bf16 v[78:81], v[146:149], v[170:173], v[78:81]
	v_mfma_f32_16x16x32_bf16 v[90:93], v[154:157], v[170:173], v[90:93]
	v_mfma_f32_16x16x32_bf16 v[34:37], v[146:149], v[178:181], v[34:37]
	v_mfma_f32_16x16x32_bf16 v[26:29], v[154:157], v[178:181], v[26:29]
	v_mfma_f32_16x16x32_bf16 v[14:17], v[146:149], v[186:189], v[14:17]
	v_mfma_f32_16x16x32_bf16 v[2:5], v[154:157], v[186:189], v[2:5]
	v_mfma_f32_16x16x32_bf16 v[102:105], v[150:153], v[166:169], v[102:105]
	v_mfma_f32_16x16x32_bf16 v[74:77], v[158:161], v[166:169], v[74:77]
	v_mfma_f32_16x16x32_bf16 v[78:81], v[150:153], v[174:177], v[78:81]
	v_mfma_f32_16x16x32_bf16 v[90:93], v[158:161], v[174:177], v[90:93]
	v_mfma_f32_16x16x32_bf16 v[34:37], v[150:153], v[182:185], v[34:37]
	v_mfma_f32_16x16x32_bf16 v[26:29], v[158:161], v[182:185], v[26:29]
	v_mfma_f32_16x16x32_bf16 v[14:17], v[150:153], v[190:193], v[14:17]
	v_mfma_f32_16x16x32_bf16 v[2:5], v[158:161], v[190:193], v[2:5]
	s_barrier
; #define PG8_STAGE(bufoff, gbase, voff) do { _Pragma("unroll") for (int _i = 0; _i < 2; ++_i) \
;         __builtin_amdgcn_global_load_lds((const unsigned*)((const char*)(gbase) + (voff)[_i]), (PG8_LAS unsigned*)(lds + (bufoff) + ldsw + _i * 8192), 16, 0, 0); } while (0)
; #define PG8_LDA(dst, b, h) do { _Pragma("unroll") for (int m = 0; m < 4; ++m) _Pragma("unroll") for (int k = 0; k < 2; ++k) dst[m][k] = *(const PG8_LAS bf16x8*)(lds + PG8_SA(b, h) + aoff + m * 2048 + k * 1024); } while (0)
; #define PG8_MMA(ai, bj, At, Bt) do { __builtin_amdgcn_s_setprio(1); _Pragma("unroll") for (int m = 0; m < 4; ++m) _Pragma("unroll") for (int n = 0; n < 2; ++n) _Pragma("unroll") for (int k = 0; k < 2; ++k) \
;         acc[ai][bj][m][n] = __builtin_amdgcn_mfma_f32_16x16x32_bf16(Bt[n][k], At[m][k], acc[ai][bj][m][n], 0, 0, 0); __builtin_amdgcn_s_setprio(0); } while (0)
; #define PG8_WAIT_V(n) asm volatile("s_waitcnt vmcnt(" #n ")" ::: "memory")
; #define PG8_WAIT_L(n) asm volatile("s_waitcnt lgkmcnt(" #n ")" ::: "memory")
; #define PG8_BAR __builtin_amdgcn_s_barrier()
; #define PG8_SCHED __builtin_amdgcn_sched_barrier(0)
; template <class Epi, class Sched, bool ALIGN_EPI = false, bool SP2 = false>
; __device__ __forceinline__ void gemm_phase(PG8_LAS unsigned char* lds, const Gemm g, const Sched& S, const Epi& E, int wave_s) {
;     ...
;             PG8_LDA(At, 1, 1); PG8_STAGE(PG8_SB(1, 0), b3, voffB); PG8_STAGE(PG8_SB(1, 1), b3 + hstepB, voffB); PG8_STAGE(PG8_SA(1, 0), a3, voffA);
;             PG8_WAIT_V(8); PG8_WAIT_L(0); PG8_BAR; PG8_MMA(1, 0, At, B0); PG8_MMA(1, 1, At, B1); PG8_BAR; PG8_SCHED;
;     ...
;         if constexpr (ALIGN_EPI) { if (wr == 0) PG8_BAR; }
	s_add_i32 s30, s86, s35
	v_lshl_add_u64 v[194:195], v[194:195], 0, s[60:61]
	s_mov_b32 m0, s30
	ds_read_b128 v[162:165], v252 offset:49152
	ds_read_b128 v[166:169], v252 offset:50176
	ds_read_b128 v[170:173], v252 offset:51200
	ds_read_b128 v[174:177], v252 offset:52224
	ds_read_b128 v[178:181], v252 offset:53248
	ds_read_b128 v[182:185], v252 offset:54272
	ds_read_b128 v[186:189], v252 offset:55296
	ds_read_b128 v[190:193], v252 offset:56320
	global_load_lds_dwordx4 v[194:195], off
	s_add_i32 m0, s30, 0x2000
	s_add_u32 s6, s6, 0x80080
	v_lshl_add_u64 v[194:195], v[196:197], 0, s[60:61]
	s_addc_u32 s7, s7, 0
	s_add_i32 s30, s87, s35
	global_load_lds_dwordx4 v[194:195], off
	v_lshl_add_u64 v[194:195], s[6:7], 0, v[238:239]
	s_mov_b32 m0, s30
	s_nop 0
	global_load_lds_dwordx4 v[194:195], off
	v_lshl_add_u64 v[194:195], s[6:7], 0, v[242:243]
	s_add_i32 m0, s30, 0x2000
	s_nop 0
	global_load_lds_dwordx4 v[194:195], off
	v_lshl_add_u64 v[194:195], v[198:199], 0, s[60:61]
	s_mov_b32 m0, s77
	s_nop 0
	global_load_lds_dwordx4 v[194:195], off
	v_lshl_add_u64 v[194:195], v[200:201], 0, s[60:61]
	s_mov_b32 m0, s94
	s_nop 0
	global_load_lds_dwordx4 v[194:195], off
	s_waitcnt vmcnt(8)
	s_waitcnt lgkmcnt(0)
	s_barrier
	s_waitcnt lgkmcnt(0)
	v_mfma_f32_16x16x32_bf16 v[54:57], v[126:129], v[162:165], v[54:57]
	v_mfma_f32_16x16x32_bf16 v[50:53], v[138:141], v[162:165], v[50:53]
	v_mfma_f32_16x16x32_bf16 v[38:41], v[126:129], v[170:173], v[38:41]
	v_mfma_f32_16x16x32_bf16 v[30:33], v[138:141], v[170:173], v[30:33]
	v_mfma_f32_16x16x32_bf16 v[86:89], v[126:129], v[178:181], v[86:89]
	v_mfma_f32_16x16x32_bf16 v[122:125], v[138:141], v[178:181], v[122:125]
	v_mfma_f32_16x16x32_bf16 v[114:117], v[126:129], v[186:189], v[114:117]
	v_mfma_f32_16x16x32_bf16 v[106:109], v[138:141], v[186:189], v[106:109]
	v_mfma_f32_16x16x32_bf16 v[54:57], v[134:137], v[166:169], v[54:57]
	v_mfma_f32_16x16x32_bf16 v[50:53], v[142:145], v[166:169], v[50:53]
	v_mfma_f32_16x16x32_bf16 v[38:41], v[134:137], v[174:177], v[38:41]
	v_mfma_f32_16x16x32_bf16 v[30:33], v[142:145], v[174:177], v[30:33]
	v_mfma_f32_16x16x32_bf16 v[86:89], v[134:137], v[182:185], v[86:89]
	v_mfma_f32_16x16x32_bf16 v[122:125], v[142:145], v[182:185], v[122:125]
	v_mfma_f32_16x16x32_bf16 v[114:117], v[134:137], v[190:193], v[114:117]
	v_mfma_f32_16x16x32_bf16 v[106:109], v[142:145], v[190:193], v[106:109]
	v_mfma_f32_16x16x32_bf16 v[22:25], v[146:149], v[162:165], v[22:25]
	v_mfma_f32_16x16x32_bf16 v[18:21], v[154:157], v[162:165], v[18:21]
	v_mfma_f32_16x16x32_bf16 v[10:13], v[146:149], v[170:173], v[10:13]
	v_mfma_f32_16x16x32_bf16 v[6:9], v[154:157], v[170:173], v[6:9]
	v_mfma_f32_16x16x32_bf16 v[82:85], v[146:149], v[178:181], v[82:85]
	v_mfma_f32_16x16x32_bf16 v[94:97], v[154:157], v[178:181], v[94:97]
	v_mfma_f32_16x16x32_bf16 v[70:73], v[146:149], v[186:189], v[70:73]
	v_mfma_f32_16x16x32_bf16 v[66:69], v[154:157], v[186:189], v[66:69]
	v_mfma_f32_16x16x32_bf16 v[22:25], v[150:153], v[166:169], v[22:25]
	v_mfma_f32_16x16x32_bf16 v[18:21], v[158:161], v[166:169], v[18:21]
	v_mfma_f32_16x16x32_bf16 v[10:13], v[150:153], v[174:177], v[10:13]
	v_mfma_f32_16x16x32_bf16 v[6:9], v[158:161], v[174:177], v[6:9]
	v_mfma_f32_16x16x32_bf16 v[82:85], v[150:153], v[182:185], v[82:85]
	v_mfma_f32_16x16x32_bf16 v[94:97], v[158:161], v[182:185], v[94:97]
	v_mfma_f32_16x16x32_bf16 v[70:73], v[150:153], v[190:193], v[70:73]
	v_mfma_f32_16x16x32_bf16 v[66:69], v[158:161], v[190:193], v[66:69]
	s_barrier
	s_add_i32 vcc_lo, vcc_lo, 2
	s_add_u32 s89, s89, 0x100
	s_addc_u32 s91, s91, 0
	s_cmp_gt_u32 vcc_lo, 29
	s_mov_b64 s[30:31], s[4:5]
	s_cbranch_scc0 .LBB0_691
	s_and_b64 vcc, exec, s[26:27]
	s_cbranch_vccz .LBB0_694
	s_barrier

; #define PG8_STAGE(bufoff, gbase, voff) do { _Pragma("unroll") for (int _i = 0; _i < 2; ++_i) \
;         __builtin_amdgcn_global_load_lds((const unsigned*)((const char*)(gbase) + (voff)[_i]), (PG8_LAS unsigned*)(lds + (bufoff) + ldsw + _i * 8192), 16, 0, 0); } while (0)
; #define PG8_LDA(dst, b, h) do { _Pragma("unroll") for (int m = 0; m < 4; ++m) _Pragma("unroll") for (int k = 0; k < 2; ++k) dst[m][k] = *(const PG8_LAS bf16x8*)(lds + PG8_SA(b, h) + aoff + m * 2048 + k * 1024); } while (0)
; #define PG8_LDB(dst, b, h) do { _Pragma("unroll") for (int n = 0; n < 2; ++n) _Pragma("unroll") for (int k = 0; k < 2; ++k) dst[n][k] = *(const PG8_LAS bf16x8*)(lds + PG8_SB(b, h) + boff + n * 2048 + k * 1024); } while (0)
; #define PG8_MMA(ai, bj, At, Bt) do { __builtin_amdgcn_s_setprio(1); _Pragma("unroll") for (int m = 0; m < 4; ++m) _Pragma("unroll") for (int n = 0; n < 2; ++n) _Pragma("unroll") for (int k = 0; k < 2; ++k) \
;         acc[ai][bj][m][n] = __builtin_amdgcn_mfma_f32_16x16x32_bf16(Bt[n][k], At[m][k], acc[ai][bj][m][n], 0, 0, 0); __builtin_amdgcn_s_setprio(0); } while (0)
; #define PG8_BAR __builtin_amdgcn_s_barrier()
; template <class Epi, class Sched, bool ALIGN_EPI = false, bool SP2 = false>
; __device__ __forceinline__ void gemm_phase(PG8_LAS unsigned char* lds, const Gemm g, const Sched& S, const Epi& E, int wave_s) {
;     ...
;         const char* nA = has_next ? (const char*)g.A + (size_t)nxt.pm * tstepA + (size_t)(nxt.pn / g.npg) * (size_t)(K * 2) : cA; const char* nB = has_next ? (const char*)g.Bt + (size_t)nxt.pn * tstepB : cB;
;         for (int t = 0; t < nt; t += 2) {
;             const bool last = (t == nt - 2);
;             const char* a1 = cA + (size_t)(t + 1) * kstep;
;             const char* a2 = last ? nA : cA + (size_t)(t + 2) * kstep; const char* b2 = last ? nB : cB + (size_t)(t + 2) * kstep;
;             const char* a3 = a2 + kstep; const char* b3 = b2 + kstep;
;             if (last && has_next) S.a_ready(nxt);
;             if constexpr (SP2) {
;             PG8_LDB(B0, 0, 0); PG8_LDB(B1, 0, 1); PG8_SCHED; PG8_LDA(At, 0, 0); PG8_STAGE(PG8_SA(1, 1), a1 + hstepA, voffA);
;             PG8_WAIT_V(8); PG8_WAIT_L(0); PG8_BAR; PG8_MMA(0, 0, At, B0); PG8_MMA(0, 1, At, B1); PG8_BAR; PG8_SCHED;
;             PG8_LDA(At, 0, 1); PG8_STAGE(PG8_SB(0, 0), b2, voffB); PG8_STAGE(PG8_SB(0, 1), b2 + hstepB, voffB); PG8_STAGE(PG8_SA(0, 0), a2, voffA);
.LBB0_785:
	s_add_u32 s2, s30, 0x100
	s_addc_u32 s3, s31, 0
	s_mov_b32 s81, -2
	s_add_u32 s4, s8, 0x100
	s_addc_u32 s5, s9, 0
	s_add_i32 s84, 0, 0x10000
	s_cmpk_eq_i32 s81, 0x54
	s_cselect_b32 s31, s95, s5
	s_cselect_b32 s30, s94, s4
	s_cselect_b32 s7, s97, s3
	s_cselect_b32 s6, s96, s2
	s_add_i32 s85, 0, 0x14000
	v_add_u32_e32 v110, s84, v211
	v_add_u32_e32 v150, s85, v211
	ds_read_b128 v[78:81], v110
	ds_read_b128 v[86:89], v110 offset:1024
	ds_read_b128 v[102:105], v110 offset:2048
	ds_read_b128 v[110:113], v110 offset:3072
	ds_read_b128 v[122:125], v150
	ds_read_b128 v[134:137], v150 offset:1024
	ds_read_b128 v[146:149], v150 offset:2048
	ds_read_b128 v[150:153], v150 offset:3072
	v_lshl_add_u64 v[206:207], s[8:9], 0, v[198:199]
	s_add_i32 m0, s35, 0xc000
	ds_read_b128 v[162:165], v212
	ds_read_b128 v[166:169], v212 offset:1024
	ds_read_b128 v[170:173], v212 offset:2048
	ds_read_b128 v[174:177], v212 offset:3072
	ds_read_b128 v[178:181], v212 offset:4096
	ds_read_b128 v[182:185], v212 offset:5120
	ds_read_b128 v[186:189], v212 offset:6144
	ds_read_b128 v[202:205], v212 offset:7168
	global_load_lds_dwordx4 v[206:207], off
	v_lshl_add_u64 v[206:207], s[8:9], 0, v[200:201]
	s_add_i32 m0, s35, 0xe000
	s_nop 0
	global_load_lds_dwordx4 v[206:207], off
	s_waitcnt vmcnt(8)
	s_waitcnt lgkmcnt(0)
	s_barrier
	s_waitcnt lgkmcnt(0)
	v_mfma_f32_16x16x32_bf16 v[158:161], v[78:81], v[162:165], 0
	v_mfma_f32_16x16x32_bf16 v[154:157], v[102:105], v[162:165], 0
	v_mfma_f32_16x16x32_bf16 v[130:133], v[78:81], v[170:173], 0
	v_mfma_f32_16x16x32_bf16 v[126:129], v[102:105], v[170:173], 0
	v_mfma_f32_16x16x32_bf16 v[106:109], v[78:81], v[178:181], 0
	v_mfma_f32_16x16x32_bf16 v[98:101], v[102:105], v[178:181], 0
	v_mfma_f32_16x16x32_bf16 v[82:85], v[78:81], v[186:189], 0
	v_mfma_f32_16x16x32_bf16 v[74:77], v[102:105], v[186:189], 0
	v_mfma_f32_16x16x32_bf16 v[158:161], v[86:89], v[166:169], v[158:161]
	v_mfma_f32_16x16x32_bf16 v[154:157], v[110:113], v[166:169], v[154:157]
	v_mfma_f32_16x16x32_bf16 v[130:133], v[86:89], v[174:177], v[130:133]
	v_mfma_f32_16x16x32_bf16 v[126:129], v[110:113], v[174:177], v[126:129]
	v_mfma_f32_16x16x32_bf16 v[106:109], v[86:89], v[182:185], v[106:109]
	v_mfma_f32_16x16x32_bf16 v[98:101], v[110:113], v[182:185], v[98:101]
	v_mfma_f32_16x16x32_bf16 v[82:85], v[86:89], v[202:205], v[82:85]
	v_mfma_f32_16x16x32_bf16 v[74:77], v[110:113], v[202:205], v[74:77]
	v_mfma_f32_16x16x32_bf16 v[142:145], v[122:125], v[162:165], 0
	v_mfma_f32_16x16x32_bf16 v[138:141], v[146:149], v[162:165], 0
	v_mfma_f32_16x16x32_bf16 v[118:121], v[122:125], v[170:173], 0
	v_mfma_f32_16x16x32_bf16 v[114:117], v[146:149], v[170:173], 0
	v_mfma_f32_16x16x32_bf16 v[94:97], v[122:125], v[178:181], 0
	v_mfma_f32_16x16x32_bf16 v[90:93], v[146:149], v[178:181], 0
	v_mfma_f32_16x16x32_bf16 v[70:73], v[122:125], v[186:189], 0
	v_mfma_f32_16x16x32_bf16 v[66:69], v[146:149], v[186:189], 0
	v_mfma_f32_16x16x32_bf16 v[142:145], v[134:137], v[166:169], v[142:145]
	v_mfma_f32_16x16x32_bf16 v[138:141], v[150:153], v[166:169], v[138:141]
	v_mfma_f32_16x16x32_bf16 v[118:121], v[134:137], v[174:177], v[118:121]
	v_mfma_f32_16x16x32_bf16 v[114:117], v[150:153], v[174:177], v[114:117]
	v_mfma_f32_16x16x32_bf16 v[94:97], v[134:137], v[182:185], v[94:97]
	v_mfma_f32_16x16x32_bf16 v[90:93], v[150:153], v[182:185], v[90:93]
	v_mfma_f32_16x16x32_bf16 v[70:73], v[134:137], v[202:205], v[70:73]
	v_mfma_f32_16x16x32_bf16 v[66:69], v[150:153], v[202:205], v[66:69]
	s_barrier
	s_add_i32 s8, s84, s22
	v_lshl_add_u64 v[206:207], s[6:7], 0, v[194:195]
	s_mov_b32 m0, s8
	ds_read_b128 v[162:165], v212 offset:16384
	ds_read_b128 v[166:169], v212 offset:17408
	ds_read_b128 v[170:173], v212 offset:18432
	ds_read_b128 v[174:177], v212 offset:19456
	ds_read_b128 v[178:181], v212 offset:20480
	ds_read_b128 v[182:185], v212 offset:21504
	ds_read_b128 v[186:189], v212 offset:22528
	ds_read_b128 v[202:205], v212 offset:23552
	global_load_lds_dwordx4 v[206:207], off
	s_add_i32 m0, s8, 0x2000
	s_add_u32 s8, s6, 0x160000
	v_lshl_add_u64 v[208:209], s[6:7], 0, v[190:191]
	s_addc_u32 s9, s7, 0
	s_add_i32 s84, s85, s22
	global_load_lds_dwordx4 v[208:209], off
	v_lshl_add_u64 v[214:215], s[8:9], 0, v[194:195]
	s_mov_b32 m0, s84
	v_lshl_add_u64 v[216:217], s[30:31], 0, v[192:193]
	global_load_lds_dwordx4 v[214:215], off
	v_lshl_add_u64 v[214:215], s[8:9], 0, v[190:191]
	s_add_i32 m0, s84, 0x2000
	s_nop 0
	global_load_lds_dwordx4 v[214:215], off
	v_lshl_add_u64 v[214:215], s[30:31], 0, v[196:197]
	s_mov_b32 m0, s35
	s_nop 0
	global_load_lds_dwordx4 v[214:215], off
	s_mov_b32 m0, s36
	s_nop 0
	global_load_lds_dwordx4 v[216:217], off
	s_waitcnt vmcnt(8)
	s_waitcnt lgkmcnt(0)
	s_barrier
; #define PG8_STAGE(bufoff, gbase, voff) do { _Pragma("unroll") for (int _i = 0; _i < 2; ++_i) \
;         __builtin_amdgcn_global_load_lds((const unsigned*)((const char*)(gbase) + (voff)[_i]), (PG8_LAS unsigned*)(lds + (bufoff) + ldsw + _i * 8192), 16, 0, 0); } while (0)
; #define PG8_LDA(dst, b, h) do { _Pragma("unroll") for (int m = 0; m < 4; ++m) _Pragma("unroll") for (int k = 0; k < 2; ++k) dst[m][k] = *(const PG8_LAS bf16x8*)(lds + PG8_SA(b, h) + aoff + m * 2048 + k * 1024); } while (0)
; #define PG8_LDB(dst, b, h) do { _Pragma("unroll") for (int n = 0; n < 2; ++n) _Pragma("unroll") for (int k = 0; k < 2; ++k) dst[n][k] = *(const PG8_LAS bf16x8*)(lds + PG8_SB(b, h) + boff + n * 2048 + k * 1024); } while (0)
; #define PG8_MMA(ai, bj, At, Bt) do { __builtin_amdgcn_s_setprio(1); _Pragma("unroll") for (int m = 0; m < 4; ++m) _Pragma("unroll") for (int n = 0; n < 2; ++n) _Pragma("unroll") for (int k = 0; k < 2; ++k) \
;         acc[ai][bj][m][n] = __builtin_amdgcn_mfma_f32_16x16x32_bf16(Bt[n][k], At[m][k], acc[ai][bj][m][n], 0, 0, 0); __builtin_amdgcn_s_setprio(0); } while (0)
; #define PG8_WAIT_V(n) asm volatile("s_waitcnt vmcnt(" #n ")" ::: "memory")
; #define PG8_WAIT_L(n) asm volatile("s_waitcnt lgkmcnt(" #n ")" ::: "memory")
; #define PG8_BAR __builtin_amdgcn_s_barrier()
; #define PG8_SCHED __builtin_amdgcn_sched_barrier(0)
; template <class Epi, class Sched, bool ALIGN_EPI = false, bool SP2 = false>
; __device__ __forceinline__ void gemm_phase(PG8_LAS unsigned char* lds, const Gemm g, const Sched& S, const Epi& E, int wave_s) {
;     ...
;             PG8_WAIT_V(8); PG8_WAIT_L(0); PG8_BAR; PG8_MMA(1, 0, At, B0); PG8_MMA(1, 1, At, B1); PG8_BAR; PG8_SCHED;
;             PG8_LDB(B0, 1, 0); PG8_LDB(B1, 1, 1); PG8_SCHED; PG8_LDA(At, 1, 0); PG8_STAGE(PG8_SA(0, 1), a2 + hstepA, voffA);
;             PG8_WAIT_V(8); PG8_WAIT_L(0); PG8_BAR; PG8_MMA(0, 0, At, B0); PG8_MMA(0, 1, At, B1); PG8_BAR; PG8_SCHED;
	s_waitcnt lgkmcnt(0)
	v_mfma_f32_16x16x32_bf16 v[62:65], v[78:81], v[162:165], 0
	v_mfma_f32_16x16x32_bf16 v[58:61], v[102:105], v[162:165], 0
	v_mfma_f32_16x16x32_bf16 v[46:49], v[78:81], v[170:173], 0
	v_mfma_f32_16x16x32_bf16 v[42:45], v[102:105], v[170:173], 0
	v_mfma_f32_16x16x32_bf16 v[30:33], v[78:81], v[178:181], 0
	v_mfma_f32_16x16x32_bf16 v[26:29], v[102:105], v[178:181], 0
	v_mfma_f32_16x16x32_bf16 v[14:17], v[78:81], v[186:189], 0
	v_mfma_f32_16x16x32_bf16 v[10:13], v[102:105], v[186:189], 0
	v_mfma_f32_16x16x32_bf16 v[62:65], v[86:89], v[166:169], v[62:65]
	v_mfma_f32_16x16x32_bf16 v[58:61], v[110:113], v[166:169], v[58:61]
	v_mfma_f32_16x16x32_bf16 v[46:49], v[86:89], v[174:177], v[46:49]
	v_mfma_f32_16x16x32_bf16 v[42:45], v[110:113], v[174:177], v[42:45]
	v_mfma_f32_16x16x32_bf16 v[30:33], v[86:89], v[182:185], v[30:33]
	v_mfma_f32_16x16x32_bf16 v[26:29], v[110:113], v[182:185], v[26:29]
	v_mfma_f32_16x16x32_bf16 v[14:17], v[86:89], v[202:205], v[14:17]
	v_mfma_f32_16x16x32_bf16 v[10:13], v[110:113], v[202:205], v[10:13]
	v_mfma_f32_16x16x32_bf16 v[54:57], v[122:125], v[162:165], 0
	v_mfma_f32_16x16x32_bf16 v[50:53], v[146:149], v[162:165], 0
	v_mfma_f32_16x16x32_bf16 v[38:41], v[122:125], v[170:173], 0
	v_mfma_f32_16x16x32_bf16 v[34:37], v[146:149], v[170:173], 0
	v_mfma_f32_16x16x32_bf16 v[22:25], v[122:125], v[178:181], 0
	v_mfma_f32_16x16x32_bf16 v[18:21], v[146:149], v[178:181], 0
	v_mfma_f32_16x16x32_bf16 v[6:9], v[122:125], v[186:189], 0
	v_mfma_f32_16x16x32_bf16 v[2:5], v[146:149], v[186:189], 0
	v_mfma_f32_16x16x32_bf16 v[54:57], v[134:137], v[166:169], v[54:57]
	v_mfma_f32_16x16x32_bf16 v[50:53], v[150:153], v[166:169], v[50:53]
	v_mfma_f32_16x16x32_bf16 v[38:41], v[134:137], v[174:177], v[38:41]
	v_mfma_f32_16x16x32_bf16 v[34:37], v[150:153], v[174:177], v[34:37]
	v_mfma_f32_16x16x32_bf16 v[22:25], v[134:137], v[182:185], v[22:25]
	v_mfma_f32_16x16x32_bf16 v[18:21], v[150:153], v[182:185], v[18:21]
	v_mfma_f32_16x16x32_bf16 v[6:9], v[134:137], v[202:205], v[6:9]
	v_mfma_f32_16x16x32_bf16 v[2:5], v[150:153], v[202:205], v[2:5]
	s_barrier
	s_add_i32 s84, 0, 0x18000
	s_add_i32 s85, 0, 0x1c000
	v_add_u32_e32 v110, s84, v211
	v_add_u32_e32 v150, s85, v211
	ds_read_b128 v[78:81], v110
	ds_read_b128 v[86:89], v110 offset:1024
	ds_read_b128 v[102:105], v110 offset:2048
	ds_read_b128 v[110:113], v110 offset:3072
	ds_read_b128 v[122:125], v150
	ds_read_b128 v[134:137], v150 offset:1024
	ds_read_b128 v[146:149], v150 offset:2048
	ds_read_b128 v[150:153], v150 offset:3072
	s_add_u32 s8, s30, 0x160000
	s_addc_u32 s9, s31, 0
	s_mov_b32 m0, s37
	v_lshl_add_u64 v[218:219], s[8:9], 0, v[196:197]
	ds_read_b128 v[162:165], v212 offset:32768
	ds_read_b128 v[166:169], v212 offset:33792
	ds_read_b128 v[170:173], v212 offset:34816
	ds_read_b128 v[174:177], v212 offset:35840
	ds_read_b128 v[178:181], v212 offset:36864
	ds_read_b128 v[182:185], v212 offset:37888
	ds_read_b128 v[186:189], v212 offset:38912
	ds_read_b128 v[202:205], v212 offset:39936
	global_load_lds_dwordx4 v[218:219], off
	v_lshl_add_u64 v[218:219], s[8:9], 0, v[192:193]
	s_mov_b32 m0, s40
	s_nop 0
	global_load_lds_dwordx4 v[218:219], off
	s_waitcnt vmcnt(8)
	s_waitcnt lgkmcnt(0)
	s_barrier
	s_waitcnt lgkmcnt(0)
	v_mfma_f32_16x16x32_bf16 v[158:161], v[78:81], v[162:165], v[158:161]
	v_mfma_f32_16x16x32_bf16 v[154:157], v[102:105], v[162:165], v[154:157]
	v_mfma_f32_16x16x32_bf16 v[130:133], v[78:81], v[170:173], v[130:133]
	v_mfma_f32_16x16x32_bf16 v[126:129], v[102:105], v[170:173], v[126:129]
	v_mfma_f32_16x16x32_bf16 v[106:109], v[78:81], v[178:181], v[106:109]
	v_mfma_f32_16x16x32_bf16 v[98:101], v[102:105], v[178:181], v[98:101]
	v_mfma_f32_16x16x32_bf16 v[82:85], v[78:81], v[186:189], v[82:85]
	v_mfma_f32_16x16x32_bf16 v[74:77], v[102:105], v[186:189], v[74:77]
	v_mfma_f32_16x16x32_bf16 v[158:161], v[86:89], v[166:169], v[158:161]
	v_mfma_f32_16x16x32_bf16 v[154:157], v[110:113], v[166:169], v[154:157]
	v_mfma_f32_16x16x32_bf16 v[130:133], v[86:89], v[174:177], v[130:133]
	v_mfma_f32_16x16x32_bf16 v[126:129], v[110:113], v[174:177], v[126:129]
	v_mfma_f32_16x16x32_bf16 v[106:109], v[86:89], v[182:185], v[106:109]
	v_mfma_f32_16x16x32_bf16 v[98:101], v[110:113], v[182:185], v[98:101]
	v_mfma_f32_16x16x32_bf16 v[82:85], v[86:89], v[202:205], v[82:85]
	v_mfma_f32_16x16x32_bf16 v[74:77], v[110:113], v[202:205], v[74:77]
	v_mfma_f32_16x16x32_bf16 v[142:145], v[122:125], v[162:165], v[142:145]
	v_mfma_f32_16x16x32_bf16 v[138:141], v[146:149], v[162:165], v[138:141]
	v_mfma_f32_16x16x32_bf16 v[118:121], v[122:125], v[170:173], v[118:121]
	v_mfma_f32_16x16x32_bf16 v[114:117], v[146:149], v[170:173], v[114:117]
	v_mfma_f32_16x16x32_bf16 v[94:97], v[122:125], v[178:181], v[94:97]
	v_mfma_f32_16x16x32_bf16 v[90:93], v[146:149], v[178:181], v[90:93]
	v_mfma_f32_16x16x32_bf16 v[70:73], v[122:125], v[186:189], v[70:73]
	v_mfma_f32_16x16x32_bf16 v[66:69], v[146:149], v[186:189], v[66:69]
	v_mfma_f32_16x16x32_bf16 v[142:145], v[134:137], v[166:169], v[142:145]
	v_mfma_f32_16x16x32_bf16 v[138:141], v[150:153], v[166:169], v[138:141]
	v_mfma_f32_16x16x32_bf16 v[118:121], v[134:137], v[174:177], v[118:121]
	v_mfma_f32_16x16x32_bf16 v[114:117], v[150:153], v[174:177], v[114:117]
	v_mfma_f32_16x16x32_bf16 v[94:97], v[134:137], v[182:185], v[94:97]
	v_mfma_f32_16x16x32_bf16 v[90:93], v[150:153], v[182:185], v[90:93]
	v_mfma_f32_16x16x32_bf16 v[70:73], v[134:137], v[202:205], v[70:73]
	v_mfma_f32_16x16x32_bf16 v[66:69], v[150:153], v[202:205], v[66:69]
	s_barrier
; #define PG8_STAGE(bufoff, gbase, voff) do { _Pragma("unroll") for (int _i = 0; _i < 2; ++_i) \
;         __builtin_amdgcn_global_load_lds((const unsigned*)((const char*)(gbase) + (voff)[_i]), (PG8_LAS unsigned*)(lds + (bufoff) + ldsw + _i * 8192), 16, 0, 0); } while (0)
; #define PG8_LDA(dst, b, h) do { _Pragma("unroll") for (int m = 0; m < 4; ++m) _Pragma("unroll") for (int k = 0; k < 2; ++k) dst[m][k] = *(const PG8_LAS bf16x8*)(lds + PG8_SA(b, h) + aoff + m * 2048 + k * 1024); } while (0)
; #define PG8_LDB(dst, b, h) do { _Pragma("unroll") for (int n = 0; n < 2; ++n) _Pragma("unroll") for (int k = 0; k < 2; ++k) dst[n][k] = *(const PG8_LAS bf16x8*)(lds + PG8_SB(b, h) + boff + n * 2048 + k * 1024); } while (0)
; #define PG8_MMA(ai, bj, At, Bt) do { __builtin_amdgcn_s_setprio(1); _Pragma("unroll") for (int m = 0; m < 4; ++m) _Pragma("unroll") for (int n = 0; n < 2; ++n) _Pragma("unroll") for (int k = 0; k < 2; ++k) \
;         acc[ai][bj][m][n] = __builtin_amdgcn_mfma_f32_16x16x32_bf16(Bt[n][k], At[m][k], acc[ai][bj][m][n], 0, 0, 0); __builtin_amdgcn_s_setprio(0); } while (0)
; #define PG8_WAIT_V(n) asm volatile("s_waitcnt vmcnt(" #n ")" ::: "memory")
; #define PG8_WAIT_L(n) asm volatile("s_waitcnt lgkmcnt(" #n ")" ::: "memory")
; #define PG8_BAR __builtin_amdgcn_s_barrier()
; #define PG8_SCHED __builtin_amdgcn_sched_barrier(0)
; template <class Epi, class Sched, bool ALIGN_EPI = false, bool SP2 = false>
; __device__ __forceinline__ void gemm_phase(PG8_LAS unsigned char* lds, const Gemm g, const Sched& S, const Epi& E, int wave_s) {
;     ...
;             const bool last = (t == nt - 2);
;             const char* a1 = cA + (size_t)(t + 1) * kstep;
;             const char* a2 = last ? nA : cA + (size_t)(t + 2) * kstep; const char* b2 = last ? nB : cB + (size_t)(t + 2) * kstep;
;             const char* a3 = a2 + kstep; const char* b3 = b2 + kstep;
;             if (last && has_next) S.a_ready(nxt);
;             if constexpr (SP2) {
;             PG8_LDB(B0, 0, 0); PG8_LDB(B1, 0, 1); PG8_SCHED; PG8_LDA(At, 0, 0); PG8_STAGE(PG8_SA(1, 1), a1 + hstepA, voffA);
;     ...
;             PG8_LDA(At, 1, 1); PG8_STAGE(PG8_SB(1, 0), b3, voffB); PG8_STAGE(PG8_SB(1, 1), b3 + hstepB, voffB); PG8_STAGE(PG8_SA(1, 0), a3, voffA);
;             PG8_WAIT_V(8); PG8_WAIT_L(0); PG8_BAR; PG8_MMA(1, 0, At, B0); PG8_MMA(1, 1, At, B1); PG8_BAR; PG8_SCHED;
	s_add_i32 s8, s84, s22
	v_lshl_add_u64 v[206:207], v[206:207], 0, s[60:61]
	s_mov_b32 m0, s8
	ds_read_b128 v[162:165], v212 offset:49152
	ds_read_b128 v[166:169], v212 offset:50176
	ds_read_b128 v[170:173], v212 offset:51200
	ds_read_b128 v[174:177], v212 offset:52224
	ds_read_b128 v[178:181], v212 offset:53248
	ds_read_b128 v[182:185], v212 offset:54272
	ds_read_b128 v[186:189], v212 offset:55296
	ds_read_b128 v[202:205], v212 offset:56320
	global_load_lds_dwordx4 v[206:207], off
	s_add_i32 m0, s8, 0x2000
	s_add_u32 s6, s6, 0x160080
	v_lshl_add_u64 v[206:207], v[208:209], 0, s[60:61]
	s_addc_u32 s7, s7, 0
	s_add_i32 s8, s85, s22
	global_load_lds_dwordx4 v[206:207], off
	v_lshl_add_u64 v[206:207], s[6:7], 0, v[194:195]
	s_mov_b32 m0, s8
	s_nop 0
	global_load_lds_dwordx4 v[206:207], off
	v_lshl_add_u64 v[206:207], s[6:7], 0, v[190:191]
	s_add_i32 m0, s8, 0x2000
	s_nop 0
	global_load_lds_dwordx4 v[206:207], off
	v_lshl_add_u64 v[206:207], v[214:215], 0, s[60:61]
	s_mov_b32 m0, s44
	s_nop 0
	global_load_lds_dwordx4 v[206:207], off
	v_lshl_add_u64 v[206:207], v[216:217], 0, s[60:61]
	s_mov_b32 m0, s45
	s_nop 0
	global_load_lds_dwordx4 v[206:207], off
	s_waitcnt vmcnt(8)
	s_waitcnt lgkmcnt(0)
	s_barrier
	s_waitcnt lgkmcnt(0)
	v_mfma_f32_16x16x32_bf16 v[62:65], v[78:81], v[162:165], v[62:65]
	v_mfma_f32_16x16x32_bf16 v[58:61], v[102:105], v[162:165], v[58:61]
	v_mfma_f32_16x16x32_bf16 v[46:49], v[78:81], v[170:173], v[46:49]
	v_mfma_f32_16x16x32_bf16 v[42:45], v[102:105], v[170:173], v[42:45]
	v_mfma_f32_16x16x32_bf16 v[30:33], v[78:81], v[178:181], v[30:33]
	v_mfma_f32_16x16x32_bf16 v[26:29], v[102:105], v[178:181], v[26:29]
	v_mfma_f32_16x16x32_bf16 v[14:17], v[78:81], v[186:189], v[14:17]
	v_mfma_f32_16x16x32_bf16 v[10:13], v[102:105], v[186:189], v[10:13]
	v_mfma_f32_16x16x32_bf16 v[62:65], v[86:89], v[166:169], v[62:65]
	v_mfma_f32_16x16x32_bf16 v[58:61], v[110:113], v[166:169], v[58:61]
	v_mfma_f32_16x16x32_bf16 v[46:49], v[86:89], v[174:177], v[46:49]
	v_mfma_f32_16x16x32_bf16 v[42:45], v[110:113], v[174:177], v[42:45]
	v_mfma_f32_16x16x32_bf16 v[30:33], v[86:89], v[182:185], v[30:33]
	v_mfma_f32_16x16x32_bf16 v[26:29], v[110:113], v[182:185], v[26:29]
	v_mfma_f32_16x16x32_bf16 v[14:17], v[86:89], v[202:205], v[14:17]
	v_mfma_f32_16x16x32_bf16 v[10:13], v[110:113], v[202:205], v[10:13]
	v_mfma_f32_16x16x32_bf16 v[54:57], v[122:125], v[162:165], v[54:57]
	v_mfma_f32_16x16x32_bf16 v[50:53], v[146:149], v[162:165], v[50:53]
	v_mfma_f32_16x16x32_bf16 v[38:41], v[122:125], v[170:173], v[38:41]
	v_mfma_f32_16x16x32_bf16 v[34:37], v[146:149], v[170:173], v[34:37]
	v_mfma_f32_16x16x32_bf16 v[22:25], v[122:125], v[178:181], v[22:25]
	v_mfma_f32_16x16x32_bf16 v[18:21], v[146:149], v[178:181], v[18:21]
	v_mfma_f32_16x16x32_bf16 v[6:9], v[122:125], v[186:189], v[6:9]
	v_mfma_f32_16x16x32_bf16 v[2:5], v[146:149], v[186:189], v[2:5]
	v_mfma_f32_16x16x32_bf16 v[54:57], v[134:137], v[166:169], v[54:57]
	v_mfma_f32_16x16x32_bf16 v[50:53], v[150:153], v[166:169], v[50:53]
	v_mfma_f32_16x16x32_bf16 v[38:41], v[134:137], v[174:177], v[38:41]
	v_mfma_f32_16x16x32_bf16 v[34:37], v[150:153], v[174:177], v[34:37]
	v_mfma_f32_16x16x32_bf16 v[22:25], v[134:137], v[182:185], v[22:25]
	v_mfma_f32_16x16x32_bf16 v[18:21], v[150:153], v[182:185], v[18:21]
	v_mfma_f32_16x16x32_bf16 v[6:9], v[134:137], v[202:205], v[6:9]
	v_mfma_f32_16x16x32_bf16 v[2:5], v[150:153], v[202:205], v[2:5]
	s_barrier
	s_add_i32 s81, s81, 2
	s_add_u32 s2, s2, 0x100
	s_addc_u32 s3, s3, 0
	s_cmpk_gt_u32 s81, 0x55
	s_mov_b64 s[8:9], s[4:5]
.LBB0_786:
	s_add_u32 s4, s8, 0x100
	s_addc_u32 s5, s9, 0
	s_add_i32 s84, 0, 0x10000
	s_cmpk_eq_i32 s81, 0x54
	s_cselect_b32 s31, s95, s5
	s_cselect_b32 s30, s94, s4
	s_cselect_b32 s7, s97, s3
	s_cselect_b32 s6, s96, s2
	s_add_i32 s85, 0, 0x14000
	v_add_u32_e32 v110, s84, v211
	v_add_u32_e32 v150, s85, v211
	ds_read_b128 v[78:81], v110
	ds_read_b128 v[86:89], v110 offset:1024
	ds_read_b128 v[102:105], v110 offset:2048
	ds_read_b128 v[110:113], v110 offset:3072
	ds_read_b128 v[122:125], v150
	ds_read_b128 v[134:137], v150 offset:1024
	ds_read_b128 v[146:149], v150 offset:2048
	ds_read_b128 v[150:153], v150 offset:3072
	v_lshl_add_u64 v[206:207], s[8:9], 0, v[198:199]
	s_add_i32 m0, s35, 0xc000
	ds_read_b128 v[162:165], v212
	ds_read_b128 v[166:169], v212 offset:1024
	ds_read_b128 v[170:173], v212 offset:2048
	ds_read_b128 v[174:177], v212 offset:3072
	ds_read_b128 v[178:181], v212 offset:4096
	ds_read_b128 v[182:185], v212 offset:5120
	ds_read_b128 v[186:189], v212 offset:6144
	ds_read_b128 v[202:205], v212 offset:7168
	global_load_lds_dwordx4 v[206:207], off
	v_lshl_add_u64 v[206:207], s[8:9], 0, v[200:201]
	s_add_i32 m0, s35, 0xe000
	s_nop 0
	global_load_lds_dwordx4 v[206:207], off
	s_waitcnt vmcnt(8)
	s_waitcnt lgkmcnt(0)
	s_barrier
; #define PG8_STAGE(bufoff, gbase, voff) do { _Pragma("unroll") for (int _i = 0; _i < 2; ++_i) \
;         __builtin_amdgcn_global_load_lds((const unsigned*)((const char*)(gbase) + (voff)[_i]), (PG8_LAS unsigned*)(lds + (bufoff) + ldsw + _i * 8192), 16, 0, 0); } while (0)
; #define PG8_LDA(dst, b, h) do { _Pragma("unroll") for (int m = 0; m < 4; ++m) _Pragma("unroll") for (int k = 0; k < 2; ++k) dst[m][k] = *(const PG8_LAS bf16x8*)(lds + PG8_SA(b, h) + aoff + m * 2048 + k * 1024); } while (0)
; #define PG8_MMA(ai, bj, At, Bt) do { __builtin_amdgcn_s_setprio(1); _Pragma("unroll") for (int m = 0; m < 4; ++m) _Pragma("unroll") for (int n = 0; n < 2; ++n) _Pragma("unroll") for (int k = 0; k < 2; ++k) \
;         acc[ai][bj][m][n] = __builtin_amdgcn_mfma_f32_16x16x32_bf16(Bt[n][k], At[m][k], acc[ai][bj][m][n], 0, 0, 0); __builtin_amdgcn_s_setprio(0); } while (0)
; #define PG8_WAIT_V(n) asm volatile("s_waitcnt vmcnt(" #n ")" ::: "memory")
; #define PG8_WAIT_L(n) asm volatile("s_waitcnt lgkmcnt(" #n ")" ::: "memory")
; #define PG8_BAR __builtin_amdgcn_s_barrier()
; #define PG8_SCHED __builtin_amdgcn_sched_barrier(0)
; template <class Epi, class Sched, bool ALIGN_EPI = false, bool SP2 = false>
; __device__ __forceinline__ void gemm_phase(PG8_LAS unsigned char* lds, const Gemm g, const Sched& S, const Epi& E, int wave_s) {
;     ...
;             PG8_WAIT_V(8); PG8_WAIT_L(0); PG8_BAR; PG8_MMA(0, 0, At, B0); PG8_MMA(0, 1, At, B1); PG8_BAR; PG8_SCHED;
;             PG8_LDA(At, 0, 1); PG8_STAGE(PG8_SB(0, 0), b2, voffB); PG8_STAGE(PG8_SB(0, 1), b2 + hstepB, voffB); PG8_STAGE(PG8_SA(0, 0), a2, voffA);
;             PG8_WAIT_V(8); PG8_WAIT_L(0); PG8_BAR; PG8_MMA(1, 0, At, B0); PG8_MMA(1, 1, At, B1); PG8_BAR; PG8_SCHED;
	s_waitcnt lgkmcnt(0)
	v_mfma_f32_16x16x32_bf16 v[158:161], v[78:81], v[162:165], v[158:161]
	v_mfma_f32_16x16x32_bf16 v[154:157], v[102:105], v[162:165], v[154:157]
	v_mfma_f32_16x16x32_bf16 v[130:133], v[78:81], v[170:173], v[130:133]
	v_mfma_f32_16x16x32_bf16 v[126:129], v[102:105], v[170:173], v[126:129]
	v_mfma_f32_16x16x32_bf16 v[106:109], v[78:81], v[178:181], v[106:109]
	v_mfma_f32_16x16x32_bf16 v[98:101], v[102:105], v[178:181], v[98:101]
	v_mfma_f32_16x16x32_bf16 v[82:85], v[78:81], v[186:189], v[82:85]
	v_mfma_f32_16x16x32_bf16 v[74:77], v[102:105], v[186:189], v[74:77]
	v_mfma_f32_16x16x32_bf16 v[158:161], v[86:89], v[166:169], v[158:161]
	v_mfma_f32_16x16x32_bf16 v[154:157], v[110:113], v[166:169], v[154:157]
	v_mfma_f32_16x16x32_bf16 v[130:133], v[86:89], v[174:177], v[130:133]
	v_mfma_f32_16x16x32_bf16 v[126:129], v[110:113], v[174:177], v[126:129]
	v_mfma_f32_16x16x32_bf16 v[106:109], v[86:89], v[182:185], v[106:109]
	v_mfma_f32_16x16x32_bf16 v[98:101], v[110:113], v[182:185], v[98:101]
	v_mfma_f32_16x16x32_bf16 v[82:85], v[86:89], v[202:205], v[82:85]
	v_mfma_f32_16x16x32_bf16 v[74:77], v[110:113], v[202:205], v[74:77]
	v_mfma_f32_16x16x32_bf16 v[142:145], v[122:125], v[162:165], v[142:145]
	v_mfma_f32_16x16x32_bf16 v[138:141], v[146:149], v[162:165], v[138:141]
	v_mfma_f32_16x16x32_bf16 v[118:121], v[122:125], v[170:173], v[118:121]
	v_mfma_f32_16x16x32_bf16 v[114:117], v[146:149], v[170:173], v[114:117]
	v_mfma_f32_16x16x32_bf16 v[94:97], v[122:125], v[178:181], v[94:97]
	v_mfma_f32_16x16x32_bf16 v[90:93], v[146:149], v[178:181], v[90:93]
	v_mfma_f32_16x16x32_bf16 v[70:73], v[122:125], v[186:189], v[70:73]
	v_mfma_f32_16x16x32_bf16 v[66:69], v[146:149], v[186:189], v[66:69]
	v_mfma_f32_16x16x32_bf16 v[142:145], v[134:137], v[166:169], v[142:145]
	v_mfma_f32_16x16x32_bf16 v[138:141], v[150:153], v[166:169], v[138:141]
	v_mfma_f32_16x16x32_bf16 v[118:121], v[134:137], v[174:177], v[118:121]
	v_mfma_f32_16x16x32_bf16 v[114:117], v[150:153], v[174:177], v[114:117]
	v_mfma_f32_16x16x32_bf16 v[94:97], v[134:137], v[182:185], v[94:97]
	v_mfma_f32_16x16x32_bf16 v[90:93], v[150:153], v[182:185], v[90:93]
	v_mfma_f32_16x16x32_bf16 v[70:73], v[134:137], v[202:205], v[70:73]
	v_mfma_f32_16x16x32_bf16 v[66:69], v[150:153], v[202:205], v[66:69]
	s_barrier
	s_add_i32 s8, s84, s22
	v_lshl_add_u64 v[206:207], s[6:7], 0, v[194:195]
	s_mov_b32 m0, s8
	ds_read_b128 v[162:165], v212 offset:16384
	ds_read_b128 v[166:169], v212 offset:17408
	ds_read_b128 v[170:173], v212 offset:18432
	ds_read_b128 v[174:177], v212 offset:19456
	ds_read_b128 v[178:181], v212 offset:20480
	ds_read_b128 v[182:185], v212 offset:21504
	ds_read_b128 v[186:189], v212 offset:22528
	ds_read_b128 v[202:205], v212 offset:23552
	global_load_lds_dwordx4 v[206:207], off
	s_add_i32 m0, s8, 0x2000
	s_add_u32 s8, s6, 0x160000
	v_lshl_add_u64 v[208:209], s[6:7], 0, v[190:191]
	s_addc_u32 s9, s7, 0
	s_add_i32 s84, s85, s22
	global_load_lds_dwordx4 v[208:209], off
	v_lshl_add_u64 v[214:215], s[8:9], 0, v[194:195]
	s_mov_b32 m0, s84
	v_lshl_add_u64 v[216:217], s[30:31], 0, v[192:193]
	global_load_lds_dwordx4 v[214:215], off
	v_lshl_add_u64 v[214:215], s[8:9], 0, v[190:191]
	s_add_i32 m0, s84, 0x2000
	s_nop 0
	global_load_lds_dwordx4 v[214:215], off
	v_lshl_add_u64 v[214:215], s[30:31], 0, v[196:197]
	s_mov_b32 m0, s35
	s_nop 0
	global_load_lds_dwordx4 v[214:215], off
	s_mov_b32 m0, s36
	s_nop 0
	global_load_lds_dwordx4 v[216:217], off
	s_waitcnt vmcnt(8)
	s_waitcnt lgkmcnt(0)
	s_barrier
	s_waitcnt lgkmcnt(0)
	v_mfma_f32_16x16x32_bf16 v[62:65], v[78:81], v[162:165], v[62:65]
	v_mfma_f32_16x16x32_bf16 v[58:61], v[102:105], v[162:165], v[58:61]
	v_mfma_f32_16x16x32_bf16 v[46:49], v[78:81], v[170:173], v[46:49]
	v_mfma_f32_16x16x32_bf16 v[42:45], v[102:105], v[170:173], v[42:45]
	v_mfma_f32_16x16x32_bf16 v[30:33], v[78:81], v[178:181], v[30:33]
	v_mfma_f32_16x16x32_bf16 v[26:29], v[102:105], v[178:181], v[26:29]
	v_mfma_f32_16x16x32_bf16 v[14:17], v[78:81], v[186:189], v[14:17]
	v_mfma_f32_16x16x32_bf16 v[10:13], v[102:105], v[186:189], v[10:13]
	v_mfma_f32_16x16x32_bf16 v[62:65], v[86:89], v[166:169], v[62:65]
	v_mfma_f32_16x16x32_bf16 v[58:61], v[110:113], v[166:169], v[58:61]
	v_mfma_f32_16x16x32_bf16 v[46:49], v[86:89], v[174:177], v[46:49]
	v_mfma_f32_16x16x32_bf16 v[42:45], v[110:113], v[174:177], v[42:45]
	v_mfma_f32_16x16x32_bf16 v[30:33], v[86:89], v[182:185], v[30:33]
	v_mfma_f32_16x16x32_bf16 v[26:29], v[110:113], v[182:185], v[26:29]
	v_mfma_f32_16x16x32_bf16 v[14:17], v[86:89], v[202:205], v[14:17]
	v_mfma_f32_16x16x32_bf16 v[10:13], v[110:113], v[202:205], v[10:13]
	v_mfma_f32_16x16x32_bf16 v[54:57], v[122:125], v[162:165], v[54:57]
	v_mfma_f32_16x16x32_bf16 v[50:53], v[146:149], v[162:165], v[50:53]
	v_mfma_f32_16x16x32_bf16 v[38:41], v[122:125], v[170:173], v[38:41]
	v_mfma_f32_16x16x32_bf16 v[34:37], v[146:149], v[170:173], v[34:37]
	v_mfma_f32_16x16x32_bf16 v[22:25], v[122:125], v[178:181], v[22:25]
	v_mfma_f32_16x16x32_bf16 v[18:21], v[146:149], v[178:181], v[18:21]
	v_mfma_f32_16x16x32_bf16 v[6:9], v[122:125], v[186:189], v[6:9]
	v_mfma_f32_16x16x32_bf16 v[2:5], v[146:149], v[186:189], v[2:5]
	v_mfma_f32_16x16x32_bf16 v[54:57], v[134:137], v[166:169], v[54:57]
	v_mfma_f32_16x16x32_bf16 v[50:53], v[150:153], v[166:169], v[50:53]
	v_mfma_f32_16x16x32_bf16 v[38:41], v[134:137], v[174:177], v[38:41]
	v_mfma_f32_16x16x32_bf16 v[34:37], v[150:153], v[174:177], v[34:37]
	v_mfma_f32_16x16x32_bf16 v[22:25], v[134:137], v[182:185], v[22:25]
	v_mfma_f32_16x16x32_bf16 v[18:21], v[150:153], v[182:185], v[18:21]
	v_mfma_f32_16x16x32_bf16 v[6:9], v[134:137], v[202:205], v[6:9]
	v_mfma_f32_16x16x32_bf16 v[2:5], v[150:153], v[202:205], v[2:5]
	s_barrier
; #define PG8_STAGE(bufoff, gbase, voff) do { _Pragma("unroll") for (int _i = 0; _i < 2; ++_i) \
;         __builtin_amdgcn_global_load_lds((const unsigned*)((const char*)(gbase) + (voff)[_i]), (PG8_LAS unsigned*)(lds + (bufoff) + ldsw + _i * 8192), 16, 0, 0); } while (0)
; #define PG8_LDA(dst, b, h) do { _Pragma("unroll") for (int m = 0; m < 4; ++m) _Pragma("unroll") for (int k = 0; k < 2; ++k) dst[m][k] = *(const PG8_LAS bf16x8*)(lds + PG8_SA(b, h) + aoff + m * 2048 + k * 1024); } while (0)
; #define PG8_LDB(dst, b, h) do { _Pragma("unroll") for (int n = 0; n < 2; ++n) _Pragma("unroll") for (int k = 0; k < 2; ++k) dst[n][k] = *(const PG8_LAS bf16x8*)(lds + PG8_SB(b, h) + boff + n * 2048 + k * 1024); } while (0)
; #define PG8_MMA(ai, bj, At, Bt) do { __builtin_amdgcn_s_setprio(1); _Pragma("unroll") for (int m = 0; m < 4; ++m) _Pragma("unroll") for (int n = 0; n < 2; ++n) _Pragma("unroll") for (int k = 0; k < 2; ++k) \
;         acc[ai][bj][m][n] = __builtin_amdgcn_mfma_f32_16x16x32_bf16(Bt[n][k], At[m][k], acc[ai][bj][m][n], 0, 0, 0); __builtin_amdgcn_s_setprio(0); } while (0)
; #define PG8_WAIT_V(n) asm volatile("s_waitcnt vmcnt(" #n ")" ::: "memory")
; #define PG8_WAIT_L(n) asm volatile("s_waitcnt lgkmcnt(" #n ")" ::: "memory")
; #define PG8_BAR __builtin_amdgcn_s_barrier()
; #define PG8_SCHED __builtin_amdgcn_sched_barrier(0)
; template <class Epi, class Sched, bool ALIGN_EPI = false, bool SP2 = false>
; __device__ __forceinline__ void gemm_phase(PG8_LAS unsigned char* lds, const Gemm g, const Sched& S, const Epi& E, int wave_s) {
;     ...
;             PG8_LDB(B0, 1, 0); PG8_LDB(B1, 1, 1); PG8_SCHED; PG8_LDA(At, 1, 0); PG8_STAGE(PG8_SA(0, 1), a2 + hstepA, voffA);
;             PG8_WAIT_V(8); PG8_WAIT_L(0); PG8_BAR; PG8_MMA(0, 0, At, B0); PG8_MMA(0, 1, At, B1); PG8_BAR; PG8_SCHED;
	s_add_i32 s84, 0, 0x18000
	s_add_i32 s85, 0, 0x1c000
	v_add_u32_e32 v110, s84, v211
	v_add_u32_e32 v150, s85, v211
	ds_read_b128 v[78:81], v110
	ds_read_b128 v[86:89], v110 offset:1024
	ds_read_b128 v[102:105], v110 offset:2048
	ds_read_b128 v[110:113], v110 offset:3072
	ds_read_b128 v[122:125], v150
	ds_read_b128 v[134:137], v150 offset:1024
	ds_read_b128 v[146:149], v150 offset:2048
	ds_read_b128 v[150:153], v150 offset:3072
	s_add_u32 s8, s30, 0x160000
	s_addc_u32 s9, s31, 0
	s_mov_b32 m0, s37
	v_lshl_add_u64 v[218:219], s[8:9], 0, v[196:197]
	ds_read_b128 v[162:165], v212 offset:32768
	ds_read_b128 v[166:169], v212 offset:33792
	ds_read_b128 v[170:173], v212 offset:34816
	ds_read_b128 v[174:177], v212 offset:35840
	ds_read_b128 v[178:181], v212 offset:36864
	ds_read_b128 v[182:185], v212 offset:37888
	ds_read_b128 v[186:189], v212 offset:38912
	ds_read_b128 v[202:205], v212 offset:39936
	global_load_lds_dwordx4 v[218:219], off
	v_lshl_add_u64 v[218:219], s[8:9], 0, v[192:193]
	s_mov_b32 m0, s40
	s_nop 0
	global_load_lds_dwordx4 v[218:219], off
	s_waitcnt vmcnt(8)
	s_waitcnt lgkmcnt(0)
	s_barrier
	s_waitcnt lgkmcnt(0)
	v_mfma_f32_16x16x32_bf16 v[158:161], v[78:81], v[162:165], v[158:161]
	v_mfma_f32_16x16x32_bf16 v[154:157], v[102:105], v[162:165], v[154:157]
	v_mfma_f32_16x16x32_bf16 v[130:133], v[78:81], v[170:173], v[130:133]
	v_mfma_f32_16x16x32_bf16 v[126:129], v[102:105], v[170:173], v[126:129]
	v_mfma_f32_16x16x32_bf16 v[106:109], v[78:81], v[178:181], v[106:109]
	v_mfma_f32_16x16x32_bf16 v[98:101], v[102:105], v[178:181], v[98:101]
	v_mfma_f32_16x16x32_bf16 v[82:85], v[78:81], v[186:189], v[82:85]
	v_mfma_f32_16x16x32_bf16 v[74:77], v[102:105], v[186:189], v[74:77]
	v_mfma_f32_16x16x32_bf16 v[158:161], v[86:89], v[166:169], v[158:161]
	v_mfma_f32_16x16x32_bf16 v[154:157], v[110:113], v[166:169], v[154:157]
	v_mfma_f32_16x16x32_bf16 v[130:133], v[86:89], v[174:177], v[130:133]
	v_mfma_f32_16x16x32_bf16 v[126:129], v[110:113], v[174:177], v[126:129]
	v_mfma_f32_16x16x32_bf16 v[106:109], v[86:89], v[182:185], v[106:109]
	v_mfma_f32_16x16x32_bf16 v[98:101], v[110:113], v[182:185], v[98:101]
	v_mfma_f32_16x16x32_bf16 v[82:85], v[86:89], v[202:205], v[82:85]
	v_mfma_f32_16x16x32_bf16 v[74:77], v[110:113], v[202:205], v[74:77]
	v_mfma_f32_16x16x32_bf16 v[142:145], v[122:125], v[162:165], v[142:145]
	v_mfma_f32_16x16x32_bf16 v[138:141], v[146:149], v[162:165], v[138:141]
	v_mfma_f32_16x16x32_bf16 v[118:121], v[122:125], v[170:173], v[118:121]
	v_mfma_f32_16x16x32_bf16 v[114:117], v[146:149], v[170:173], v[114:117]
	v_mfma_f32_16x16x32_bf16 v[94:97], v[122:125], v[178:181], v[94:97]
	v_mfma_f32_16x16x32_bf16 v[90:93], v[146:149], v[178:181], v[90:93]
	v_mfma_f32_16x16x32_bf16 v[70:73], v[122:125], v[186:189], v[70:73]
	v_mfma_f32_16x16x32_bf16 v[66:69], v[146:149], v[186:189], v[66:69]
	v_mfma_f32_16x16x32_bf16 v[142:145], v[134:137], v[166:169], v[142:145]
	v_mfma_f32_16x16x32_bf16 v[138:141], v[150:153], v[166:169], v[138:141]
	v_mfma_f32_16x16x32_bf16 v[118:121], v[134:137], v[174:177], v[118:121]
	v_mfma_f32_16x16x32_bf16 v[114:117], v[150:153], v[174:177], v[114:117]
	v_mfma_f32_16x16x32_bf16 v[94:97], v[134:137], v[182:185], v[94:97]
	v_mfma_f32_16x16x32_bf16 v[90:93], v[150:153], v[182:185], v[90:93]
	v_mfma_f32_16x16x32_bf16 v[70:73], v[134:137], v[202:205], v[70:73]
	v_mfma_f32_16x16x32_bf16 v[66:69], v[150:153], v[202:205], v[66:69]
	s_barrier
; #define PG8_STAGE(bufoff, gbase, voff) do { _Pragma("unroll") for (int _i = 0; _i < 2; ++_i) \
;         __builtin_amdgcn_global_load_lds((const unsigned*)((const char*)(gbase) + (voff)[_i]), (PG8_LAS unsigned*)(lds + (bufoff) + ldsw + _i * 8192), 16, 0, 0); } while (0)
; #define PG8_LDA(dst, b, h) do { _Pragma("unroll") for (int m = 0; m < 4; ++m) _Pragma("unroll") for (int k = 0; k < 2; ++k) dst[m][k] = *(const PG8_LAS bf16x8*)(lds + PG8_SA(b, h) + aoff + m * 2048 + k * 1024); } while (0)
; #define PG8_MMA(ai, bj, At, Bt) do { __builtin_amdgcn_s_setprio(1); _Pragma("unroll") for (int m = 0; m < 4; ++m) _Pragma("unroll") for (int n = 0; n < 2; ++n) _Pragma("unroll") for (int k = 0; k < 2; ++k) \
;         acc[ai][bj][m][n] = __builtin_amdgcn_mfma_f32_16x16x32_bf16(Bt[n][k], At[m][k], acc[ai][bj][m][n], 0, 0, 0); __builtin_amdgcn_s_setprio(0); } while (0)
; #define PG8_WAIT_V(n) asm volatile("s_waitcnt vmcnt(" #n ")" ::: "memory")
; #define PG8_WAIT_L(n) asm volatile("s_waitcnt lgkmcnt(" #n ")" ::: "memory")
; #define PG8_BAR __builtin_amdgcn_s_barrier()
; #define PG8_SCHED __builtin_amdgcn_sched_barrier(0)
; template <class Epi, class Sched, bool ALIGN_EPI = false, bool SP2 = false>
; __device__ __forceinline__ void gemm_phase(PG8_LAS unsigned char* lds, const Gemm g, const Sched& S, const Epi& E, int wave_s) {
;     ...
;             PG8_LDA(At, 1, 1); PG8_STAGE(PG8_SB(1, 0), b3, voffB); PG8_STAGE(PG8_SB(1, 1), b3 + hstepB, voffB); PG8_STAGE(PG8_SA(1, 0), a3, voffA);
;             PG8_WAIT_V(8); PG8_WAIT_L(0); PG8_BAR; PG8_MMA(1, 0, At, B0); PG8_MMA(1, 1, At, B1); PG8_BAR; PG8_SCHED;
;     ...
;         if constexpr (ALIGN_EPI) { if (wr == 0) PG8_BAR; }
	s_add_i32 s8, s84, s22
	v_lshl_add_u64 v[206:207], v[206:207], 0, s[60:61]
	s_mov_b32 m0, s8
	ds_read_b128 v[162:165], v212 offset:49152
	ds_read_b128 v[166:169], v212 offset:50176
	ds_read_b128 v[170:173], v212 offset:51200
	ds_read_b128 v[174:177], v212 offset:52224
	ds_read_b128 v[178:181], v212 offset:53248
	ds_read_b128 v[182:185], v212 offset:54272
	ds_read_b128 v[186:189], v212 offset:55296
	ds_read_b128 v[202:205], v212 offset:56320
	global_load_lds_dwordx4 v[206:207], off
	s_add_i32 m0, s8, 0x2000
	s_add_u32 s6, s6, 0x160080
	v_lshl_add_u64 v[206:207], v[208:209], 0, s[60:61]
	s_addc_u32 s7, s7, 0
	s_add_i32 s8, s85, s22
	global_load_lds_dwordx4 v[206:207], off
	v_lshl_add_u64 v[206:207], s[6:7], 0, v[194:195]
	s_mov_b32 m0, s8
	s_nop 0
	global_load_lds_dwordx4 v[206:207], off
	v_lshl_add_u64 v[206:207], s[6:7], 0, v[190:191]
	s_add_i32 m0, s8, 0x2000
	s_nop 0
	global_load_lds_dwordx4 v[206:207], off
	v_lshl_add_u64 v[206:207], v[214:215], 0, s[60:61]
	s_mov_b32 m0, s44
	s_nop 0
	global_load_lds_dwordx4 v[206:207], off
	v_lshl_add_u64 v[206:207], v[216:217], 0, s[60:61]
	s_mov_b32 m0, s45
	s_nop 0
	global_load_lds_dwordx4 v[206:207], off
	s_waitcnt vmcnt(8)
	s_waitcnt lgkmcnt(0)
	s_barrier
	s_waitcnt lgkmcnt(0)
	v_mfma_f32_16x16x32_bf16 v[62:65], v[78:81], v[162:165], v[62:65]
	v_mfma_f32_16x16x32_bf16 v[58:61], v[102:105], v[162:165], v[58:61]
	v_mfma_f32_16x16x32_bf16 v[46:49], v[78:81], v[170:173], v[46:49]
	v_mfma_f32_16x16x32_bf16 v[42:45], v[102:105], v[170:173], v[42:45]
	v_mfma_f32_16x16x32_bf16 v[30:33], v[78:81], v[178:181], v[30:33]
	v_mfma_f32_16x16x32_bf16 v[26:29], v[102:105], v[178:181], v[26:29]
	v_mfma_f32_16x16x32_bf16 v[14:17], v[78:81], v[186:189], v[14:17]
	v_mfma_f32_16x16x32_bf16 v[10:13], v[102:105], v[186:189], v[10:13]
	v_mfma_f32_16x16x32_bf16 v[62:65], v[86:89], v[166:169], v[62:65]
	v_mfma_f32_16x16x32_bf16 v[58:61], v[110:113], v[166:169], v[58:61]
	v_mfma_f32_16x16x32_bf16 v[46:49], v[86:89], v[174:177], v[46:49]
	v_mfma_f32_16x16x32_bf16 v[42:45], v[110:113], v[174:177], v[42:45]
	v_mfma_f32_16x16x32_bf16 v[30:33], v[86:89], v[182:185], v[30:33]
	v_mfma_f32_16x16x32_bf16 v[26:29], v[110:113], v[182:185], v[26:29]
	v_mfma_f32_16x16x32_bf16 v[14:17], v[86:89], v[202:205], v[14:17]
	v_mfma_f32_16x16x32_bf16 v[10:13], v[110:113], v[202:205], v[10:13]
	v_mfma_f32_16x16x32_bf16 v[54:57], v[122:125], v[162:165], v[54:57]
	v_mfma_f32_16x16x32_bf16 v[50:53], v[146:149], v[162:165], v[50:53]
	v_mfma_f32_16x16x32_bf16 v[38:41], v[122:125], v[170:173], v[38:41]
	v_mfma_f32_16x16x32_bf16 v[34:37], v[146:149], v[170:173], v[34:37]
	v_mfma_f32_16x16x32_bf16 v[22:25], v[122:125], v[178:181], v[22:25]
	v_mfma_f32_16x16x32_bf16 v[18:21], v[146:149], v[178:181], v[18:21]
	v_mfma_f32_16x16x32_bf16 v[6:9], v[122:125], v[186:189], v[6:9]
	v_mfma_f32_16x16x32_bf16 v[2:5], v[146:149], v[186:189], v[2:5]
	v_mfma_f32_16x16x32_bf16 v[54:57], v[134:137], v[166:169], v[54:57]
	v_mfma_f32_16x16x32_bf16 v[50:53], v[150:153], v[166:169], v[50:53]
	v_mfma_f32_16x16x32_bf16 v[38:41], v[134:137], v[174:177], v[38:41]
	v_mfma_f32_16x16x32_bf16 v[34:37], v[150:153], v[174:177], v[34:37]
	v_mfma_f32_16x16x32_bf16 v[22:25], v[134:137], v[182:185], v[22:25]
	v_mfma_f32_16x16x32_bf16 v[18:21], v[150:153], v[182:185], v[18:21]
	v_mfma_f32_16x16x32_bf16 v[6:9], v[134:137], v[202:205], v[6:9]
	v_mfma_f32_16x16x32_bf16 v[2:5], v[150:153], v[202:205], v[2:5]
	s_barrier
	s_add_i32 s81, s81, 2
	s_add_u32 s2, s2, 0x100
	s_addc_u32 s3, s3, 0
	s_cmpk_gt_u32 s81, 0x55
	s_mov_b64 s[8:9], s[4:5]
	s_cbranch_scc0 .LBB0_786
	s_and_b64 vcc, exec, s[88:89]
	s_cbranch_vccz .LBB0_789
	s_barrier
